# MFMA blocks: one priority raise in front of the opening barrier, closing barrier directly after the last MFMA, priority drop behind it, no flips inside the block
# speedup vs baseline: 1.0013x; 1.0013x over previous
; #define PG8_STAGE(bufoff, gbase, voff) do { _Pragma("unroll") for (int _i = 0; _i < 2; ++_i) \
;         __builtin_amdgcn_global_load_lds((const unsigned*)((const char*)(gbase) + (voff)[_i]), (PG8_LAS unsigned*)(lds + (bufoff) + ldsw + _i * 8192), 16, 0, 0); } while (0)
; #define PG8_LDA(dst, b, h) do { _Pragma("unroll") for (int m = 0; m < 4; ++m) _Pragma("unroll") for (int k = 0; k < 2; ++k) dst[m][k] = *(const PG8_LAS bf16x8*)(lds + PG8_SA(b, h) + aoff + m * 2048 + k * 1024); } while (0)
; #define PG8_LDB(dst, b, h) do { _Pragma("unroll") for (int n = 0; n < 2; ++n) _Pragma("unroll") for (int k = 0; k < 2; ++k) dst[n][k] = *(const PG8_LAS bf16x8*)(lds + PG8_SB(b, h) + boff + n * 2048 + k * 1024); } while (0)
; #define PG8_MMA(ai, bj, At, Bt) do { __builtin_amdgcn_s_setprio(1); _Pragma("unroll") for (int m = 0; m < 4; ++m) _Pragma("unroll") for (int n = 0; n < 2; ++n) _Pragma("unroll") for (int k = 0; k < 2; ++k) \
;         acc[ai][bj][m][n] = __builtin_amdgcn_mfma_f32_16x16x32_bf16(Bt[n][k], At[m][k], acc[ai][bj][m][n], 0, 0, 0); __builtin_amdgcn_s_setprio(0); } while (0)
; #define PG8_WAIT_V(n) asm volatile("s_waitcnt vmcnt(" #n ")" ::: "memory")
; #define PG8_WAIT_VN(n) asm volatile("s_waitcnt vmcnt(%0)" :: "n"(n) : "memory")
; #define PG8_WAIT_L(n) asm volatile("s_waitcnt lgkmcnt(" #n ")" ::: "memory")
; #define PG8_BAR __builtin_amdgcn_s_barrier()
; #define PG8_SCHED __builtin_amdgcn_sched_barrier(0)
; template <class Epi, class Sched, bool ALIGN_EPI = false, bool SP2 = false>
; __device__ __forceinline__ void gemm_phase(PG8_LAS unsigned char* lds, const Gemm g, const Sched& S, const Epi& E, const int wave_id) {
;     ...
;             PG8_WAIT_VN(8 + Epi::NS); if (strict) PG8_WAIT_V(8); PG8_WAIT_L(0); PG8_BAR; PG8_MMA(1, 0, At, B0); PG8_MMA(1, 1, At, B1); PG8_BAR; PG8_SCHED;
;             PG8_LDB(B0, 1, 0); PG8_LDB(B1, 1, 1); PG8_SCHED; PG8_LDA(At, 1, 0); PG8_STAGE(PG8_SA(0, 1), a2 + hstep, voffA);
;             PG8_WAIT_V(8); PG8_WAIT_L(0); PG8_BAR; PG8_MMA(0, 0, At, B0); PG8_MMA(0, 1, At, B1); PG8_BAR; PG8_SCHED;
.LBB0_157:
	s_waitcnt lgkmcnt(0)
	s_setprio 1
	s_barrier
	v_mfma_f32_16x16x32_bf16 v[62:65], v[146:149], v[186:189], v[62:65]
	v_mfma_f32_16x16x32_bf16 v[58:61], v[154:157], v[186:189], v[58:61]
	v_mfma_f32_16x16x32_bf16 v[54:57], v[146:149], v[178:181], v[54:57]
	v_mfma_f32_16x16x32_bf16 v[50:53], v[154:157], v[178:181], v[50:53]
	v_mfma_f32_16x16x32_bf16 v[30:33], v[146:149], v[170:173], v[30:33]
	v_mfma_f32_16x16x32_bf16 v[26:29], v[154:157], v[170:173], v[26:29]
	v_mfma_f32_16x16x32_bf16 v[22:25], v[146:149], v[162:165], v[22:25]
	v_mfma_f32_16x16x32_bf16 v[18:21], v[154:157], v[162:165], v[18:21]
	v_mfma_f32_16x16x32_bf16 v[62:65], v[150:153], v[190:193], v[62:65]
	v_mfma_f32_16x16x32_bf16 v[58:61], v[158:161], v[190:193], v[58:61]
	v_mfma_f32_16x16x32_bf16 v[54:57], v[150:153], v[182:185], v[54:57]
	v_mfma_f32_16x16x32_bf16 v[50:53], v[158:161], v[182:185], v[50:53]
	v_mfma_f32_16x16x32_bf16 v[30:33], v[150:153], v[174:177], v[30:33]
	v_mfma_f32_16x16x32_bf16 v[26:29], v[158:161], v[174:177], v[26:29]
	v_mfma_f32_16x16x32_bf16 v[22:25], v[150:153], v[166:169], v[22:25]
	v_mfma_f32_16x16x32_bf16 v[18:21], v[158:161], v[166:169], v[18:21]
	v_mfma_f32_16x16x32_bf16 v[46:49], v[130:133], v[186:189], v[46:49]
	v_mfma_f32_16x16x32_bf16 v[42:45], v[138:141], v[186:189], v[42:45]
	v_mfma_f32_16x16x32_bf16 v[38:41], v[130:133], v[178:181], v[38:41]
	v_mfma_f32_16x16x32_bf16 v[34:37], v[138:141], v[178:181], v[34:37]
	v_mfma_f32_16x16x32_bf16 v[14:17], v[130:133], v[170:173], v[14:17]
	v_mfma_f32_16x16x32_bf16 v[10:13], v[138:141], v[170:173], v[10:13]
	v_mfma_f32_16x16x32_bf16 v[6:9], v[130:133], v[162:165], v[6:9]
	v_mfma_f32_16x16x32_bf16 v[2:5], v[138:141], v[162:165], v[2:5]
	v_mfma_f32_16x16x32_bf16 v[46:49], v[134:137], v[190:193], v[46:49]
	v_mfma_f32_16x16x32_bf16 v[42:45], v[142:145], v[190:193], v[42:45]
	v_mfma_f32_16x16x32_bf16 v[38:41], v[134:137], v[182:185], v[38:41]
	v_mfma_f32_16x16x32_bf16 v[34:37], v[142:145], v[182:185], v[34:37]
	v_mfma_f32_16x16x32_bf16 v[14:17], v[134:137], v[174:177], v[14:17]
	v_mfma_f32_16x16x32_bf16 v[10:13], v[142:145], v[174:177], v[10:13]
	v_mfma_f32_16x16x32_bf16 v[6:9], v[134:137], v[166:169], v[6:9]
	v_mfma_f32_16x16x32_bf16 v[2:5], v[142:145], v[166:169], v[2:5]
	s_barrier
	s_setprio 0
	s_add_i32 s28, 0, 0x18000
	s_add_i32 s29, 0, 0x1c000
	v_add_u32_e32 v142, s28, v246
	v_add_u32_e32 v158, s29, v246
	ds_read_b128 v[130:133], v142
	ds_read_b128 v[134:137], v142 offset:1024
	ds_read_b128 v[138:141], v142 offset:2048
	ds_read_b128 v[142:145], v142 offset:3072
	ds_read_b128 v[146:149], v158
	ds_read_b128 v[150:153], v158 offset:1024
	ds_read_b128 v[154:157], v158 offset:2048
	ds_read_b128 v[158:161], v158 offset:3072
	s_add_u32 s26, s26, 0x40000
	s_addc_u32 s27, s27, 0
	s_mov_b32 m0, s52
	v_lshl_add_u64 v[194:195], s[26:27], 0, v[210:211]
	ds_read_b128 v[162:165], v249 offset:32768
	ds_read_b128 v[166:169], v249 offset:33792
	ds_read_b128 v[170:173], v249 offset:34816
	ds_read_b128 v[174:177], v249 offset:35840
	ds_read_b128 v[178:181], v249 offset:36864
	ds_read_b128 v[182:185], v249 offset:37888
	ds_read_b128 v[186:189], v249 offset:38912
	ds_read_b128 v[190:193], v249 offset:39936
	global_load_lds_dwordx4 v[194:195], off
	v_lshl_add_u64 v[194:195], s[26:27], 0, v[214:215]
	s_mov_b32 m0, s54
	s_nop 0
	global_load_lds_dwordx4 v[194:195], off
	s_waitcnt vmcnt(18)
	s_cmp_eq_u32 s100, 0
	s_cbranch_scc1 .Lthird_wait_relaxed_6
	s_waitcnt vmcnt(8)
; #define PG8_STAGE(bufoff, gbase, voff) do { _Pragma("unroll") for (int _i = 0; _i < 2; ++_i) \
;         __builtin_amdgcn_global_load_lds((const unsigned*)((const char*)(gbase) + (voff)[_i]), (PG8_LAS unsigned*)(lds + (bufoff) + ldsw + _i * 8192), 16, 0, 0); } while (0)
; #define PG8_LDA(dst, b, h) do { _Pragma("unroll") for (int m = 0; m < 4; ++m) _Pragma("unroll") for (int k = 0; k < 2; ++k) dst[m][k] = *(const PG8_LAS bf16x8*)(lds + PG8_SA(b, h) + aoff + m * 2048 + k * 1024); } while (0)
; #define PG8_LDB(dst, b, h) do { _Pragma("unroll") for (int n = 0; n < 2; ++n) _Pragma("unroll") for (int k = 0; k < 2; ++k) dst[n][k] = *(const PG8_LAS bf16x8*)(lds + PG8_SB(b, h) + boff + n * 2048 + k * 1024); } while (0)
; #define PG8_MMA(ai, bj, At, Bt) do { __builtin_amdgcn_s_setprio(1); _Pragma("unroll") for (int m = 0; m < 4; ++m) _Pragma("unroll") for (int n = 0; n < 2; ++n) _Pragma("unroll") for (int k = 0; k < 2; ++k) \
;         acc[ai][bj][m][n] = __builtin_amdgcn_mfma_f32_16x16x32_bf16(Bt[n][k], At[m][k], acc[ai][bj][m][n], 0, 0, 0); __builtin_amdgcn_s_setprio(0); } while (0)
; #define PG8_WAIT_V(n) asm volatile("s_waitcnt vmcnt(" #n ")" ::: "memory")
; #define PG8_WAIT_L(n) asm volatile("s_waitcnt lgkmcnt(" #n ")" ::: "memory")
; #define PG8_BAR __builtin_amdgcn_s_barrier()
; #define PG8_SCHED __builtin_amdgcn_sched_barrier(0)
; template <class Epi, class Sched, bool ALIGN_EPI = false, bool SP2 = false>
; __device__ __forceinline__ void gemm_phase(PG8_LAS unsigned char* lds, const Gemm g, const Sched& S, const Epi& E, const int wave_id) {
;     ...
;             PG8_LDB(B0, 1, 0); PG8_LDB(B1, 1, 1); PG8_SCHED; PG8_LDA(At, 1, 0); PG8_STAGE(PG8_SA(0, 1), a2 + hstep, voffA);
;             PG8_WAIT_V(8); PG8_WAIT_L(0); PG8_BAR; PG8_MMA(0, 0, At, B0); PG8_MMA(0, 1, At, B1); PG8_BAR; PG8_SCHED;
;             PG8_LDA(At, 1, 1); PG8_STAGE(PG8_SB(1, 0), b3, voffB); PG8_STAGE(PG8_SB(1, 1), b3 + hstep, voffB); PG8_STAGE(PG8_SA(1, 0), a3, voffA);
;             PG8_WAIT_V(8); PG8_WAIT_L(0); PG8_BAR; PG8_MMA(1, 0, At, B0); PG8_MMA(1, 1, At, B1); PG8_BAR; PG8_SCHED;
.Lthird_wait_relaxed_6:
	s_waitcnt lgkmcnt(0)
	s_setprio 1
	s_barrier
	v_mfma_f32_16x16x32_bf16 v[126:129], v[130:133], v[162:165], v[126:129]
	v_mfma_f32_16x16x32_bf16 v[122:125], v[138:141], v[162:165], v[122:125]
	v_mfma_f32_16x16x32_bf16 v[118:121], v[130:133], v[170:173], v[118:121]
	v_mfma_f32_16x16x32_bf16 v[114:117], v[138:141], v[170:173], v[114:117]
	v_mfma_f32_16x16x32_bf16 v[94:97], v[130:133], v[178:181], v[94:97]
	v_mfma_f32_16x16x32_bf16 v[90:93], v[138:141], v[178:181], v[90:93]
	v_mfma_f32_16x16x32_bf16 v[86:89], v[130:133], v[186:189], v[86:89]
	v_mfma_f32_16x16x32_bf16 v[82:85], v[138:141], v[186:189], v[82:85]
	v_mfma_f32_16x16x32_bf16 v[126:129], v[134:137], v[166:169], v[126:129]
	v_mfma_f32_16x16x32_bf16 v[122:125], v[142:145], v[166:169], v[122:125]
	v_mfma_f32_16x16x32_bf16 v[118:121], v[134:137], v[174:177], v[118:121]
	v_mfma_f32_16x16x32_bf16 v[114:117], v[142:145], v[174:177], v[114:117]
	v_mfma_f32_16x16x32_bf16 v[94:97], v[134:137], v[182:185], v[94:97]
	v_mfma_f32_16x16x32_bf16 v[90:93], v[142:145], v[182:185], v[90:93]
	v_mfma_f32_16x16x32_bf16 v[86:89], v[134:137], v[190:193], v[86:89]
	v_mfma_f32_16x16x32_bf16 v[82:85], v[142:145], v[190:193], v[82:85]
	v_mfma_f32_16x16x32_bf16 v[110:113], v[146:149], v[162:165], v[110:113]
	v_mfma_f32_16x16x32_bf16 v[106:109], v[154:157], v[162:165], v[106:109]
	v_mfma_f32_16x16x32_bf16 v[102:105], v[146:149], v[170:173], v[102:105]
	v_mfma_f32_16x16x32_bf16 v[98:101], v[154:157], v[170:173], v[98:101]
	v_mfma_f32_16x16x32_bf16 v[78:81], v[146:149], v[178:181], v[78:81]
	v_mfma_f32_16x16x32_bf16 v[74:77], v[154:157], v[178:181], v[74:77]
	v_mfma_f32_16x16x32_bf16 v[70:73], v[146:149], v[186:189], v[70:73]
	v_mfma_f32_16x16x32_bf16 v[66:69], v[154:157], v[186:189], v[66:69]
	v_mfma_f32_16x16x32_bf16 v[110:113], v[150:153], v[166:169], v[110:113]
	v_mfma_f32_16x16x32_bf16 v[106:109], v[158:161], v[166:169], v[106:109]
	v_mfma_f32_16x16x32_bf16 v[102:105], v[150:153], v[174:177], v[102:105]
	v_mfma_f32_16x16x32_bf16 v[98:101], v[158:161], v[174:177], v[98:101]
	v_mfma_f32_16x16x32_bf16 v[78:81], v[150:153], v[182:185], v[78:81]
	v_mfma_f32_16x16x32_bf16 v[74:77], v[158:161], v[182:185], v[74:77]
	v_mfma_f32_16x16x32_bf16 v[70:73], v[150:153], v[190:193], v[70:73]
	v_mfma_f32_16x16x32_bf16 v[66:69], v[158:161], v[190:193], v[66:69]
	s_barrier
	s_setprio 0
	s_add_i32 s26, s28, s40
	v_lshl_add_u64 v[194:195], v[232:233], 0, s[64:65]
	s_mov_b32 m0, s26
	ds_read_b128 v[162:165], v249 offset:49152
	ds_read_b128 v[166:169], v249 offset:50176
	ds_read_b128 v[170:173], v249 offset:51200
	ds_read_b128 v[174:177], v249 offset:52224
	ds_read_b128 v[178:181], v249 offset:53248
	ds_read_b128 v[182:185], v249 offset:54272
	ds_read_b128 v[186:189], v249 offset:55296
	ds_read_b128 v[190:193], v249 offset:56320
	global_load_lds_dwordx4 v[194:195], off
	s_add_i32 m0, s26, 0x2000
	s_add_u32 s24, s24, 0x40080
	v_lshl_add_u64 v[194:195], v[230:231], 0, s[64:65]
	s_addc_u32 s25, s25, 0
	s_add_i32 s26, s29, s40
	global_load_lds_dwordx4 v[194:195], off
	v_lshl_add_u64 v[194:195], s[24:25], 0, v[212:213]
	s_mov_b32 m0, s26
	s_nop 0
	global_load_lds_dwordx4 v[194:195], off
	v_lshl_add_u64 v[194:195], s[24:25], 0, v[216:217]
	s_add_i32 m0, s26, 0x2000
	s_nop 0
	global_load_lds_dwordx4 v[194:195], off
	v_lshl_add_u64 v[194:195], v[226:227], 0, s[64:65]
	s_mov_b32 m0, s57
	s_nop 0
	global_load_lds_dwordx4 v[194:195], off
	v_lshl_add_u64 v[194:195], v[228:229], 0, s[64:65]
	s_mov_b32 m0, s62
	s_nop 0
	global_load_lds_dwordx4 v[194:195], off
	s_waitcnt vmcnt(8)
	s_waitcnt lgkmcnt(0)
	s_setprio 1
	s_barrier
	v_mfma_f32_16x16x32_bf16 v[62:65], v[130:133], v[162:165], v[62:65]
	v_mfma_f32_16x16x32_bf16 v[58:61], v[138:141], v[162:165], v[58:61]
	v_mfma_f32_16x16x32_bf16 v[54:57], v[130:133], v[170:173], v[54:57]
	v_mfma_f32_16x16x32_bf16 v[50:53], v[138:141], v[170:173], v[50:53]
	v_mfma_f32_16x16x32_bf16 v[30:33], v[130:133], v[178:181], v[30:33]
	v_mfma_f32_16x16x32_bf16 v[26:29], v[138:141], v[178:181], v[26:29]
	v_mfma_f32_16x16x32_bf16 v[22:25], v[130:133], v[186:189], v[22:25]
	v_mfma_f32_16x16x32_bf16 v[18:21], v[138:141], v[186:189], v[18:21]
	v_mfma_f32_16x16x32_bf16 v[62:65], v[134:137], v[166:169], v[62:65]
	v_mfma_f32_16x16x32_bf16 v[58:61], v[142:145], v[166:169], v[58:61]
	v_mfma_f32_16x16x32_bf16 v[54:57], v[134:137], v[174:177], v[54:57]
	v_mfma_f32_16x16x32_bf16 v[50:53], v[142:145], v[174:177], v[50:53]
	v_mfma_f32_16x16x32_bf16 v[30:33], v[134:137], v[182:185], v[30:33]
	v_mfma_f32_16x16x32_bf16 v[26:29], v[142:145], v[182:185], v[26:29]
	v_mfma_f32_16x16x32_bf16 v[22:25], v[134:137], v[190:193], v[22:25]
	v_mfma_f32_16x16x32_bf16 v[18:21], v[142:145], v[190:193], v[18:21]
	v_mfma_f32_16x16x32_bf16 v[46:49], v[146:149], v[162:165], v[46:49]
	v_mfma_f32_16x16x32_bf16 v[42:45], v[154:157], v[162:165], v[42:45]
	v_mfma_f32_16x16x32_bf16 v[38:41], v[146:149], v[170:173], v[38:41]
	v_mfma_f32_16x16x32_bf16 v[34:37], v[154:157], v[170:173], v[34:37]
	v_mfma_f32_16x16x32_bf16 v[14:17], v[146:149], v[178:181], v[14:17]
	v_mfma_f32_16x16x32_bf16 v[10:13], v[154:157], v[178:181], v[10:13]
	v_mfma_f32_16x16x32_bf16 v[6:9], v[146:149], v[186:189], v[6:9]
	v_mfma_f32_16x16x32_bf16 v[2:5], v[154:157], v[186:189], v[2:5]
	v_mfma_f32_16x16x32_bf16 v[46:49], v[150:153], v[166:169], v[46:49]
	v_mfma_f32_16x16x32_bf16 v[42:45], v[158:161], v[166:169], v[42:45]
	v_mfma_f32_16x16x32_bf16 v[38:41], v[150:153], v[174:177], v[38:41]
	v_mfma_f32_16x16x32_bf16 v[34:37], v[158:161], v[174:177], v[34:37]
	v_mfma_f32_16x16x32_bf16 v[14:17], v[150:153], v[182:185], v[14:17]
	v_mfma_f32_16x16x32_bf16 v[10:13], v[158:161], v[182:185], v[10:13]
	v_mfma_f32_16x16x32_bf16 v[6:9], v[150:153], v[190:193], v[6:9]
	v_mfma_f32_16x16x32_bf16 v[2:5], v[158:161], v[190:193], v[2:5]
	s_barrier
	s_setprio 0
	s_add_i32 s76, s76, 2
	s_add_u32 s22, s22, 0x100
	s_addc_u32 s23, s23, 0
	s_cmp_gt_u32 s76, 13
	s_cbranch_scc1 .LBB0_162

; #define PG8_STAGE(bufoff, gbase, voff) do { _Pragma("unroll") for (int _i = 0; _i < 2; ++_i) \
;         __builtin_amdgcn_global_load_lds((const unsigned*)((const char*)(gbase) + (voff)[_i]), (PG8_LAS unsigned*)(lds + (bufoff) + ldsw + _i * 8192), 16, 0, 0); } while (0)
; #define PG8_LDA(dst, b, h) do { _Pragma("unroll") for (int m = 0; m < 4; ++m) _Pragma("unroll") for (int k = 0; k < 2; ++k) dst[m][k] = *(const PG8_LAS bf16x8*)(lds + PG8_SA(b, h) + aoff + m * 2048 + k * 1024); } while (0)
; #define PG8_LDB(dst, b, h) do { _Pragma("unroll") for (int n = 0; n < 2; ++n) _Pragma("unroll") for (int k = 0; k < 2; ++k) dst[n][k] = *(const PG8_LAS bf16x8*)(lds + PG8_SB(b, h) + boff + n * 2048 + k * 1024); } while (0)
; #define PG8_WAIT_V(n) asm volatile("s_waitcnt vmcnt(" #n ")" ::: "memory")
; #define PG8_WAIT_VN(n) asm volatile("s_waitcnt vmcnt(%0)" :: "n"(n) : "memory")
; #define PG8_WAIT_L(n) asm volatile("s_waitcnt lgkmcnt(" #n ")" ::: "memory")
; template <class Epi, class Sched, bool ALIGN_EPI = false, bool SP2 = false>
; __device__ __forceinline__ void gemm_phase(PG8_LAS unsigned char* lds, const Gemm g, const Sched& S, const Epi& E, const int wave_id) {
;     ...
;         for (int t = 0; t < nt; t += 2) {
;             const bool last = (t == nt - 2);
;             const char* a1 = cA + (size_t)(t + 1) * kstep;
;             const char* a2 = last ? nA : cA + (size_t)(t + 2) * kstep; const char* b2 = last ? nB : cB + (size_t)(t + 2) * kstep;
;             const char* a3 = a2 + kstep; const char* b3 = b2 + kstep;
;             if (last && has_next) S.a_ready(nxt);
;             if constexpr (SP2) {
;             int tz_ = __builtin_amdgcn_readfirstlane(t | (ui > 0 ? 0 : 1)); asm volatile("" : "+s"(tz_));
;             const bool strict = !(Epi::NS > 0 && tz_ == 0);
;             PG8_LDB(B0, 0, 0); PG8_LDB(B1, 0, 1); PG8_SCHED; PG8_LDA(At, 0, 0); PG8_STAGE(PG8_SA(1, 1), a1 + hstep, voffA);
;             PG8_WAIT_VN(8 + Epi::NS); if (strict) PG8_WAIT_V(8); PG8_WAIT_L(0); PG8_BAR; PG8_MMA(0, 0, At, B0); PG8_MMA(0, 1, At, B1); PG8_BAR; PG8_SCHED;
;             PG8_LDA(At, 0, 1); PG8_STAGE(PG8_SB(0, 0), b2, voffB); PG8_STAGE(PG8_SB(0, 1), b2 + hstep, voffB); PG8_STAGE(PG8_SA(0, 0), a2, voffA);
;             PG8_WAIT_VN(8 + Epi::NS); if (strict) PG8_WAIT_V(8); PG8_WAIT_L(0); PG8_BAR; PG8_MMA(1, 0, At, B0); PG8_MMA(1, 1, At, B1); PG8_BAR; PG8_SCHED;
.LBB0_160:
	s_add_u32 s24, s20, s22
	s_addc_u32 s25, s21, s23
	s_add_u32 s24, s24, 0x100
	s_addc_u32 s25, s25, 0
	s_add_u32 s53, s74, s22
	s_addc_u32 s78, s75, s23
	s_cmpk_eq_i32 s22, 0x700
	s_cselect_b32 s27, s13, s25
	s_cselect_b32 s26, s68, s24
	s_cselect_b32 s25, s11, s78
	s_cselect_b32 s24, s69, s53
	s_waitcnt lgkmcnt(0)
	s_setprio 1
	s_barrier
	v_mfma_f32_16x16x32_bf16 v[126:129], v[146:149], v[186:189], v[126:129]
	v_mfma_f32_16x16x32_bf16 v[122:125], v[154:157], v[186:189], v[122:125]
	v_mfma_f32_16x16x32_bf16 v[118:121], v[146:149], v[178:181], v[118:121]
	v_mfma_f32_16x16x32_bf16 v[114:117], v[154:157], v[178:181], v[114:117]
	v_mfma_f32_16x16x32_bf16 v[94:97], v[146:149], v[170:173], v[94:97]
	v_mfma_f32_16x16x32_bf16 v[90:93], v[154:157], v[170:173], v[90:93]
	v_mfma_f32_16x16x32_bf16 v[86:89], v[146:149], v[162:165], v[86:89]
	v_mfma_f32_16x16x32_bf16 v[82:85], v[154:157], v[162:165], v[82:85]
	v_mfma_f32_16x16x32_bf16 v[126:129], v[150:153], v[190:193], v[126:129]
	v_mfma_f32_16x16x32_bf16 v[122:125], v[158:161], v[190:193], v[122:125]
	v_mfma_f32_16x16x32_bf16 v[118:121], v[150:153], v[182:185], v[118:121]
	v_mfma_f32_16x16x32_bf16 v[114:117], v[158:161], v[182:185], v[114:117]
	v_mfma_f32_16x16x32_bf16 v[94:97], v[150:153], v[174:177], v[94:97]
	v_mfma_f32_16x16x32_bf16 v[90:93], v[158:161], v[174:177], v[90:93]
	v_mfma_f32_16x16x32_bf16 v[86:89], v[150:153], v[166:169], v[86:89]
	v_mfma_f32_16x16x32_bf16 v[82:85], v[158:161], v[166:169], v[82:85]
	v_mfma_f32_16x16x32_bf16 v[110:113], v[130:133], v[186:189], v[110:113]
	v_mfma_f32_16x16x32_bf16 v[106:109], v[138:141], v[186:189], v[106:109]
	v_mfma_f32_16x16x32_bf16 v[102:105], v[130:133], v[178:181], v[102:105]
	v_mfma_f32_16x16x32_bf16 v[98:101], v[138:141], v[178:181], v[98:101]
	v_mfma_f32_16x16x32_bf16 v[78:81], v[130:133], v[170:173], v[78:81]
	v_mfma_f32_16x16x32_bf16 v[74:77], v[138:141], v[170:173], v[74:77]
	v_mfma_f32_16x16x32_bf16 v[70:73], v[130:133], v[162:165], v[70:73]
	v_mfma_f32_16x16x32_bf16 v[66:69], v[138:141], v[162:165], v[66:69]
	v_mfma_f32_16x16x32_bf16 v[110:113], v[134:137], v[190:193], v[110:113]
	v_mfma_f32_16x16x32_bf16 v[106:109], v[142:145], v[190:193], v[106:109]
	v_mfma_f32_16x16x32_bf16 v[102:105], v[134:137], v[182:185], v[102:105]
	v_mfma_f32_16x16x32_bf16 v[98:101], v[142:145], v[182:185], v[98:101]
	v_mfma_f32_16x16x32_bf16 v[78:81], v[134:137], v[174:177], v[78:81]
	v_mfma_f32_16x16x32_bf16 v[74:77], v[142:145], v[174:177], v[74:77]
	v_mfma_f32_16x16x32_bf16 v[70:73], v[134:137], v[166:169], v[70:73]
	v_mfma_f32_16x16x32_bf16 v[66:69], v[142:145], v[166:169], v[66:69]
	s_barrier
	s_setprio 0
	s_mov_b32 m0, s42
	v_lshl_add_u64 v[232:233], s[24:25], 0, v[212:213]
	s_add_u32 s90, s24, 0x40000
	ds_read_b128 v[186:189], v249 offset:16384
	ds_read_b128 v[190:193], v249 offset:17408
	ds_read_b128 v[178:181], v249 offset:18432
	ds_read_b128 v[182:185], v249 offset:19456
	ds_read_b128 v[170:173], v249 offset:20480
	ds_read_b128 v[174:177], v249 offset:21504
	ds_read_b128 v[162:165], v249 offset:22528
	ds_read_b128 v[166:169], v249 offset:23552
	global_load_lds_dwordx4 v[232:233], off
	v_lshl_add_u64 v[230:231], s[24:25], 0, v[216:217]
	s_mov_b32 m0, s43
	s_addc_u32 s91, s25, 0
	global_load_lds_dwordx4 v[230:231], off
	v_lshl_add_u64 v[194:195], s[90:91], 0, v[212:213]
	s_mov_b32 m0, s49
	v_lshl_add_u64 v[226:227], s[26:27], 0, v[210:211]
	global_load_lds_dwordx4 v[194:195], off
	v_lshl_add_u64 v[194:195], s[90:91], 0, v[216:217]
	s_mov_b32 m0, s50
	v_lshl_add_u64 v[228:229], s[26:27], 0, v[214:215]
	global_load_lds_dwordx4 v[194:195], off
	s_mov_b32 m0, s41
	s_andn2_b64 vcc, exec, s[28:29]
	global_load_lds_dwordx4 v[226:227], off
	s_mov_b32 m0, s51
	s_nop 0
	global_load_lds_dwordx4 v[228:229], off
	s_waitcnt vmcnt(16)
	s_cbranch_vccnz .LBB0_157
	s_waitcnt vmcnt(8)
	s_branch .LBB0_157

; #define PG8_STAGE(bufoff, gbase, voff) do { _Pragma("unroll") for (int _i = 0; _i < 2; ++_i) \
;         __builtin_amdgcn_global_load_lds((const unsigned*)((const char*)(gbase) + (voff)[_i]), (PG8_LAS unsigned*)(lds + (bufoff) + ldsw + _i * 8192), 16, 0, 0); } while (0)
; #define PG8_LDA(dst, b, h) do { _Pragma("unroll") for (int m = 0; m < 4; ++m) _Pragma("unroll") for (int k = 0; k < 2; ++k) dst[m][k] = *(const PG8_LAS bf16x8*)(lds + PG8_SA(b, h) + aoff + m * 2048 + k * 1024); } while (0)
; #define PG8_LDB(dst, b, h) do { _Pragma("unroll") for (int n = 0; n < 2; ++n) _Pragma("unroll") for (int k = 0; k < 2; ++k) dst[n][k] = *(const PG8_LAS bf16x8*)(lds + PG8_SB(b, h) + boff + n * 2048 + k * 1024); } while (0)
; #define PG8_MMA(ai, bj, At, Bt) do { __builtin_amdgcn_s_setprio(1); _Pragma("unroll") for (int m = 0; m < 4; ++m) _Pragma("unroll") for (int n = 0; n < 2; ++n) _Pragma("unroll") for (int k = 0; k < 2; ++k) \
;         acc[ai][bj][m][n] = __builtin_amdgcn_mfma_f32_16x16x32_bf16(Bt[n][k], At[m][k], acc[ai][bj][m][n], 0, 0, 0); __builtin_amdgcn_s_setprio(0); } while (0)
; #define PG8_WAIT_V(n) asm volatile("s_waitcnt vmcnt(" #n ")" ::: "memory")
; #define PG8_WAIT_VN(n) asm volatile("s_waitcnt vmcnt(%0)" :: "n"(n) : "memory")
; #define PG8_WAIT_L(n) asm volatile("s_waitcnt lgkmcnt(" #n ")" ::: "memory")
; #define PG8_BAR __builtin_amdgcn_s_barrier()
; #define PG8_SCHED __builtin_amdgcn_sched_barrier(0)
; template <class Epi, class Sched, bool ALIGN_EPI = false, bool SP2 = false>
; __device__ __forceinline__ void gemm_phase(PG8_LAS unsigned char* lds, const Gemm g, const Sched& S, const Epi& E, const int wave_id) {
;     ...
;             PG8_WAIT_VN(8 + Epi::NS); if (strict) PG8_WAIT_V(8); PG8_WAIT_L(0); PG8_BAR; PG8_MMA(1, 0, At, B0); PG8_MMA(1, 1, At, B1); PG8_BAR; PG8_SCHED;
;             PG8_LDB(B0, 1, 0); PG8_LDB(B1, 1, 1); PG8_SCHED; PG8_LDA(At, 1, 0); PG8_STAGE(PG8_SA(0, 1), a2 + hstep, voffA);
;             PG8_WAIT_V(8); PG8_WAIT_L(0); PG8_BAR; PG8_MMA(0, 0, At, B0); PG8_MMA(0, 1, At, B1); PG8_BAR; PG8_SCHED;
.LBB0_235:
	s_waitcnt lgkmcnt(0)
	s_setprio 1
	s_barrier
	v_mfma_f32_16x16x32_bf16 v[62:65], v[146:149], v[186:189], v[62:65]
	v_mfma_f32_16x16x32_bf16 v[58:61], v[154:157], v[186:189], v[58:61]
	v_mfma_f32_16x16x32_bf16 v[46:49], v[146:149], v[178:181], v[46:49]
	v_mfma_f32_16x16x32_bf16 v[42:45], v[154:157], v[178:181], v[42:45]
	v_mfma_f32_16x16x32_bf16 v[30:33], v[146:149], v[170:173], v[30:33]
	v_mfma_f32_16x16x32_bf16 v[26:29], v[154:157], v[170:173], v[26:29]
	v_mfma_f32_16x16x32_bf16 v[14:17], v[146:149], v[162:165], v[14:17]
	v_mfma_f32_16x16x32_bf16 v[10:13], v[154:157], v[162:165], v[10:13]
	v_mfma_f32_16x16x32_bf16 v[62:65], v[150:153], v[190:193], v[62:65]
	v_mfma_f32_16x16x32_bf16 v[58:61], v[158:161], v[190:193], v[58:61]
	v_mfma_f32_16x16x32_bf16 v[46:49], v[150:153], v[182:185], v[46:49]
	v_mfma_f32_16x16x32_bf16 v[42:45], v[158:161], v[182:185], v[42:45]
	v_mfma_f32_16x16x32_bf16 v[30:33], v[150:153], v[174:177], v[30:33]
	v_mfma_f32_16x16x32_bf16 v[26:29], v[158:161], v[174:177], v[26:29]
	v_mfma_f32_16x16x32_bf16 v[14:17], v[150:153], v[166:169], v[14:17]
	v_mfma_f32_16x16x32_bf16 v[10:13], v[158:161], v[166:169], v[10:13]
	v_mfma_f32_16x16x32_bf16 v[54:57], v[130:133], v[186:189], v[54:57]
	v_mfma_f32_16x16x32_bf16 v[50:53], v[138:141], v[186:189], v[50:53]
	v_mfma_f32_16x16x32_bf16 v[38:41], v[130:133], v[178:181], v[38:41]
	v_mfma_f32_16x16x32_bf16 v[34:37], v[138:141], v[178:181], v[34:37]
	v_mfma_f32_16x16x32_bf16 v[22:25], v[130:133], v[170:173], v[22:25]
	v_mfma_f32_16x16x32_bf16 v[18:21], v[138:141], v[170:173], v[18:21]
	v_mfma_f32_16x16x32_bf16 v[6:9], v[130:133], v[162:165], v[6:9]
	v_mfma_f32_16x16x32_bf16 v[2:5], v[138:141], v[162:165], v[2:5]
	v_mfma_f32_16x16x32_bf16 v[54:57], v[134:137], v[190:193], v[54:57]
	v_mfma_f32_16x16x32_bf16 v[50:53], v[142:145], v[190:193], v[50:53]
	v_mfma_f32_16x16x32_bf16 v[38:41], v[134:137], v[182:185], v[38:41]
	v_mfma_f32_16x16x32_bf16 v[34:37], v[142:145], v[182:185], v[34:37]
	v_mfma_f32_16x16x32_bf16 v[22:25], v[134:137], v[174:177], v[22:25]
	v_mfma_f32_16x16x32_bf16 v[18:21], v[142:145], v[174:177], v[18:21]
	v_mfma_f32_16x16x32_bf16 v[6:9], v[134:137], v[166:169], v[6:9]
	v_mfma_f32_16x16x32_bf16 v[2:5], v[142:145], v[166:169], v[2:5]
	s_barrier
	s_setprio 0
	s_add_i32 s20, 0, 0x18000
	s_add_i32 s21, 0, 0x1c000
	v_add_u32_e32 v142, s20, v246
	v_add_u32_e32 v158, s21, v246
	ds_read_b128 v[130:133], v142
	ds_read_b128 v[134:137], v142 offset:1024
	ds_read_b128 v[138:141], v142 offset:2048
	ds_read_b128 v[142:145], v142 offset:3072
	ds_read_b128 v[146:149], v158
	ds_read_b128 v[150:153], v158 offset:1024
	ds_read_b128 v[154:157], v158 offset:2048
	ds_read_b128 v[158:161], v158 offset:3072
	s_add_u32 s18, s18, 0xb0000
	s_addc_u32 s19, s19, 0
	s_mov_b32 m0, s39
	v_lshl_add_u64 v[194:195], s[18:19], 0, v[210:211]
	ds_read_b128 v[162:165], v247 offset:32768
	ds_read_b128 v[166:169], v247 offset:33792
	ds_read_b128 v[170:173], v247 offset:34816
	ds_read_b128 v[174:177], v247 offset:35840
	ds_read_b128 v[178:181], v247 offset:36864
	ds_read_b128 v[182:185], v247 offset:37888
	ds_read_b128 v[186:189], v247 offset:38912
	ds_read_b128 v[190:193], v247 offset:39936
	global_load_lds_dwordx4 v[194:195], off
	v_lshl_add_u64 v[194:195], s[18:19], 0, v[214:215]
	s_mov_b32 m0, s40
	s_nop 0
	global_load_lds_dwordx4 v[194:195], off
	s_waitcnt vmcnt(26)
	s_cmp_eq_u32 s100, 0
	s_cbranch_scc1 .Lthird_wait_relaxed_5
	s_waitcnt vmcnt(8)
; #define PG8_STAGE(bufoff, gbase, voff) do { _Pragma("unroll") for (int _i = 0; _i < 2; ++_i) \
;         __builtin_amdgcn_global_load_lds((const unsigned*)((const char*)(gbase) + (voff)[_i]), (PG8_LAS unsigned*)(lds + (bufoff) + ldsw + _i * 8192), 16, 0, 0); } while (0)
; #define PG8_LDA(dst, b, h) do { _Pragma("unroll") for (int m = 0; m < 4; ++m) _Pragma("unroll") for (int k = 0; k < 2; ++k) dst[m][k] = *(const PG8_LAS bf16x8*)(lds + PG8_SA(b, h) + aoff + m * 2048 + k * 1024); } while (0)
; #define PG8_LDB(dst, b, h) do { _Pragma("unroll") for (int n = 0; n < 2; ++n) _Pragma("unroll") for (int k = 0; k < 2; ++k) dst[n][k] = *(const PG8_LAS bf16x8*)(lds + PG8_SB(b, h) + boff + n * 2048 + k * 1024); } while (0)
; #define PG8_MMA(ai, bj, At, Bt) do { __builtin_amdgcn_s_setprio(1); _Pragma("unroll") for (int m = 0; m < 4; ++m) _Pragma("unroll") for (int n = 0; n < 2; ++n) _Pragma("unroll") for (int k = 0; k < 2; ++k) \
;         acc[ai][bj][m][n] = __builtin_amdgcn_mfma_f32_16x16x32_bf16(Bt[n][k], At[m][k], acc[ai][bj][m][n], 0, 0, 0); __builtin_amdgcn_s_setprio(0); } while (0)
; #define PG8_WAIT_V(n) asm volatile("s_waitcnt vmcnt(" #n ")" ::: "memory")
; #define PG8_WAIT_L(n) asm volatile("s_waitcnt lgkmcnt(" #n ")" ::: "memory")
; #define PG8_BAR __builtin_amdgcn_s_barrier()
; #define PG8_SCHED __builtin_amdgcn_sched_barrier(0)
; template <class Epi, class Sched, bool ALIGN_EPI = false, bool SP2 = false>
; __device__ __forceinline__ void gemm_phase(PG8_LAS unsigned char* lds, const Gemm g, const Sched& S, const Epi& E, const int wave_id) {
;     ...
;             PG8_LDB(B0, 1, 0); PG8_LDB(B1, 1, 1); PG8_SCHED; PG8_LDA(At, 1, 0); PG8_STAGE(PG8_SA(0, 1), a2 + hstep, voffA);
;             PG8_WAIT_V(8); PG8_WAIT_L(0); PG8_BAR; PG8_MMA(0, 0, At, B0); PG8_MMA(0, 1, At, B1); PG8_BAR; PG8_SCHED;
;             PG8_LDA(At, 1, 1); PG8_STAGE(PG8_SB(1, 0), b3, voffB); PG8_STAGE(PG8_SB(1, 1), b3 + hstep, voffB); PG8_STAGE(PG8_SA(1, 0), a3, voffA);
;             PG8_WAIT_V(8); PG8_WAIT_L(0); PG8_BAR; PG8_MMA(1, 0, At, B0); PG8_MMA(1, 1, At, B1); PG8_BAR; PG8_SCHED;
.Lthird_wait_relaxed_5:
	s_waitcnt lgkmcnt(0)
	s_setprio 1
	s_barrier
	v_mfma_f32_16x16x32_bf16 v[126:129], v[130:133], v[162:165], v[126:129]
	v_mfma_f32_16x16x32_bf16 v[122:125], v[138:141], v[162:165], v[122:125]
	v_mfma_f32_16x16x32_bf16 v[110:113], v[130:133], v[170:173], v[110:113]
	v_mfma_f32_16x16x32_bf16 v[106:109], v[138:141], v[170:173], v[106:109]
	v_mfma_f32_16x16x32_bf16 v[94:97], v[130:133], v[178:181], v[94:97]
	v_mfma_f32_16x16x32_bf16 v[90:93], v[138:141], v[178:181], v[90:93]
	v_mfma_f32_16x16x32_bf16 v[78:81], v[130:133], v[186:189], v[78:81]
	v_mfma_f32_16x16x32_bf16 v[74:77], v[138:141], v[186:189], v[74:77]
	v_mfma_f32_16x16x32_bf16 v[126:129], v[134:137], v[166:169], v[126:129]
	v_mfma_f32_16x16x32_bf16 v[122:125], v[142:145], v[166:169], v[122:125]
	v_mfma_f32_16x16x32_bf16 v[110:113], v[134:137], v[174:177], v[110:113]
	v_mfma_f32_16x16x32_bf16 v[106:109], v[142:145], v[174:177], v[106:109]
	v_mfma_f32_16x16x32_bf16 v[94:97], v[134:137], v[182:185], v[94:97]
	v_mfma_f32_16x16x32_bf16 v[90:93], v[142:145], v[182:185], v[90:93]
	v_mfma_f32_16x16x32_bf16 v[78:81], v[134:137], v[190:193], v[78:81]
	v_mfma_f32_16x16x32_bf16 v[74:77], v[142:145], v[190:193], v[74:77]
	v_mfma_f32_16x16x32_bf16 v[118:121], v[146:149], v[162:165], v[118:121]
	v_mfma_f32_16x16x32_bf16 v[114:117], v[154:157], v[162:165], v[114:117]
	v_mfma_f32_16x16x32_bf16 v[102:105], v[146:149], v[170:173], v[102:105]
	v_mfma_f32_16x16x32_bf16 v[98:101], v[154:157], v[170:173], v[98:101]
	v_mfma_f32_16x16x32_bf16 v[86:89], v[146:149], v[178:181], v[86:89]
	v_mfma_f32_16x16x32_bf16 v[82:85], v[154:157], v[178:181], v[82:85]
	v_mfma_f32_16x16x32_bf16 v[70:73], v[146:149], v[186:189], v[70:73]
	v_mfma_f32_16x16x32_bf16 v[66:69], v[154:157], v[186:189], v[66:69]
	v_mfma_f32_16x16x32_bf16 v[118:121], v[150:153], v[166:169], v[118:121]
	v_mfma_f32_16x16x32_bf16 v[114:117], v[158:161], v[166:169], v[114:117]
	v_mfma_f32_16x16x32_bf16 v[102:105], v[150:153], v[174:177], v[102:105]
	v_mfma_f32_16x16x32_bf16 v[98:101], v[158:161], v[174:177], v[98:101]
	v_mfma_f32_16x16x32_bf16 v[86:89], v[150:153], v[182:185], v[86:89]
	v_mfma_f32_16x16x32_bf16 v[82:85], v[158:161], v[182:185], v[82:85]
	v_mfma_f32_16x16x32_bf16 v[70:73], v[150:153], v[190:193], v[70:73]
	v_mfma_f32_16x16x32_bf16 v[66:69], v[158:161], v[190:193], v[66:69]
	s_barrier
	s_setprio 0
	s_add_i32 s18, s20, s30
	v_lshl_add_u64 v[194:195], v[232:233], 0, s[64:65]
	s_mov_b32 m0, s18
	ds_read_b128 v[162:165], v247 offset:49152
	ds_read_b128 v[166:169], v247 offset:50176
	ds_read_b128 v[170:173], v247 offset:51200
	ds_read_b128 v[174:177], v247 offset:52224
	ds_read_b128 v[178:181], v247 offset:53248
	ds_read_b128 v[182:185], v247 offset:54272
	ds_read_b128 v[186:189], v247 offset:55296
	ds_read_b128 v[190:193], v247 offset:56320
	global_load_lds_dwordx4 v[194:195], off
	s_add_i32 m0, s18, 0x2000
	s_add_u32 s16, s16, 0xb0080
	v_lshl_add_u64 v[194:195], v[230:231], 0, s[64:65]
	s_addc_u32 s17, s17, 0
	s_add_i32 s18, s21, s30
	global_load_lds_dwordx4 v[194:195], off
	v_lshl_add_u64 v[194:195], s[16:17], 0, v[212:213]
	s_mov_b32 m0, s18
	s_nop 0
	global_load_lds_dwordx4 v[194:195], off
	v_lshl_add_u64 v[194:195], s[16:17], 0, v[216:217]
	s_add_i32 m0, s18, 0x2000
	s_nop 0
	global_load_lds_dwordx4 v[194:195], off
	v_lshl_add_u64 v[194:195], v[226:227], 0, s[64:65]
	s_mov_b32 m0, s42
	s_nop 0
	global_load_lds_dwordx4 v[194:195], off
	v_lshl_add_u64 v[194:195], v[228:229], 0, s[64:65]
	s_mov_b32 m0, s43
	s_nop 0
	global_load_lds_dwordx4 v[194:195], off
	s_waitcnt vmcnt(8)
	s_waitcnt lgkmcnt(0)
	s_setprio 1
	s_barrier
	v_mfma_f32_16x16x32_bf16 v[62:65], v[130:133], v[162:165], v[62:65]
	v_mfma_f32_16x16x32_bf16 v[58:61], v[138:141], v[162:165], v[58:61]
	v_mfma_f32_16x16x32_bf16 v[46:49], v[130:133], v[170:173], v[46:49]
	v_mfma_f32_16x16x32_bf16 v[42:45], v[138:141], v[170:173], v[42:45]
	v_mfma_f32_16x16x32_bf16 v[30:33], v[130:133], v[178:181], v[30:33]
	v_mfma_f32_16x16x32_bf16 v[26:29], v[138:141], v[178:181], v[26:29]
	v_mfma_f32_16x16x32_bf16 v[14:17], v[130:133], v[186:189], v[14:17]
	v_mfma_f32_16x16x32_bf16 v[10:13], v[138:141], v[186:189], v[10:13]
	v_mfma_f32_16x16x32_bf16 v[62:65], v[134:137], v[166:169], v[62:65]
	v_mfma_f32_16x16x32_bf16 v[58:61], v[142:145], v[166:169], v[58:61]
	v_mfma_f32_16x16x32_bf16 v[46:49], v[134:137], v[174:177], v[46:49]
	v_mfma_f32_16x16x32_bf16 v[42:45], v[142:145], v[174:177], v[42:45]
	v_mfma_f32_16x16x32_bf16 v[30:33], v[134:137], v[182:185], v[30:33]
	v_mfma_f32_16x16x32_bf16 v[26:29], v[142:145], v[182:185], v[26:29]
	v_mfma_f32_16x16x32_bf16 v[14:17], v[134:137], v[190:193], v[14:17]
	v_mfma_f32_16x16x32_bf16 v[10:13], v[142:145], v[190:193], v[10:13]
	v_mfma_f32_16x16x32_bf16 v[54:57], v[146:149], v[162:165], v[54:57]
	v_mfma_f32_16x16x32_bf16 v[50:53], v[154:157], v[162:165], v[50:53]
	v_mfma_f32_16x16x32_bf16 v[38:41], v[146:149], v[170:173], v[38:41]
	v_mfma_f32_16x16x32_bf16 v[34:37], v[154:157], v[170:173], v[34:37]
	v_mfma_f32_16x16x32_bf16 v[22:25], v[146:149], v[178:181], v[22:25]
	v_mfma_f32_16x16x32_bf16 v[18:21], v[154:157], v[178:181], v[18:21]
	v_mfma_f32_16x16x32_bf16 v[6:9], v[146:149], v[186:189], v[6:9]
	v_mfma_f32_16x16x32_bf16 v[2:5], v[154:157], v[186:189], v[2:5]
	v_mfma_f32_16x16x32_bf16 v[54:57], v[150:153], v[166:169], v[54:57]
	v_mfma_f32_16x16x32_bf16 v[50:53], v[158:161], v[166:169], v[50:53]
	v_mfma_f32_16x16x32_bf16 v[38:41], v[150:153], v[174:177], v[38:41]
	v_mfma_f32_16x16x32_bf16 v[34:37], v[158:161], v[174:177], v[34:37]
	v_mfma_f32_16x16x32_bf16 v[22:25], v[150:153], v[182:185], v[22:25]
	v_mfma_f32_16x16x32_bf16 v[18:21], v[158:161], v[182:185], v[18:21]
	v_mfma_f32_16x16x32_bf16 v[6:9], v[150:153], v[190:193], v[6:9]
	v_mfma_f32_16x16x32_bf16 v[2:5], v[158:161], v[190:193], v[2:5]
	s_barrier
	s_setprio 0
	s_add_i32 s63, s63, 2
	s_add_u32 s14, s14, 0x100
	s_addc_u32 s15, s15, 0
	s_cmp_gt_u32 s63, 41
	s_cbranch_scc1 .LBB0_240

; #define PG8_STAGE(bufoff, gbase, voff) do { _Pragma("unroll") for (int _i = 0; _i < 2; ++_i) \
;         __builtin_amdgcn_global_load_lds((const unsigned*)((const char*)(gbase) + (voff)[_i]), (PG8_LAS unsigned*)(lds + (bufoff) + ldsw + _i * 8192), 16, 0, 0); } while (0)
; #define PG8_LDA(dst, b, h) do { _Pragma("unroll") for (int m = 0; m < 4; ++m) _Pragma("unroll") for (int k = 0; k < 2; ++k) dst[m][k] = *(const PG8_LAS bf16x8*)(lds + PG8_SA(b, h) + aoff + m * 2048 + k * 1024); } while (0)
; #define PG8_LDB(dst, b, h) do { _Pragma("unroll") for (int n = 0; n < 2; ++n) _Pragma("unroll") for (int k = 0; k < 2; ++k) dst[n][k] = *(const PG8_LAS bf16x8*)(lds + PG8_SB(b, h) + boff + n * 2048 + k * 1024); } while (0)
; #define PG8_WAIT_V(n) asm volatile("s_waitcnt vmcnt(" #n ")" ::: "memory")
; #define PG8_WAIT_VN(n) asm volatile("s_waitcnt vmcnt(%0)" :: "n"(n) : "memory")
; #define PG8_WAIT_L(n) asm volatile("s_waitcnt lgkmcnt(" #n ")" ::: "memory")
; template <class Epi, class Sched, bool ALIGN_EPI = false, bool SP2 = false>
; __device__ __forceinline__ void gemm_phase(PG8_LAS unsigned char* lds, const Gemm g, const Sched& S, const Epi& E, const int wave_id) {
;     ...
;         for (int t = 0; t < nt; t += 2) {
;             const bool last = (t == nt - 2);
;             const char* a1 = cA + (size_t)(t + 1) * kstep;
;             const char* a2 = last ? nA : cA + (size_t)(t + 2) * kstep; const char* b2 = last ? nB : cB + (size_t)(t + 2) * kstep;
;             const char* a3 = a2 + kstep; const char* b3 = b2 + kstep;
;             if (last && has_next) S.a_ready(nxt);
;             if constexpr (SP2) {
;             int tz_ = __builtin_amdgcn_readfirstlane(t | (ui > 0 ? 0 : 1)); asm volatile("" : "+s"(tz_));
;             const bool strict = !(Epi::NS > 0 && tz_ == 0);
;             PG8_LDB(B0, 0, 0); PG8_LDB(B1, 0, 1); PG8_SCHED; PG8_LDA(At, 0, 0); PG8_STAGE(PG8_SA(1, 1), a1 + hstep, voffA);
;             PG8_WAIT_VN(8 + Epi::NS); if (strict) PG8_WAIT_V(8); PG8_WAIT_L(0); PG8_BAR; PG8_MMA(0, 0, At, B0); PG8_MMA(0, 1, At, B1); PG8_BAR; PG8_SCHED;
;             PG8_LDA(At, 0, 1); PG8_STAGE(PG8_SB(0, 0), b2, voffB); PG8_STAGE(PG8_SB(0, 1), b2 + hstep, voffB); PG8_STAGE(PG8_SA(0, 0), a2, voffA);
;             PG8_WAIT_VN(8 + Epi::NS); if (strict) PG8_WAIT_V(8); PG8_WAIT_L(0); PG8_BAR; PG8_MMA(1, 0, At, B0); PG8_MMA(1, 1, At, B1); PG8_BAR; PG8_SCHED;
.LBB0_238:
	s_add_u32 s16, s12, s14
	s_addc_u32 s17, s13, s15
	s_add_u32 s16, s16, 0x100
	s_addc_u32 s17, s17, 0
	s_add_u32 s53, s57, s14
	s_addc_u32 s67, s62, s15
	s_cmpk_eq_i32 s14, 0x1500
	s_cselect_b32 s19, s7, s17
	s_cselect_b32 s18, s6, s16
	s_cselect_b32 s17, s11, s67
	s_cselect_b32 s16, s10, s53
	s_waitcnt lgkmcnt(0)
	s_setprio 1
	s_barrier
	v_mfma_f32_16x16x32_bf16 v[126:129], v[146:149], v[186:189], v[126:129]
	v_mfma_f32_16x16x32_bf16 v[122:125], v[154:157], v[186:189], v[122:125]
	v_mfma_f32_16x16x32_bf16 v[110:113], v[146:149], v[178:181], v[110:113]
	v_mfma_f32_16x16x32_bf16 v[106:109], v[154:157], v[178:181], v[106:109]
	v_mfma_f32_16x16x32_bf16 v[94:97], v[146:149], v[170:173], v[94:97]
	v_mfma_f32_16x16x32_bf16 v[90:93], v[154:157], v[170:173], v[90:93]
	v_mfma_f32_16x16x32_bf16 v[78:81], v[146:149], v[162:165], v[78:81]
	v_mfma_f32_16x16x32_bf16 v[74:77], v[154:157], v[162:165], v[74:77]
	v_mfma_f32_16x16x32_bf16 v[126:129], v[150:153], v[190:193], v[126:129]
	v_mfma_f32_16x16x32_bf16 v[122:125], v[158:161], v[190:193], v[122:125]
	v_mfma_f32_16x16x32_bf16 v[110:113], v[150:153], v[182:185], v[110:113]
	v_mfma_f32_16x16x32_bf16 v[106:109], v[158:161], v[182:185], v[106:109]
	v_mfma_f32_16x16x32_bf16 v[94:97], v[150:153], v[174:177], v[94:97]
	v_mfma_f32_16x16x32_bf16 v[90:93], v[158:161], v[174:177], v[90:93]
	v_mfma_f32_16x16x32_bf16 v[78:81], v[150:153], v[166:169], v[78:81]
	v_mfma_f32_16x16x32_bf16 v[74:77], v[158:161], v[166:169], v[74:77]
	v_mfma_f32_16x16x32_bf16 v[118:121], v[130:133], v[186:189], v[118:121]
	v_mfma_f32_16x16x32_bf16 v[114:117], v[138:141], v[186:189], v[114:117]
	v_mfma_f32_16x16x32_bf16 v[102:105], v[130:133], v[178:181], v[102:105]
	v_mfma_f32_16x16x32_bf16 v[98:101], v[138:141], v[178:181], v[98:101]
	v_mfma_f32_16x16x32_bf16 v[86:89], v[130:133], v[170:173], v[86:89]
	v_mfma_f32_16x16x32_bf16 v[82:85], v[138:141], v[170:173], v[82:85]
	v_mfma_f32_16x16x32_bf16 v[70:73], v[130:133], v[162:165], v[70:73]
	v_mfma_f32_16x16x32_bf16 v[66:69], v[138:141], v[162:165], v[66:69]
	v_mfma_f32_16x16x32_bf16 v[118:121], v[134:137], v[190:193], v[118:121]
	v_mfma_f32_16x16x32_bf16 v[114:117], v[142:145], v[190:193], v[114:117]
	v_mfma_f32_16x16x32_bf16 v[102:105], v[134:137], v[182:185], v[102:105]
	v_mfma_f32_16x16x32_bf16 v[98:101], v[142:145], v[182:185], v[98:101]
	v_mfma_f32_16x16x32_bf16 v[86:89], v[134:137], v[174:177], v[86:89]
	v_mfma_f32_16x16x32_bf16 v[82:85], v[142:145], v[174:177], v[82:85]
	v_mfma_f32_16x16x32_bf16 v[70:73], v[134:137], v[166:169], v[70:73]
	v_mfma_f32_16x16x32_bf16 v[66:69], v[142:145], v[166:169], v[66:69]
	s_barrier
	s_setprio 0
	s_mov_b32 m0, s34
	v_lshl_add_u64 v[232:233], s[16:17], 0, v[212:213]
	s_add_u32 s68, s16, 0xb0000
	ds_read_b128 v[186:189], v247 offset:16384
	ds_read_b128 v[190:193], v247 offset:17408
	ds_read_b128 v[178:181], v247 offset:18432
	ds_read_b128 v[182:185], v247 offset:19456
	ds_read_b128 v[170:173], v247 offset:20480
	ds_read_b128 v[174:177], v247 offset:21504
	ds_read_b128 v[162:165], v247 offset:22528
	ds_read_b128 v[166:169], v247 offset:23552
	global_load_lds_dwordx4 v[232:233], off
	v_lshl_add_u64 v[230:231], s[16:17], 0, v[216:217]
	s_mov_b32 m0, s35
	s_addc_u32 s69, s17, 0
	global_load_lds_dwordx4 v[230:231], off
	v_lshl_add_u64 v[194:195], s[68:69], 0, v[212:213]
	s_mov_b32 m0, s36
	v_lshl_add_u64 v[226:227], s[18:19], 0, v[210:211]
	global_load_lds_dwordx4 v[194:195], off
	v_lshl_add_u64 v[194:195], s[68:69], 0, v[216:217]
	s_mov_b32 m0, s37
	v_lshl_add_u64 v[228:229], s[18:19], 0, v[214:215]
	global_load_lds_dwordx4 v[194:195], off
	s_mov_b32 m0, s31
	s_andn2_b64 vcc, exec, s[20:21]
	global_load_lds_dwordx4 v[226:227], off
	s_mov_b32 m0, s38
	s_nop 0
	global_load_lds_dwordx4 v[228:229], off
	s_waitcnt vmcnt(24)
	s_cbranch_vccnz .LBB0_235
	s_waitcnt vmcnt(8)
	s_branch .LBB0_235

; #define PG8_STAGE(bufoff, gbase, voff) do { _Pragma("unroll") for (int _i = 0; _i < 2; ++_i) \
;         __builtin_amdgcn_global_load_lds((const unsigned*)((const char*)(gbase) + (voff)[_i]), (PG8_LAS unsigned*)(lds + (bufoff) + ldsw + _i * 8192), 16, 0, 0); } while (0)
; #define PG8_LDA(dst, b, h) do { _Pragma("unroll") for (int m = 0; m < 4; ++m) _Pragma("unroll") for (int k = 0; k < 2; ++k) dst[m][k] = *(const PG8_LAS bf16x8*)(lds + PG8_SA(b, h) + aoff + m * 2048 + k * 1024); } while (0)
; #define PG8_LDB(dst, b, h) do { _Pragma("unroll") for (int n = 0; n < 2; ++n) _Pragma("unroll") for (int k = 0; k < 2; ++k) dst[n][k] = *(const PG8_LAS bf16x8*)(lds + PG8_SB(b, h) + boff + n * 2048 + k * 1024); } while (0)
; #define PG8_MMA(ai, bj, At, Bt) do { __builtin_amdgcn_s_setprio(1); _Pragma("unroll") for (int m = 0; m < 4; ++m) _Pragma("unroll") for (int n = 0; n < 2; ++n) _Pragma("unroll") for (int k = 0; k < 2; ++k) \
;         acc[ai][bj][m][n] = __builtin_amdgcn_mfma_f32_16x16x32_bf16(Bt[n][k], At[m][k], acc[ai][bj][m][n], 0, 0, 0); __builtin_amdgcn_s_setprio(0); } while (0)
; #define PG8_WAIT_V(n) asm volatile("s_waitcnt vmcnt(" #n ")" ::: "memory")
; #define PG8_WAIT_VN(n) asm volatile("s_waitcnt vmcnt(%0)" :: "n"(n) : "memory")
; #define PG8_WAIT_L(n) asm volatile("s_waitcnt lgkmcnt(" #n ")" ::: "memory")
; #define PG8_BAR __builtin_amdgcn_s_barrier()
; #define PG8_SCHED __builtin_amdgcn_sched_barrier(0)
; template <class Epi, class Sched, bool ALIGN_EPI = false, bool SP2 = false>
; __device__ __forceinline__ void gemm_phase(PG8_LAS unsigned char* lds, const Gemm g, const Sched& S, const Epi& E, const int wave_id) {
;     ...
;             PG8_WAIT_VN(8 + Epi::NS); if (strict) PG8_WAIT_V(8); PG8_WAIT_L(0); PG8_BAR; PG8_MMA(1, 0, At, B0); PG8_MMA(1, 1, At, B1); PG8_BAR; PG8_SCHED;
;             PG8_LDB(B0, 1, 0); PG8_LDB(B1, 1, 1); PG8_SCHED; PG8_LDA(At, 1, 0); PG8_STAGE(PG8_SA(0, 1), a2 + hstep, voffA);
;             PG8_WAIT_V(8); PG8_WAIT_L(0); PG8_BAR; PG8_MMA(0, 0, At, B0); PG8_MMA(0, 1, At, B1); PG8_BAR; PG8_SCHED;
.LBB0_304:
	s_waitcnt lgkmcnt(0)
	s_setprio 1
	s_barrier
	v_mfma_f32_16x16x32_bf16 v[62:65], v[146:149], v[186:189], v[62:65]
	v_mfma_f32_16x16x32_bf16 v[58:61], v[154:157], v[186:189], v[58:61]
	v_mfma_f32_16x16x32_bf16 v[54:57], v[146:149], v[178:181], v[54:57]
	v_mfma_f32_16x16x32_bf16 v[50:53], v[154:157], v[178:181], v[50:53]
	v_mfma_f32_16x16x32_bf16 v[42:45], v[146:149], v[170:173], v[42:45]
	v_mfma_f32_16x16x32_bf16 v[34:37], v[154:157], v[170:173], v[34:37]
	v_mfma_f32_16x16x32_bf16 v[26:29], v[146:149], v[162:165], v[26:29]
	v_mfma_f32_16x16x32_bf16 v[18:21], v[154:157], v[162:165], v[18:21]
	v_mfma_f32_16x16x32_bf16 v[62:65], v[150:153], v[190:193], v[62:65]
	v_mfma_f32_16x16x32_bf16 v[58:61], v[158:161], v[190:193], v[58:61]
	v_mfma_f32_16x16x32_bf16 v[54:57], v[150:153], v[182:185], v[54:57]
	v_mfma_f32_16x16x32_bf16 v[50:53], v[158:161], v[182:185], v[50:53]
	v_mfma_f32_16x16x32_bf16 v[42:45], v[150:153], v[174:177], v[42:45]
	v_mfma_f32_16x16x32_bf16 v[34:37], v[158:161], v[174:177], v[34:37]
	v_mfma_f32_16x16x32_bf16 v[26:29], v[150:153], v[166:169], v[26:29]
	v_mfma_f32_16x16x32_bf16 v[18:21], v[158:161], v[166:169], v[18:21]
	v_mfma_f32_16x16x32_bf16 v[46:49], v[130:133], v[186:189], v[46:49]
	v_mfma_f32_16x16x32_bf16 v[38:41], v[138:141], v[186:189], v[38:41]
	v_mfma_f32_16x16x32_bf16 v[30:33], v[130:133], v[178:181], v[30:33]
	v_mfma_f32_16x16x32_bf16 v[22:25], v[138:141], v[178:181], v[22:25]
	v_mfma_f32_16x16x32_bf16 v[14:17], v[130:133], v[170:173], v[14:17]
	v_mfma_f32_16x16x32_bf16 v[10:13], v[138:141], v[170:173], v[10:13]
	v_mfma_f32_16x16x32_bf16 v[6:9], v[130:133], v[162:165], v[6:9]
	v_mfma_f32_16x16x32_bf16 v[2:5], v[138:141], v[162:165], v[2:5]
	v_mfma_f32_16x16x32_bf16 v[46:49], v[134:137], v[190:193], v[46:49]
	v_mfma_f32_16x16x32_bf16 v[38:41], v[142:145], v[190:193], v[38:41]
	v_mfma_f32_16x16x32_bf16 v[30:33], v[134:137], v[182:185], v[30:33]
	v_mfma_f32_16x16x32_bf16 v[22:25], v[142:145], v[182:185], v[22:25]
	v_mfma_f32_16x16x32_bf16 v[14:17], v[134:137], v[174:177], v[14:17]
	v_mfma_f32_16x16x32_bf16 v[10:13], v[142:145], v[174:177], v[10:13]
	v_mfma_f32_16x16x32_bf16 v[6:9], v[134:137], v[166:169], v[6:9]
	v_mfma_f32_16x16x32_bf16 v[2:5], v[142:145], v[166:169], v[2:5]
	s_barrier
	s_setprio 0
	s_add_i32 s16, 0, 0x18000
	s_add_i32 s17, 0, 0x1c000
	v_add_u32_e32 v142, s16, v231
	v_add_u32_e32 v158, s17, v231
	ds_read_b128 v[130:133], v142
	ds_read_b128 v[134:137], v142 offset:1024
	ds_read_b128 v[138:141], v142 offset:2048
	ds_read_b128 v[142:145], v142 offset:3072
	ds_read_b128 v[146:149], v158
	ds_read_b128 v[150:153], v158 offset:1024
	ds_read_b128 v[154:157], v158 offset:2048
	ds_read_b128 v[158:161], v158 offset:3072
	s_add_u32 s14, s14, 0xb0000
	s_addc_u32 s15, s15, 0
	s_mov_b32 m0, s29
	v_lshl_add_u64 v[194:195], s[14:15], 0, v[216:217]
	ds_read_b128 v[162:165], v232 offset:32768
	ds_read_b128 v[166:169], v232 offset:33792
	ds_read_b128 v[170:173], v232 offset:34816
	ds_read_b128 v[174:177], v232 offset:35840
	ds_read_b128 v[178:181], v232 offset:36864
	ds_read_b128 v[182:185], v232 offset:37888
	ds_read_b128 v[186:189], v232 offset:38912
	ds_read_b128 v[190:193], v232 offset:39936
	global_load_lds_dwordx4 v[194:195], off
	v_lshl_add_u64 v[194:195], s[14:15], 0, v[212:213]
	s_mov_b32 m0, s30
	s_nop 0
	global_load_lds_dwordx4 v[194:195], off
	s_waitcnt vmcnt(8)
	s_waitcnt lgkmcnt(0)
	s_setprio 1
	s_barrier
	v_mfma_f32_16x16x32_bf16 v[126:129], v[130:133], v[162:165], v[126:129]
	v_mfma_f32_16x16x32_bf16 v[122:125], v[138:141], v[162:165], v[122:125]
	v_mfma_f32_16x16x32_bf16 v[118:121], v[130:133], v[170:173], v[118:121]
	v_mfma_f32_16x16x32_bf16 v[114:117], v[138:141], v[170:173], v[114:117]
	v_mfma_f32_16x16x32_bf16 v[110:113], v[130:133], v[178:181], v[110:113]
	v_mfma_f32_16x16x32_bf16 v[102:105], v[138:141], v[178:181], v[102:105]
	v_mfma_f32_16x16x32_bf16 v[94:97], v[130:133], v[186:189], v[94:97]
	v_mfma_f32_16x16x32_bf16 v[86:89], v[138:141], v[186:189], v[86:89]
	v_mfma_f32_16x16x32_bf16 v[126:129], v[134:137], v[166:169], v[126:129]
	v_mfma_f32_16x16x32_bf16 v[122:125], v[142:145], v[166:169], v[122:125]
	v_mfma_f32_16x16x32_bf16 v[118:121], v[134:137], v[174:177], v[118:121]
	v_mfma_f32_16x16x32_bf16 v[114:117], v[142:145], v[174:177], v[114:117]
	v_mfma_f32_16x16x32_bf16 v[110:113], v[134:137], v[182:185], v[110:113]
	v_mfma_f32_16x16x32_bf16 v[102:105], v[142:145], v[182:185], v[102:105]
	v_mfma_f32_16x16x32_bf16 v[94:97], v[134:137], v[190:193], v[94:97]
	v_mfma_f32_16x16x32_bf16 v[86:89], v[142:145], v[190:193], v[86:89]
	v_mfma_f32_16x16x32_bf16 v[106:109], v[146:149], v[162:165], v[106:109]
	v_mfma_f32_16x16x32_bf16 v[98:101], v[154:157], v[162:165], v[98:101]
	v_mfma_f32_16x16x32_bf16 v[90:93], v[146:149], v[170:173], v[90:93]
	v_mfma_f32_16x16x32_bf16 v[82:85], v[154:157], v[170:173], v[82:85]
	v_mfma_f32_16x16x32_bf16 v[78:81], v[146:149], v[178:181], v[78:81]
	v_mfma_f32_16x16x32_bf16 v[74:77], v[154:157], v[178:181], v[74:77]
	v_mfma_f32_16x16x32_bf16 v[70:73], v[146:149], v[186:189], v[70:73]
	v_mfma_f32_16x16x32_bf16 v[66:69], v[154:157], v[186:189], v[66:69]
	v_mfma_f32_16x16x32_bf16 v[106:109], v[150:153], v[166:169], v[106:109]
	v_mfma_f32_16x16x32_bf16 v[98:101], v[158:161], v[166:169], v[98:101]
	v_mfma_f32_16x16x32_bf16 v[90:93], v[150:153], v[174:177], v[90:93]
	v_mfma_f32_16x16x32_bf16 v[82:85], v[158:161], v[174:177], v[82:85]
	v_mfma_f32_16x16x32_bf16 v[78:81], v[150:153], v[182:185], v[78:81]
	v_mfma_f32_16x16x32_bf16 v[74:77], v[158:161], v[182:185], v[74:77]
	v_mfma_f32_16x16x32_bf16 v[70:73], v[150:153], v[190:193], v[70:73]
	v_mfma_f32_16x16x32_bf16 v[66:69], v[158:161], v[190:193], v[66:69]
	s_barrier
; #define PG8_STAGE(bufoff, gbase, voff) do { _Pragma("unroll") for (int _i = 0; _i < 2; ++_i) \
;         __builtin_amdgcn_global_load_lds((const unsigned*)((const char*)(gbase) + (voff)[_i]), (PG8_LAS unsigned*)(lds + (bufoff) + ldsw + _i * 8192), 16, 0, 0); } while (0)
; #define PG8_LDA(dst, b, h) do { _Pragma("unroll") for (int m = 0; m < 4; ++m) _Pragma("unroll") for (int k = 0; k < 2; ++k) dst[m][k] = *(const PG8_LAS bf16x8*)(lds + PG8_SA(b, h) + aoff + m * 2048 + k * 1024); } while (0)
; #define PG8_MMA(ai, bj, At, Bt) do { __builtin_amdgcn_s_setprio(1); _Pragma("unroll") for (int m = 0; m < 4; ++m) _Pragma("unroll") for (int n = 0; n < 2; ++n) _Pragma("unroll") for (int k = 0; k < 2; ++k) \
;         acc[ai][bj][m][n] = __builtin_amdgcn_mfma_f32_16x16x32_bf16(Bt[n][k], At[m][k], acc[ai][bj][m][n], 0, 0, 0); __builtin_amdgcn_s_setprio(0); } while (0)
; #define PG8_WAIT_V(n) asm volatile("s_waitcnt vmcnt(" #n ")" ::: "memory")
; #define PG8_WAIT_L(n) asm volatile("s_waitcnt lgkmcnt(" #n ")" ::: "memory")
; #define PG8_BAR __builtin_amdgcn_s_barrier()
; #define PG8_SCHED __builtin_amdgcn_sched_barrier(0)
; template <class Epi, class Sched, bool ALIGN_EPI = false, bool SP2 = false>
; __device__ __forceinline__ void gemm_phase(PG8_LAS unsigned char* lds, const Gemm g, const Sched& S, const Epi& E, const int wave_id) {
;     ...
;             PG8_WAIT_V(8); PG8_WAIT_L(0); PG8_BAR; PG8_MMA(0, 0, At, B0); PG8_MMA(0, 1, At, B1); PG8_BAR; PG8_SCHED;
;             PG8_LDA(At, 1, 1); PG8_STAGE(PG8_SB(1, 0), b3, voffB); PG8_STAGE(PG8_SB(1, 1), b3 + hstep, voffB); PG8_STAGE(PG8_SA(1, 0), a3, voffA);
;             PG8_WAIT_V(8); PG8_WAIT_L(0); PG8_BAR; PG8_MMA(1, 0, At, B0); PG8_MMA(1, 1, At, B1); PG8_BAR; PG8_SCHED;
	s_setprio 0
	s_add_i32 s14, s16, s21
	v_lshl_add_u64 v[194:195], v[228:229], 0, s[64:65]
	s_mov_b32 m0, s14
	ds_read_b128 v[162:165], v232 offset:49152
	ds_read_b128 v[166:169], v232 offset:50176
	ds_read_b128 v[170:173], v232 offset:51200
	ds_read_b128 v[174:177], v232 offset:52224
	ds_read_b128 v[178:181], v232 offset:53248
	ds_read_b128 v[182:185], v232 offset:54272
	ds_read_b128 v[186:189], v232 offset:55296
	ds_read_b128 v[190:193], v232 offset:56320
	global_load_lds_dwordx4 v[194:195], off
	s_add_i32 m0, s14, 0x2000
	s_add_u32 s12, s12, 0xb0080
	v_lshl_add_u64 v[194:195], v[226:227], 0, s[64:65]
	s_addc_u32 s13, s13, 0
	s_add_i32 s14, s17, s21
	global_load_lds_dwordx4 v[194:195], off
	v_lshl_add_u64 v[194:195], s[12:13], 0, v[214:215]
	s_mov_b32 m0, s14
	s_nop 0
	global_load_lds_dwordx4 v[194:195], off
	v_lshl_add_u64 v[194:195], s[12:13], 0, v[210:211]
	s_add_i32 m0, s14, 0x2000
	s_nop 0
	global_load_lds_dwordx4 v[194:195], off
	v_lshl_add_u64 v[194:195], v[222:223], 0, s[64:65]
	s_mov_b32 m0, s31
	s_nop 0
	global_load_lds_dwordx4 v[194:195], off
	v_lshl_add_u64 v[194:195], v[224:225], 0, s[64:65]
	s_mov_b32 m0, s34
	s_nop 0
	global_load_lds_dwordx4 v[194:195], off
	s_waitcnt vmcnt(8)
	s_waitcnt lgkmcnt(0)
	s_setprio 1
	s_barrier
	v_mfma_f32_16x16x32_bf16 v[62:65], v[130:133], v[162:165], v[62:65]
	v_mfma_f32_16x16x32_bf16 v[58:61], v[138:141], v[162:165], v[58:61]
	v_mfma_f32_16x16x32_bf16 v[54:57], v[130:133], v[170:173], v[54:57]
	v_mfma_f32_16x16x32_bf16 v[50:53], v[138:141], v[170:173], v[50:53]
	v_mfma_f32_16x16x32_bf16 v[42:45], v[130:133], v[178:181], v[42:45]
	v_mfma_f32_16x16x32_bf16 v[34:37], v[138:141], v[178:181], v[34:37]
	v_mfma_f32_16x16x32_bf16 v[26:29], v[130:133], v[186:189], v[26:29]
	v_mfma_f32_16x16x32_bf16 v[18:21], v[138:141], v[186:189], v[18:21]
	v_mfma_f32_16x16x32_bf16 v[62:65], v[134:137], v[166:169], v[62:65]
	v_mfma_f32_16x16x32_bf16 v[58:61], v[142:145], v[166:169], v[58:61]
	v_mfma_f32_16x16x32_bf16 v[54:57], v[134:137], v[174:177], v[54:57]
	v_mfma_f32_16x16x32_bf16 v[50:53], v[142:145], v[174:177], v[50:53]
	v_mfma_f32_16x16x32_bf16 v[42:45], v[134:137], v[182:185], v[42:45]
	v_mfma_f32_16x16x32_bf16 v[34:37], v[142:145], v[182:185], v[34:37]
	v_mfma_f32_16x16x32_bf16 v[26:29], v[134:137], v[190:193], v[26:29]
	v_mfma_f32_16x16x32_bf16 v[18:21], v[142:145], v[190:193], v[18:21]
	v_mfma_f32_16x16x32_bf16 v[46:49], v[146:149], v[162:165], v[46:49]
	v_mfma_f32_16x16x32_bf16 v[38:41], v[154:157], v[162:165], v[38:41]
	v_mfma_f32_16x16x32_bf16 v[30:33], v[146:149], v[170:173], v[30:33]
	v_mfma_f32_16x16x32_bf16 v[22:25], v[154:157], v[170:173], v[22:25]
	v_mfma_f32_16x16x32_bf16 v[14:17], v[146:149], v[178:181], v[14:17]
	v_mfma_f32_16x16x32_bf16 v[10:13], v[154:157], v[178:181], v[10:13]
	v_mfma_f32_16x16x32_bf16 v[6:9], v[146:149], v[186:189], v[6:9]
	v_mfma_f32_16x16x32_bf16 v[2:5], v[154:157], v[186:189], v[2:5]
	v_mfma_f32_16x16x32_bf16 v[46:49], v[150:153], v[166:169], v[46:49]
	v_mfma_f32_16x16x32_bf16 v[38:41], v[158:161], v[166:169], v[38:41]
	v_mfma_f32_16x16x32_bf16 v[30:33], v[150:153], v[174:177], v[30:33]
	v_mfma_f32_16x16x32_bf16 v[22:25], v[158:161], v[174:177], v[22:25]
	v_mfma_f32_16x16x32_bf16 v[14:17], v[150:153], v[182:185], v[14:17]
	v_mfma_f32_16x16x32_bf16 v[10:13], v[158:161], v[182:185], v[10:13]
	v_mfma_f32_16x16x32_bf16 v[6:9], v[150:153], v[190:193], v[6:9]
	v_mfma_f32_16x16x32_bf16 v[2:5], v[158:161], v[190:193], v[2:5]
	s_barrier
	s_setprio 0
	s_add_u32 s10, s10, 0x100
	s_addc_u32 s11, s11, 0
	s_cmp_gt_u32 s39, 19
	v_readlane_b32 s40, v254, 55
	s_cbranch_scc1 .LBB0_309

; #define PG8_STAGE(bufoff, gbase, voff) do { _Pragma("unroll") for (int _i = 0; _i < 2; ++_i) \
;         __builtin_amdgcn_global_load_lds((const unsigned*)((const char*)(gbase) + (voff)[_i]), (PG8_LAS unsigned*)(lds + (bufoff) + ldsw + _i * 8192), 16, 0, 0); } while (0)
; #define PG8_LDA(dst, b, h) do { _Pragma("unroll") for (int m = 0; m < 4; ++m) _Pragma("unroll") for (int k = 0; k < 2; ++k) dst[m][k] = *(const PG8_LAS bf16x8*)(lds + PG8_SA(b, h) + aoff + m * 2048 + k * 1024); } while (0)
; #define PG8_LDB(dst, b, h) do { _Pragma("unroll") for (int n = 0; n < 2; ++n) _Pragma("unroll") for (int k = 0; k < 2; ++k) dst[n][k] = *(const PG8_LAS bf16x8*)(lds + PG8_SB(b, h) + boff + n * 2048 + k * 1024); } while (0)
; #define PG8_WAIT_V(n) asm volatile("s_waitcnt vmcnt(" #n ")" ::: "memory")
; #define PG8_WAIT_VN(n) asm volatile("s_waitcnt vmcnt(%0)" :: "n"(n) : "memory")
; #define PG8_WAIT_L(n) asm volatile("s_waitcnt lgkmcnt(" #n ")" ::: "memory")
; template <class Epi, class Sched, bool ALIGN_EPI = false, bool SP2 = false>
; __device__ __forceinline__ void gemm_phase(PG8_LAS unsigned char* lds, const Gemm g, const Sched& S, const Epi& E, const int wave_id) {
;     ...
;         for (int t = 0; t < nt; t += 2) {
;             const bool last = (t == nt - 2);
;             const char* a1 = cA + (size_t)(t + 1) * kstep;
;             const char* a2 = last ? nA : cA + (size_t)(t + 2) * kstep; const char* b2 = last ? nB : cB + (size_t)(t + 2) * kstep;
;             const char* a3 = a2 + kstep; const char* b3 = b2 + kstep;
;             if (last && has_next) S.a_ready(nxt);
;             if constexpr (SP2) {
;             int tz_ = __builtin_amdgcn_readfirstlane(t | (ui > 0 ? 0 : 1)); asm volatile("" : "+s"(tz_));
;             const bool strict = !(Epi::NS > 0 && tz_ == 0);
;             PG8_LDB(B0, 0, 0); PG8_LDB(B1, 0, 1); PG8_SCHED; PG8_LDA(At, 0, 0); PG8_STAGE(PG8_SA(1, 1), a1 + hstep, voffA);
;             PG8_WAIT_VN(8 + Epi::NS); if (strict) PG8_WAIT_V(8); PG8_WAIT_L(0); PG8_BAR; PG8_MMA(0, 0, At, B0); PG8_MMA(0, 1, At, B1); PG8_BAR; PG8_SCHED;
;             PG8_LDA(At, 0, 1); PG8_STAGE(PG8_SB(0, 0), b2, voffB); PG8_STAGE(PG8_SB(0, 1), b2 + hstep, voffB); PG8_STAGE(PG8_SA(0, 0), a2, voffA);
;             PG8_WAIT_VN(8 + Epi::NS); if (strict) PG8_WAIT_V(8); PG8_WAIT_L(0); PG8_BAR; PG8_MMA(1, 0, At, B0); PG8_MMA(1, 1, At, B1); PG8_BAR; PG8_SCHED;
.LBB0_307:
	s_add_u32 s12, s37, s10
	s_addc_u32 s13, s38, s11
	s_add_u32 s12, s12, 0x26300100
	s_addc_u32 s13, s13, 0
	s_add_u32 s40, s35, s10
	s_addc_u32 s41, s36, s11
	s_cmpk_eq_i32 s10, 0xa00
	s_cselect_b32 s15, s9, s13
	s_cselect_b32 s14, s8, s12
	s_cselect_b32 s13, s7, s41
	s_cselect_b32 s12, s6, s40
	s_waitcnt lgkmcnt(0)
	s_setprio 1
	s_barrier
	v_mfma_f32_16x16x32_bf16 v[126:129], v[146:149], v[186:189], v[126:129]
	v_mfma_f32_16x16x32_bf16 v[122:125], v[154:157], v[186:189], v[122:125]
	v_mfma_f32_16x16x32_bf16 v[118:121], v[146:149], v[178:181], v[118:121]
	v_mfma_f32_16x16x32_bf16 v[114:117], v[154:157], v[178:181], v[114:117]
	v_mfma_f32_16x16x32_bf16 v[110:113], v[146:149], v[170:173], v[110:113]
	v_mfma_f32_16x16x32_bf16 v[102:105], v[154:157], v[170:173], v[102:105]
	v_mfma_f32_16x16x32_bf16 v[94:97], v[146:149], v[162:165], v[94:97]
	v_mfma_f32_16x16x32_bf16 v[86:89], v[154:157], v[162:165], v[86:89]
	v_mfma_f32_16x16x32_bf16 v[126:129], v[150:153], v[190:193], v[126:129]
	v_mfma_f32_16x16x32_bf16 v[122:125], v[158:161], v[190:193], v[122:125]
	v_mfma_f32_16x16x32_bf16 v[118:121], v[150:153], v[182:185], v[118:121]
	v_mfma_f32_16x16x32_bf16 v[114:117], v[158:161], v[182:185], v[114:117]
	v_mfma_f32_16x16x32_bf16 v[110:113], v[150:153], v[174:177], v[110:113]
	v_mfma_f32_16x16x32_bf16 v[102:105], v[158:161], v[174:177], v[102:105]
	v_mfma_f32_16x16x32_bf16 v[94:97], v[150:153], v[166:169], v[94:97]
	v_mfma_f32_16x16x32_bf16 v[86:89], v[158:161], v[166:169], v[86:89]
	v_mfma_f32_16x16x32_bf16 v[106:109], v[130:133], v[186:189], v[106:109]
	v_mfma_f32_16x16x32_bf16 v[98:101], v[138:141], v[186:189], v[98:101]
	v_mfma_f32_16x16x32_bf16 v[90:93], v[130:133], v[178:181], v[90:93]
	v_mfma_f32_16x16x32_bf16 v[82:85], v[138:141], v[178:181], v[82:85]
	v_mfma_f32_16x16x32_bf16 v[78:81], v[130:133], v[170:173], v[78:81]
	v_mfma_f32_16x16x32_bf16 v[74:77], v[138:141], v[170:173], v[74:77]
	v_mfma_f32_16x16x32_bf16 v[70:73], v[130:133], v[162:165], v[70:73]
	v_mfma_f32_16x16x32_bf16 v[66:69], v[138:141], v[162:165], v[66:69]
	v_mfma_f32_16x16x32_bf16 v[106:109], v[134:137], v[190:193], v[106:109]
	v_mfma_f32_16x16x32_bf16 v[98:101], v[142:145], v[190:193], v[98:101]
	v_mfma_f32_16x16x32_bf16 v[90:93], v[134:137], v[182:185], v[90:93]
	v_mfma_f32_16x16x32_bf16 v[82:85], v[142:145], v[182:185], v[82:85]
	v_mfma_f32_16x16x32_bf16 v[78:81], v[134:137], v[174:177], v[78:81]
	v_mfma_f32_16x16x32_bf16 v[74:77], v[142:145], v[174:177], v[74:77]
	v_mfma_f32_16x16x32_bf16 v[70:73], v[134:137], v[166:169], v[70:73]
	v_mfma_f32_16x16x32_bf16 v[66:69], v[142:145], v[166:169], v[66:69]
	s_barrier
	s_setprio 0
	s_mov_b32 m0, s23
	v_lshl_add_u64 v[228:229], s[12:13], 0, v[214:215]
	s_add_u32 s40, s12, 0xb0000
	ds_read_b128 v[186:189], v232 offset:16384
	ds_read_b128 v[190:193], v232 offset:17408
	ds_read_b128 v[178:181], v232 offset:18432
	ds_read_b128 v[182:185], v232 offset:19456
	ds_read_b128 v[170:173], v232 offset:20480
	ds_read_b128 v[174:177], v232 offset:21504
	ds_read_b128 v[162:165], v232 offset:22528
	ds_read_b128 v[166:169], v232 offset:23552
	global_load_lds_dwordx4 v[228:229], off
	v_lshl_add_u64 v[226:227], s[12:13], 0, v[210:211]
	s_mov_b32 m0, s24
	s_addc_u32 s41, s13, 0
	global_load_lds_dwordx4 v[226:227], off
	v_lshl_add_u64 v[194:195], s[40:41], 0, v[214:215]
	s_mov_b32 m0, s25
	v_lshl_add_u64 v[222:223], s[14:15], 0, v[216:217]
	global_load_lds_dwordx4 v[194:195], off
	v_lshl_add_u64 v[194:195], s[40:41], 0, v[210:211]
	s_mov_b32 m0, s26
	v_lshl_add_u64 v[224:225], s[14:15], 0, v[212:213]
	global_load_lds_dwordx4 v[194:195], off
	s_mov_b32 m0, s22
	s_andn2_b64 vcc, exec, s[16:17]
	global_load_lds_dwordx4 v[222:223], off
	s_mov_b32 m0, s28
	s_nop 0
	global_load_lds_dwordx4 v[224:225], off
	s_waitcnt vmcnt(24)
	s_cbranch_vccnz .LBB0_304
	s_waitcnt vmcnt(8)
	s_branch .LBB0_304

; #define PG8_STAGE(bufoff, gbase, voff) do { _Pragma("unroll") for (int _i = 0; _i < 2; ++_i) \
;         __builtin_amdgcn_global_load_lds((const unsigned*)((const char*)(gbase) + (voff)[_i]), (PG8_LAS unsigned*)(lds + (bufoff) + ldsw + _i * 8192), 16, 0, 0); } while (0)
; #define PG8_LDA(dst, b, h) do { _Pragma("unroll") for (int m = 0; m < 4; ++m) _Pragma("unroll") for (int k = 0; k < 2; ++k) dst[m][k] = *(const PG8_LAS bf16x8*)(lds + PG8_SA(b, h) + aoff + m * 2048 + k * 1024); } while (0)
; #define PG8_LDB(dst, b, h) do { _Pragma("unroll") for (int n = 0; n < 2; ++n) _Pragma("unroll") for (int k = 0; k < 2; ++k) dst[n][k] = *(const PG8_LAS bf16x8*)(lds + PG8_SB(b, h) + boff + n * 2048 + k * 1024); } while (0)
; #define PG8_MMA(ai, bj, At, Bt) do { __builtin_amdgcn_s_setprio(1); _Pragma("unroll") for (int m = 0; m < 4; ++m) _Pragma("unroll") for (int n = 0; n < 2; ++n) _Pragma("unroll") for (int k = 0; k < 2; ++k) \
;         acc[ai][bj][m][n] = __builtin_amdgcn_mfma_f32_16x16x32_bf16(Bt[n][k], At[m][k], acc[ai][bj][m][n], 0, 0, 0); __builtin_amdgcn_s_setprio(0); } while (0)
; #define PG8_WAIT_V(n) asm volatile("s_waitcnt vmcnt(" #n ")" ::: "memory")
; #define PG8_WAIT_VN(n) asm volatile("s_waitcnt vmcnt(%0)" :: "n"(n) : "memory")
; #define PG8_WAIT_L(n) asm volatile("s_waitcnt lgkmcnt(" #n ")" ::: "memory")
; #define PG8_BAR __builtin_amdgcn_s_barrier()
; #define PG8_SCHED __builtin_amdgcn_sched_barrier(0)
; template <class Epi, class Sched, bool ALIGN_EPI = false, bool SP2 = false>
; __device__ __forceinline__ void gemm_phase(PG8_LAS unsigned char* lds, const Gemm g, const Sched& S, const Epi& E, const int wave_id) {
;     ...
;             PG8_WAIT_VN(8 + Epi::NS); if (strict) PG8_WAIT_V(8); PG8_WAIT_L(0); PG8_BAR; PG8_MMA(1, 0, At, B0); PG8_MMA(1, 1, At, B1); PG8_BAR; PG8_SCHED;
;             PG8_LDB(B0, 1, 0); PG8_LDB(B1, 1, 1); PG8_SCHED; PG8_LDA(At, 1, 0); PG8_STAGE(PG8_SA(0, 1), a2 + hstep, voffA);
;             PG8_WAIT_V(8); PG8_WAIT_L(0); PG8_BAR; PG8_MMA(0, 0, At, B0); PG8_MMA(0, 1, At, B1); PG8_BAR; PG8_SCHED;
.LBB0_420:
	s_waitcnt lgkmcnt(0)
	s_setprio 1
	s_barrier
	v_mfma_f32_16x16x32_bf16 v[62:65], v[146:149], v[186:189], v[62:65]
	v_mfma_f32_16x16x32_bf16 v[58:61], v[154:157], v[186:189], v[58:61]
	v_mfma_f32_16x16x32_bf16 v[46:49], v[146:149], v[178:181], v[46:49]
	v_mfma_f32_16x16x32_bf16 v[42:45], v[154:157], v[178:181], v[42:45]
	v_mfma_f32_16x16x32_bf16 v[30:33], v[146:149], v[170:173], v[30:33]
	v_mfma_f32_16x16x32_bf16 v[26:29], v[154:157], v[170:173], v[26:29]
	v_mfma_f32_16x16x32_bf16 v[14:17], v[146:149], v[162:165], v[14:17]
	v_mfma_f32_16x16x32_bf16 v[10:13], v[154:157], v[162:165], v[10:13]
	v_mfma_f32_16x16x32_bf16 v[62:65], v[150:153], v[190:193], v[62:65]
	v_mfma_f32_16x16x32_bf16 v[58:61], v[158:161], v[190:193], v[58:61]
	v_mfma_f32_16x16x32_bf16 v[46:49], v[150:153], v[182:185], v[46:49]
	v_mfma_f32_16x16x32_bf16 v[42:45], v[158:161], v[182:185], v[42:45]
	v_mfma_f32_16x16x32_bf16 v[30:33], v[150:153], v[174:177], v[30:33]
	v_mfma_f32_16x16x32_bf16 v[26:29], v[158:161], v[174:177], v[26:29]
	v_mfma_f32_16x16x32_bf16 v[14:17], v[150:153], v[166:169], v[14:17]
	v_mfma_f32_16x16x32_bf16 v[10:13], v[158:161], v[166:169], v[10:13]
	v_mfma_f32_16x16x32_bf16 v[54:57], v[130:133], v[186:189], v[54:57]
	v_mfma_f32_16x16x32_bf16 v[50:53], v[138:141], v[186:189], v[50:53]
	v_mfma_f32_16x16x32_bf16 v[38:41], v[130:133], v[178:181], v[38:41]
	v_mfma_f32_16x16x32_bf16 v[34:37], v[138:141], v[178:181], v[34:37]
	v_mfma_f32_16x16x32_bf16 v[22:25], v[130:133], v[170:173], v[22:25]
	v_mfma_f32_16x16x32_bf16 v[18:21], v[138:141], v[170:173], v[18:21]
	v_mfma_f32_16x16x32_bf16 v[6:9], v[130:133], v[162:165], v[6:9]
	v_mfma_f32_16x16x32_bf16 v[2:5], v[138:141], v[162:165], v[2:5]
	v_mfma_f32_16x16x32_bf16 v[54:57], v[134:137], v[190:193], v[54:57]
	v_mfma_f32_16x16x32_bf16 v[50:53], v[142:145], v[190:193], v[50:53]
	v_mfma_f32_16x16x32_bf16 v[38:41], v[134:137], v[182:185], v[38:41]
	v_mfma_f32_16x16x32_bf16 v[34:37], v[142:145], v[182:185], v[34:37]
	v_mfma_f32_16x16x32_bf16 v[22:25], v[134:137], v[174:177], v[22:25]
	v_mfma_f32_16x16x32_bf16 v[18:21], v[142:145], v[174:177], v[18:21]
	v_mfma_f32_16x16x32_bf16 v[6:9], v[134:137], v[166:169], v[6:9]
	v_mfma_f32_16x16x32_bf16 v[2:5], v[142:145], v[166:169], v[2:5]
	s_barrier
	s_setprio 0
	s_add_i32 s34, 0, 0x18000
	s_add_i32 s35, 0, 0x1c000
	v_add_u32_e32 v142, s34, v246
	v_add_u32_e32 v158, s35, v246
	ds_read_b128 v[130:133], v142
	ds_read_b128 v[134:137], v142 offset:1024
	ds_read_b128 v[138:141], v142 offset:2048
	ds_read_b128 v[142:145], v142 offset:3072
	ds_read_b128 v[146:149], v158
	ds_read_b128 v[150:153], v158 offset:1024
	ds_read_b128 v[154:157], v158 offset:2048
	ds_read_b128 v[158:161], v158 offset:3072
	s_add_u32 s14, s14, 0x40000
	s_addc_u32 s15, s15, 0
	s_mov_b32 m0, s3
	v_lshl_add_u64 v[194:195], s[14:15], 0, v[210:211]
	ds_read_b128 v[162:165], v247 offset:32768
	ds_read_b128 v[166:169], v247 offset:33792
	ds_read_b128 v[170:173], v247 offset:34816
	ds_read_b128 v[174:177], v247 offset:35840
	ds_read_b128 v[178:181], v247 offset:36864
	ds_read_b128 v[182:185], v247 offset:37888
	ds_read_b128 v[186:189], v247 offset:38912
	ds_read_b128 v[190:193], v247 offset:39936
	global_load_lds_dwordx4 v[194:195], off
	v_lshl_add_u64 v[194:195], s[14:15], 0, v[214:215]
	s_mov_b32 m0, s4
	s_nop 0
	global_load_lds_dwordx4 v[194:195], off
	s_waitcnt vmcnt(26)
	s_cmp_eq_u32 s100, 0
	s_cbranch_scc1 .Lthird_wait_relaxed_4
	s_waitcnt vmcnt(8)
; #define PG8_STAGE(bufoff, gbase, voff) do { _Pragma("unroll") for (int _i = 0; _i < 2; ++_i) \
;         __builtin_amdgcn_global_load_lds((const unsigned*)((const char*)(gbase) + (voff)[_i]), (PG8_LAS unsigned*)(lds + (bufoff) + ldsw + _i * 8192), 16, 0, 0); } while (0)
; #define PG8_LDA(dst, b, h) do { _Pragma("unroll") for (int m = 0; m < 4; ++m) _Pragma("unroll") for (int k = 0; k < 2; ++k) dst[m][k] = *(const PG8_LAS bf16x8*)(lds + PG8_SA(b, h) + aoff + m * 2048 + k * 1024); } while (0)
; #define PG8_LDB(dst, b, h) do { _Pragma("unroll") for (int n = 0; n < 2; ++n) _Pragma("unroll") for (int k = 0; k < 2; ++k) dst[n][k] = *(const PG8_LAS bf16x8*)(lds + PG8_SB(b, h) + boff + n * 2048 + k * 1024); } while (0)
; #define PG8_MMA(ai, bj, At, Bt) do { __builtin_amdgcn_s_setprio(1); _Pragma("unroll") for (int m = 0; m < 4; ++m) _Pragma("unroll") for (int n = 0; n < 2; ++n) _Pragma("unroll") for (int k = 0; k < 2; ++k) \
;         acc[ai][bj][m][n] = __builtin_amdgcn_mfma_f32_16x16x32_bf16(Bt[n][k], At[m][k], acc[ai][bj][m][n], 0, 0, 0); __builtin_amdgcn_s_setprio(0); } while (0)
; #define PG8_WAIT_V(n) asm volatile("s_waitcnt vmcnt(" #n ")" ::: "memory")
; #define PG8_WAIT_L(n) asm volatile("s_waitcnt lgkmcnt(" #n ")" ::: "memory")
; #define PG8_BAR __builtin_amdgcn_s_barrier()
; #define PG8_SCHED __builtin_amdgcn_sched_barrier(0)
; template <class Epi, class Sched, bool ALIGN_EPI = false, bool SP2 = false>
; __device__ __forceinline__ void gemm_phase(PG8_LAS unsigned char* lds, const Gemm g, const Sched& S, const Epi& E, const int wave_id) {
;     ...
;             PG8_LDB(B0, 1, 0); PG8_LDB(B1, 1, 1); PG8_SCHED; PG8_LDA(At, 1, 0); PG8_STAGE(PG8_SA(0, 1), a2 + hstep, voffA);
;             PG8_WAIT_V(8); PG8_WAIT_L(0); PG8_BAR; PG8_MMA(0, 0, At, B0); PG8_MMA(0, 1, At, B1); PG8_BAR; PG8_SCHED;
;             PG8_LDA(At, 1, 1); PG8_STAGE(PG8_SB(1, 0), b3, voffB); PG8_STAGE(PG8_SB(1, 1), b3 + hstep, voffB); PG8_STAGE(PG8_SA(1, 0), a3, voffA);
;             PG8_WAIT_V(8); PG8_WAIT_L(0); PG8_BAR; PG8_MMA(1, 0, At, B0); PG8_MMA(1, 1, At, B1); PG8_BAR; PG8_SCHED;
.Lthird_wait_relaxed_4:
	s_waitcnt lgkmcnt(0)
	s_setprio 1
	s_barrier
	v_mfma_f32_16x16x32_bf16 v[126:129], v[130:133], v[162:165], v[126:129]
	v_mfma_f32_16x16x32_bf16 v[122:125], v[138:141], v[162:165], v[122:125]
	v_mfma_f32_16x16x32_bf16 v[110:113], v[130:133], v[170:173], v[110:113]
	v_mfma_f32_16x16x32_bf16 v[106:109], v[138:141], v[170:173], v[106:109]
	v_mfma_f32_16x16x32_bf16 v[94:97], v[130:133], v[178:181], v[94:97]
	v_mfma_f32_16x16x32_bf16 v[90:93], v[138:141], v[178:181], v[90:93]
	v_mfma_f32_16x16x32_bf16 v[78:81], v[130:133], v[186:189], v[78:81]
	v_mfma_f32_16x16x32_bf16 v[74:77], v[138:141], v[186:189], v[74:77]
	v_mfma_f32_16x16x32_bf16 v[126:129], v[134:137], v[166:169], v[126:129]
	v_mfma_f32_16x16x32_bf16 v[122:125], v[142:145], v[166:169], v[122:125]
	v_mfma_f32_16x16x32_bf16 v[110:113], v[134:137], v[174:177], v[110:113]
	v_mfma_f32_16x16x32_bf16 v[106:109], v[142:145], v[174:177], v[106:109]
	v_mfma_f32_16x16x32_bf16 v[94:97], v[134:137], v[182:185], v[94:97]
	v_mfma_f32_16x16x32_bf16 v[90:93], v[142:145], v[182:185], v[90:93]
	v_mfma_f32_16x16x32_bf16 v[78:81], v[134:137], v[190:193], v[78:81]
	v_mfma_f32_16x16x32_bf16 v[74:77], v[142:145], v[190:193], v[74:77]
	v_mfma_f32_16x16x32_bf16 v[118:121], v[146:149], v[162:165], v[118:121]
	v_mfma_f32_16x16x32_bf16 v[114:117], v[154:157], v[162:165], v[114:117]
	v_mfma_f32_16x16x32_bf16 v[102:105], v[146:149], v[170:173], v[102:105]
	v_mfma_f32_16x16x32_bf16 v[98:101], v[154:157], v[170:173], v[98:101]
	v_mfma_f32_16x16x32_bf16 v[86:89], v[146:149], v[178:181], v[86:89]
	v_mfma_f32_16x16x32_bf16 v[82:85], v[154:157], v[178:181], v[82:85]
	v_mfma_f32_16x16x32_bf16 v[70:73], v[146:149], v[186:189], v[70:73]
	v_mfma_f32_16x16x32_bf16 v[66:69], v[154:157], v[186:189], v[66:69]
	v_mfma_f32_16x16x32_bf16 v[118:121], v[150:153], v[166:169], v[118:121]
	v_mfma_f32_16x16x32_bf16 v[114:117], v[158:161], v[166:169], v[114:117]
	v_mfma_f32_16x16x32_bf16 v[102:105], v[150:153], v[174:177], v[102:105]
	v_mfma_f32_16x16x32_bf16 v[98:101], v[158:161], v[174:177], v[98:101]
	v_mfma_f32_16x16x32_bf16 v[86:89], v[150:153], v[182:185], v[86:89]
	v_mfma_f32_16x16x32_bf16 v[82:85], v[158:161], v[182:185], v[82:85]
	v_mfma_f32_16x16x32_bf16 v[70:73], v[150:153], v[190:193], v[70:73]
	v_mfma_f32_16x16x32_bf16 v[66:69], v[158:161], v[190:193], v[66:69]
	s_barrier
	s_setprio 0
	s_add_i32 s14, s34, s90
	v_lshl_add_u64 v[194:195], v[232:233], 0, s[64:65]
	s_mov_b32 m0, s14
	ds_read_b128 v[162:165], v247 offset:49152
	ds_read_b128 v[166:169], v247 offset:50176
	ds_read_b128 v[170:173], v247 offset:51200
	ds_read_b128 v[174:177], v247 offset:52224
	ds_read_b128 v[178:181], v247 offset:53248
	ds_read_b128 v[182:185], v247 offset:54272
	ds_read_b128 v[186:189], v247 offset:55296
	ds_read_b128 v[190:193], v247 offset:56320
	global_load_lds_dwordx4 v[194:195], off
	s_add_i32 m0, s14, 0x2000
	s_add_u32 s12, s12, 0x40080
	v_lshl_add_u64 v[194:195], v[230:231], 0, s[64:65]
	s_addc_u32 s13, s13, 0
	s_add_i32 s14, s35, s90
	global_load_lds_dwordx4 v[194:195], off
	v_lshl_add_u64 v[194:195], s[12:13], 0, v[212:213]
	s_mov_b32 m0, s14
	s_nop 0
	global_load_lds_dwordx4 v[194:195], off
	v_lshl_add_u64 v[194:195], s[12:13], 0, v[216:217]
	s_add_i32 m0, s14, 0x2000
	s_nop 0
	global_load_lds_dwordx4 v[194:195], off
	v_lshl_add_u64 v[194:195], v[226:227], 0, s[64:65]
	s_mov_b32 m0, s63
	s_nop 0
	global_load_lds_dwordx4 v[194:195], off
	v_lshl_add_u64 v[194:195], v[228:229], 0, s[64:65]
	s_mov_b32 m0, s68
	s_nop 0
	global_load_lds_dwordx4 v[194:195], off
	s_waitcnt vmcnt(8)
	s_waitcnt lgkmcnt(0)
	s_setprio 1
	s_barrier
	v_mfma_f32_16x16x32_bf16 v[62:65], v[130:133], v[162:165], v[62:65]
	v_mfma_f32_16x16x32_bf16 v[58:61], v[138:141], v[162:165], v[58:61]
	v_mfma_f32_16x16x32_bf16 v[46:49], v[130:133], v[170:173], v[46:49]
	v_mfma_f32_16x16x32_bf16 v[42:45], v[138:141], v[170:173], v[42:45]
	v_mfma_f32_16x16x32_bf16 v[30:33], v[130:133], v[178:181], v[30:33]
	v_mfma_f32_16x16x32_bf16 v[26:29], v[138:141], v[178:181], v[26:29]
	v_mfma_f32_16x16x32_bf16 v[14:17], v[130:133], v[186:189], v[14:17]
	v_mfma_f32_16x16x32_bf16 v[10:13], v[138:141], v[186:189], v[10:13]
	v_mfma_f32_16x16x32_bf16 v[62:65], v[134:137], v[166:169], v[62:65]
	v_mfma_f32_16x16x32_bf16 v[58:61], v[142:145], v[166:169], v[58:61]
	v_mfma_f32_16x16x32_bf16 v[46:49], v[134:137], v[174:177], v[46:49]
	v_mfma_f32_16x16x32_bf16 v[42:45], v[142:145], v[174:177], v[42:45]
	v_mfma_f32_16x16x32_bf16 v[30:33], v[134:137], v[182:185], v[30:33]
	v_mfma_f32_16x16x32_bf16 v[26:29], v[142:145], v[182:185], v[26:29]
	v_mfma_f32_16x16x32_bf16 v[14:17], v[134:137], v[190:193], v[14:17]
	v_mfma_f32_16x16x32_bf16 v[10:13], v[142:145], v[190:193], v[10:13]
	v_mfma_f32_16x16x32_bf16 v[54:57], v[146:149], v[162:165], v[54:57]
	v_mfma_f32_16x16x32_bf16 v[50:53], v[154:157], v[162:165], v[50:53]
	v_mfma_f32_16x16x32_bf16 v[38:41], v[146:149], v[170:173], v[38:41]
	v_mfma_f32_16x16x32_bf16 v[34:37], v[154:157], v[170:173], v[34:37]
	v_mfma_f32_16x16x32_bf16 v[22:25], v[146:149], v[178:181], v[22:25]
	v_mfma_f32_16x16x32_bf16 v[18:21], v[154:157], v[178:181], v[18:21]
	v_mfma_f32_16x16x32_bf16 v[6:9], v[146:149], v[186:189], v[6:9]
	v_mfma_f32_16x16x32_bf16 v[2:5], v[154:157], v[186:189], v[2:5]
	v_mfma_f32_16x16x32_bf16 v[54:57], v[150:153], v[166:169], v[54:57]
	v_mfma_f32_16x16x32_bf16 v[50:53], v[158:161], v[166:169], v[50:53]
	v_mfma_f32_16x16x32_bf16 v[38:41], v[150:153], v[174:177], v[38:41]
	v_mfma_f32_16x16x32_bf16 v[34:37], v[158:161], v[174:177], v[34:37]
	v_mfma_f32_16x16x32_bf16 v[22:25], v[150:153], v[182:185], v[22:25]
	v_mfma_f32_16x16x32_bf16 v[18:21], v[158:161], v[182:185], v[18:21]
	v_mfma_f32_16x16x32_bf16 v[6:9], v[150:153], v[190:193], v[6:9]
	v_mfma_f32_16x16x32_bf16 v[2:5], v[158:161], v[190:193], v[2:5]
	s_barrier
	s_setprio 0
	s_add_i32 s40, s40, 2
	s_add_u32 s10, s10, 0x100
	s_addc_u32 s11, s11, 0
	s_cmp_gt_u32 s40, 13
	s_cbranch_scc1 .LBB0_425

; #define PG8_STAGE(bufoff, gbase, voff) do { _Pragma("unroll") for (int _i = 0; _i < 2; ++_i) \
;         __builtin_amdgcn_global_load_lds((const unsigned*)((const char*)(gbase) + (voff)[_i]), (PG8_LAS unsigned*)(lds + (bufoff) + ldsw + _i * 8192), 16, 0, 0); } while (0)
; #define PG8_LDA(dst, b, h) do { _Pragma("unroll") for (int m = 0; m < 4; ++m) _Pragma("unroll") for (int k = 0; k < 2; ++k) dst[m][k] = *(const PG8_LAS bf16x8*)(lds + PG8_SA(b, h) + aoff + m * 2048 + k * 1024); } while (0)
; #define PG8_LDB(dst, b, h) do { _Pragma("unroll") for (int n = 0; n < 2; ++n) _Pragma("unroll") for (int k = 0; k < 2; ++k) dst[n][k] = *(const PG8_LAS bf16x8*)(lds + PG8_SB(b, h) + boff + n * 2048 + k * 1024); } while (0)
; #define PG8_WAIT_V(n) asm volatile("s_waitcnt vmcnt(" #n ")" ::: "memory")
; #define PG8_WAIT_VN(n) asm volatile("s_waitcnt vmcnt(%0)" :: "n"(n) : "memory")
; #define PG8_WAIT_L(n) asm volatile("s_waitcnt lgkmcnt(" #n ")" ::: "memory")
; template <class Epi, class Sched, bool ALIGN_EPI = false, bool SP2 = false>
; __device__ __forceinline__ void gemm_phase(PG8_LAS unsigned char* lds, const Gemm g, const Sched& S, const Epi& E, const int wave_id) {
;     ...
;         for (int t = 0; t < nt; t += 2) {
;             const bool last = (t == nt - 2);
;             const char* a1 = cA + (size_t)(t + 1) * kstep;
;             const char* a2 = last ? nA : cA + (size_t)(t + 2) * kstep; const char* b2 = last ? nB : cB + (size_t)(t + 2) * kstep;
;             const char* a3 = a2 + kstep; const char* b3 = b2 + kstep;
;             if (last && has_next) S.a_ready(nxt);
;             if constexpr (SP2) {
;             int tz_ = __builtin_amdgcn_readfirstlane(t | (ui > 0 ? 0 : 1)); asm volatile("" : "+s"(tz_));
;             const bool strict = !(Epi::NS > 0 && tz_ == 0);
;             PG8_LDB(B0, 0, 0); PG8_LDB(B1, 0, 1); PG8_SCHED; PG8_LDA(At, 0, 0); PG8_STAGE(PG8_SA(1, 1), a1 + hstep, voffA);
;             PG8_WAIT_VN(8 + Epi::NS); if (strict) PG8_WAIT_V(8); PG8_WAIT_L(0); PG8_BAR; PG8_MMA(0, 0, At, B0); PG8_MMA(0, 1, At, B1); PG8_BAR; PG8_SCHED;
;             PG8_LDA(At, 0, 1); PG8_STAGE(PG8_SB(0, 0), b2, voffB); PG8_STAGE(PG8_SB(0, 1), b2 + hstep, voffB); PG8_STAGE(PG8_SA(0, 0), a2, voffA);
;             PG8_WAIT_VN(8 + Epi::NS); if (strict) PG8_WAIT_V(8); PG8_WAIT_L(0); PG8_BAR; PG8_MMA(1, 0, At, B0); PG8_MMA(1, 1, At, B1); PG8_BAR; PG8_SCHED;
.LBB0_423:
	s_add_u32 s12, s8, s10
	s_addc_u32 s13, s9, s11
	s_add_u32 s12, s12, 0x100
	s_addc_u32 s13, s13, 0
	s_add_u32 s41, s36, s10
	s_addc_u32 s42, s37, s11
	s_cmpk_eq_i32 s10, 0x700
	s_cselect_b32 s15, s23, s13
	s_cselect_b32 s14, s29, s12
	s_cselect_b32 s13, s21, s42
	s_cselect_b32 s12, s31, s41
	s_waitcnt lgkmcnt(0)
	s_setprio 1
	s_barrier
	v_mfma_f32_16x16x32_bf16 v[126:129], v[146:149], v[186:189], v[126:129]
	v_mfma_f32_16x16x32_bf16 v[122:125], v[154:157], v[186:189], v[122:125]
	v_mfma_f32_16x16x32_bf16 v[110:113], v[146:149], v[178:181], v[110:113]
	v_mfma_f32_16x16x32_bf16 v[106:109], v[154:157], v[178:181], v[106:109]
	v_mfma_f32_16x16x32_bf16 v[94:97], v[146:149], v[170:173], v[94:97]
	v_mfma_f32_16x16x32_bf16 v[90:93], v[154:157], v[170:173], v[90:93]
	v_mfma_f32_16x16x32_bf16 v[78:81], v[146:149], v[162:165], v[78:81]
	v_mfma_f32_16x16x32_bf16 v[74:77], v[154:157], v[162:165], v[74:77]
	v_mfma_f32_16x16x32_bf16 v[126:129], v[150:153], v[190:193], v[126:129]
	v_mfma_f32_16x16x32_bf16 v[122:125], v[158:161], v[190:193], v[122:125]
	v_mfma_f32_16x16x32_bf16 v[110:113], v[150:153], v[182:185], v[110:113]
	v_mfma_f32_16x16x32_bf16 v[106:109], v[158:161], v[182:185], v[106:109]
	v_mfma_f32_16x16x32_bf16 v[94:97], v[150:153], v[174:177], v[94:97]
	v_mfma_f32_16x16x32_bf16 v[90:93], v[158:161], v[174:177], v[90:93]
	v_mfma_f32_16x16x32_bf16 v[78:81], v[150:153], v[166:169], v[78:81]
	v_mfma_f32_16x16x32_bf16 v[74:77], v[158:161], v[166:169], v[74:77]
	v_mfma_f32_16x16x32_bf16 v[118:121], v[130:133], v[186:189], v[118:121]
	v_mfma_f32_16x16x32_bf16 v[114:117], v[138:141], v[186:189], v[114:117]
	v_mfma_f32_16x16x32_bf16 v[102:105], v[130:133], v[178:181], v[102:105]
	v_mfma_f32_16x16x32_bf16 v[98:101], v[138:141], v[178:181], v[98:101]
	v_mfma_f32_16x16x32_bf16 v[86:89], v[130:133], v[170:173], v[86:89]
	v_mfma_f32_16x16x32_bf16 v[82:85], v[138:141], v[170:173], v[82:85]
	v_mfma_f32_16x16x32_bf16 v[70:73], v[130:133], v[162:165], v[70:73]
	v_mfma_f32_16x16x32_bf16 v[66:69], v[138:141], v[162:165], v[66:69]
	v_mfma_f32_16x16x32_bf16 v[118:121], v[134:137], v[190:193], v[118:121]
	v_mfma_f32_16x16x32_bf16 v[114:117], v[142:145], v[190:193], v[114:117]
	v_mfma_f32_16x16x32_bf16 v[102:105], v[134:137], v[182:185], v[102:105]
	v_mfma_f32_16x16x32_bf16 v[98:101], v[142:145], v[182:185], v[98:101]
	v_mfma_f32_16x16x32_bf16 v[86:89], v[134:137], v[174:177], v[86:89]
	v_mfma_f32_16x16x32_bf16 v[82:85], v[142:145], v[174:177], v[82:85]
	v_mfma_f32_16x16x32_bf16 v[70:73], v[134:137], v[166:169], v[70:73]
	v_mfma_f32_16x16x32_bf16 v[66:69], v[142:145], v[166:169], v[66:69]
	s_barrier
	s_setprio 0
	s_mov_b32 m0, s94
	v_lshl_add_u64 v[232:233], s[12:13], 0, v[212:213]
	s_add_u32 s42, s12, 0x40000
	ds_read_b128 v[186:189], v247 offset:16384
	ds_read_b128 v[190:193], v247 offset:17408
	ds_read_b128 v[178:181], v247 offset:18432
	ds_read_b128 v[182:185], v247 offset:19456
	ds_read_b128 v[170:173], v247 offset:20480
	ds_read_b128 v[174:177], v247 offset:21504
	ds_read_b128 v[162:165], v247 offset:22528
	ds_read_b128 v[166:169], v247 offset:23552
	global_load_lds_dwordx4 v[232:233], off
	v_lshl_add_u64 v[230:231], s[12:13], 0, v[216:217]
	s_mov_b32 m0, s95
	s_addc_u32 s43, s13, 0
	global_load_lds_dwordx4 v[230:231], off
	v_lshl_add_u64 v[194:195], s[42:43], 0, v[212:213]
	s_mov_b32 m0, s38
	v_lshl_add_u64 v[226:227], s[14:15], 0, v[210:211]
	global_load_lds_dwordx4 v[194:195], off
	v_lshl_add_u64 v[194:195], s[42:43], 0, v[216:217]
	s_mov_b32 m0, s39
	v_lshl_add_u64 v[228:229], s[14:15], 0, v[214:215]
	global_load_lds_dwordx4 v[194:195], off
	s_mov_b32 m0, s91
	s_andn2_b64 vcc, exec, s[34:35]
	global_load_lds_dwordx4 v[226:227], off
	s_mov_b32 m0, s2
	s_nop 0
	global_load_lds_dwordx4 v[228:229], off
	s_waitcnt vmcnt(24)
	s_cbranch_vccnz .LBB0_420
	s_waitcnt vmcnt(8)
	s_branch .LBB0_420

; #define PG8_STAGE(bufoff, gbase, voff) do { _Pragma("unroll") for (int _i = 0; _i < 2; ++_i) \
;         __builtin_amdgcn_global_load_lds((const unsigned*)((const char*)(gbase) + (voff)[_i]), (PG8_LAS unsigned*)(lds + (bufoff) + ldsw + _i * 8192), 16, 0, 0); } while (0)
; #define PG8_LDA(dst, b, h) do { _Pragma("unroll") for (int m = 0; m < 4; ++m) _Pragma("unroll") for (int k = 0; k < 2; ++k) dst[m][k] = *(const PG8_LAS bf16x8*)(lds + PG8_SA(b, h) + aoff + m * 2048 + k * 1024); } while (0)
; #define PG8_LDB(dst, b, h) do { _Pragma("unroll") for (int n = 0; n < 2; ++n) _Pragma("unroll") for (int k = 0; k < 2; ++k) dst[n][k] = *(const PG8_LAS bf16x8*)(lds + PG8_SB(b, h) + boff + n * 2048 + k * 1024); } while (0)
; #define PG8_MMA(ai, bj, At, Bt) do { __builtin_amdgcn_s_setprio(1); _Pragma("unroll") for (int m = 0; m < 4; ++m) _Pragma("unroll") for (int n = 0; n < 2; ++n) _Pragma("unroll") for (int k = 0; k < 2; ++k) \
;         acc[ai][bj][m][n] = __builtin_amdgcn_mfma_f32_16x16x32_bf16(Bt[n][k], At[m][k], acc[ai][bj][m][n], 0, 0, 0); __builtin_amdgcn_s_setprio(0); } while (0)
; #define PG8_WAIT_V(n) asm volatile("s_waitcnt vmcnt(" #n ")" ::: "memory")
; #define PG8_WAIT_VN(n) asm volatile("s_waitcnt vmcnt(%0)" :: "n"(n) : "memory")
; #define PG8_WAIT_L(n) asm volatile("s_waitcnt lgkmcnt(" #n ")" ::: "memory")
; #define PG8_BAR __builtin_amdgcn_s_barrier()
; #define PG8_SCHED __builtin_amdgcn_sched_barrier(0)
; template <class Epi, class Sched, bool ALIGN_EPI = false, bool SP2 = false>
; __device__ __forceinline__ void gemm_phase(PG8_LAS unsigned char* lds, const Gemm g, const Sched& S, const Epi& E, const int wave_id) {
;     ...
;             PG8_WAIT_VN(8 + Epi::NS); if (strict) PG8_WAIT_V(8); PG8_WAIT_L(0); PG8_BAR; PG8_MMA(1, 0, At, B0); PG8_MMA(1, 1, At, B1); PG8_BAR; PG8_SCHED;
;             PG8_LDB(B0, 1, 0); PG8_LDB(B1, 1, 1); PG8_SCHED; PG8_LDA(At, 1, 0); PG8_STAGE(PG8_SA(0, 1), a2 + hstep, voffA);
;             PG8_WAIT_V(8); PG8_WAIT_L(0); PG8_BAR; PG8_MMA(0, 0, At, B0); PG8_MMA(0, 1, At, B1); PG8_BAR; PG8_SCHED;
.LBB0_1504:
	s_waitcnt lgkmcnt(0)
	s_setprio 1
	s_barrier
	v_mfma_f32_16x16x32_bf16 v[62:65], v[146:149], v[186:189], v[62:65]
	v_mfma_f32_16x16x32_bf16 v[58:61], v[154:157], v[186:189], v[58:61]
	v_mfma_f32_16x16x32_bf16 v[46:49], v[146:149], v[178:181], v[46:49]
	v_mfma_f32_16x16x32_bf16 v[42:45], v[154:157], v[178:181], v[42:45]
	v_mfma_f32_16x16x32_bf16 v[30:33], v[146:149], v[170:173], v[30:33]
	v_mfma_f32_16x16x32_bf16 v[26:29], v[154:157], v[170:173], v[26:29]
	v_mfma_f32_16x16x32_bf16 v[14:17], v[146:149], v[162:165], v[14:17]
	v_mfma_f32_16x16x32_bf16 v[10:13], v[154:157], v[162:165], v[10:13]
	v_mfma_f32_16x16x32_bf16 v[62:65], v[150:153], v[190:193], v[62:65]
	v_mfma_f32_16x16x32_bf16 v[58:61], v[158:161], v[190:193], v[58:61]
	v_mfma_f32_16x16x32_bf16 v[46:49], v[150:153], v[182:185], v[46:49]
	v_mfma_f32_16x16x32_bf16 v[42:45], v[158:161], v[182:185], v[42:45]
	v_mfma_f32_16x16x32_bf16 v[30:33], v[150:153], v[174:177], v[30:33]
	v_mfma_f32_16x16x32_bf16 v[26:29], v[158:161], v[174:177], v[26:29]
	v_mfma_f32_16x16x32_bf16 v[14:17], v[150:153], v[166:169], v[14:17]
	v_mfma_f32_16x16x32_bf16 v[10:13], v[158:161], v[166:169], v[10:13]
	v_mfma_f32_16x16x32_bf16 v[54:57], v[130:133], v[186:189], v[54:57]
	v_mfma_f32_16x16x32_bf16 v[50:53], v[138:141], v[186:189], v[50:53]
	v_mfma_f32_16x16x32_bf16 v[38:41], v[130:133], v[178:181], v[38:41]
	v_mfma_f32_16x16x32_bf16 v[34:37], v[138:141], v[178:181], v[34:37]
	v_mfma_f32_16x16x32_bf16 v[22:25], v[130:133], v[170:173], v[22:25]
	v_mfma_f32_16x16x32_bf16 v[18:21], v[138:141], v[170:173], v[18:21]
	v_mfma_f32_16x16x32_bf16 v[6:9], v[130:133], v[162:165], v[6:9]
	v_mfma_f32_16x16x32_bf16 v[2:5], v[138:141], v[162:165], v[2:5]
	v_mfma_f32_16x16x32_bf16 v[54:57], v[134:137], v[190:193], v[54:57]
	v_mfma_f32_16x16x32_bf16 v[50:53], v[142:145], v[190:193], v[50:53]
	v_mfma_f32_16x16x32_bf16 v[38:41], v[134:137], v[182:185], v[38:41]
	v_mfma_f32_16x16x32_bf16 v[34:37], v[142:145], v[182:185], v[34:37]
	v_mfma_f32_16x16x32_bf16 v[22:25], v[134:137], v[174:177], v[22:25]
	v_mfma_f32_16x16x32_bf16 v[18:21], v[142:145], v[174:177], v[18:21]
	v_mfma_f32_16x16x32_bf16 v[6:9], v[134:137], v[166:169], v[6:9]
	v_mfma_f32_16x16x32_bf16 v[2:5], v[142:145], v[166:169], v[2:5]
	s_barrier
	s_setprio 0
	s_add_i32 s20, 0, 0x18000
	s_add_i32 s21, 0, 0x1c000
	v_add_u32_e32 v142, s20, v1
	v_add_u32_e32 v158, s21, v1
	ds_read_b128 v[130:133], v142
	ds_read_b128 v[134:137], v142 offset:1024
	ds_read_b128 v[138:141], v142 offset:2048
	ds_read_b128 v[142:145], v142 offset:3072
	ds_read_b128 v[146:149], v158
	ds_read_b128 v[150:153], v158 offset:1024
	ds_read_b128 v[154:157], v158 offset:2048
	ds_read_b128 v[158:161], v158 offset:3072
	s_add_u32 s18, s18, 0x40000
	s_addc_u32 s19, s19, 0
	s_mov_b32 m0, s35
	v_lshl_add_u64 v[194:195], s[18:19], 0, v[216:217]
	ds_read_b128 v[162:165], v232 offset:32768
	ds_read_b128 v[166:169], v232 offset:33792
	ds_read_b128 v[170:173], v232 offset:34816
	ds_read_b128 v[174:177], v232 offset:35840
	ds_read_b128 v[178:181], v232 offset:36864
	ds_read_b128 v[182:185], v232 offset:37888
	ds_read_b128 v[186:189], v232 offset:38912
	ds_read_b128 v[190:193], v232 offset:39936
	global_load_lds_dwordx4 v[194:195], off
	v_lshl_add_u64 v[194:195], s[18:19], 0, v[212:213]
	s_mov_b32 m0, s36
	s_nop 0
	global_load_lds_dwordx4 v[194:195], off
	s_waitcnt vmcnt(8)
	s_waitcnt lgkmcnt(0)
	s_setprio 1
	s_barrier
	v_mfma_f32_16x16x32_bf16 v[126:129], v[130:133], v[162:165], v[126:129]
	v_mfma_f32_16x16x32_bf16 v[122:125], v[138:141], v[162:165], v[122:125]
	v_mfma_f32_16x16x32_bf16 v[110:113], v[130:133], v[170:173], v[110:113]
	v_mfma_f32_16x16x32_bf16 v[106:109], v[138:141], v[170:173], v[106:109]
	v_mfma_f32_16x16x32_bf16 v[94:97], v[130:133], v[178:181], v[94:97]
	v_mfma_f32_16x16x32_bf16 v[90:93], v[138:141], v[178:181], v[90:93]
	v_mfma_f32_16x16x32_bf16 v[78:81], v[130:133], v[186:189], v[78:81]
	v_mfma_f32_16x16x32_bf16 v[74:77], v[138:141], v[186:189], v[74:77]
	v_mfma_f32_16x16x32_bf16 v[126:129], v[134:137], v[166:169], v[126:129]
	v_mfma_f32_16x16x32_bf16 v[122:125], v[142:145], v[166:169], v[122:125]
	v_mfma_f32_16x16x32_bf16 v[110:113], v[134:137], v[174:177], v[110:113]
	v_mfma_f32_16x16x32_bf16 v[106:109], v[142:145], v[174:177], v[106:109]
	v_mfma_f32_16x16x32_bf16 v[94:97], v[134:137], v[182:185], v[94:97]
	v_mfma_f32_16x16x32_bf16 v[90:93], v[142:145], v[182:185], v[90:93]
	v_mfma_f32_16x16x32_bf16 v[78:81], v[134:137], v[190:193], v[78:81]
	v_mfma_f32_16x16x32_bf16 v[74:77], v[142:145], v[190:193], v[74:77]
	v_mfma_f32_16x16x32_bf16 v[118:121], v[146:149], v[162:165], v[118:121]
	v_mfma_f32_16x16x32_bf16 v[114:117], v[154:157], v[162:165], v[114:117]
	v_mfma_f32_16x16x32_bf16 v[102:105], v[146:149], v[170:173], v[102:105]
	v_mfma_f32_16x16x32_bf16 v[98:101], v[154:157], v[170:173], v[98:101]
	v_mfma_f32_16x16x32_bf16 v[86:89], v[146:149], v[178:181], v[86:89]
	v_mfma_f32_16x16x32_bf16 v[82:85], v[154:157], v[178:181], v[82:85]
	v_mfma_f32_16x16x32_bf16 v[70:73], v[146:149], v[186:189], v[70:73]
	v_mfma_f32_16x16x32_bf16 v[66:69], v[154:157], v[186:189], v[66:69]
	v_mfma_f32_16x16x32_bf16 v[118:121], v[150:153], v[166:169], v[118:121]
	v_mfma_f32_16x16x32_bf16 v[114:117], v[158:161], v[166:169], v[114:117]
	v_mfma_f32_16x16x32_bf16 v[102:105], v[150:153], v[174:177], v[102:105]
	v_mfma_f32_16x16x32_bf16 v[98:101], v[158:161], v[174:177], v[98:101]
	v_mfma_f32_16x16x32_bf16 v[86:89], v[150:153], v[182:185], v[86:89]
	v_mfma_f32_16x16x32_bf16 v[82:85], v[158:161], v[182:185], v[82:85]
	v_mfma_f32_16x16x32_bf16 v[70:73], v[150:153], v[190:193], v[70:73]
	v_mfma_f32_16x16x32_bf16 v[66:69], v[158:161], v[190:193], v[66:69]
	s_barrier
; #define PG8_STAGE(bufoff, gbase, voff) do { _Pragma("unroll") for (int _i = 0; _i < 2; ++_i) \
;         __builtin_amdgcn_global_load_lds((const unsigned*)((const char*)(gbase) + (voff)[_i]), (PG8_LAS unsigned*)(lds + (bufoff) + ldsw + _i * 8192), 16, 0, 0); } while (0)
; #define PG8_LDA(dst, b, h) do { _Pragma("unroll") for (int m = 0; m < 4; ++m) _Pragma("unroll") for (int k = 0; k < 2; ++k) dst[m][k] = *(const PG8_LAS bf16x8*)(lds + PG8_SA(b, h) + aoff + m * 2048 + k * 1024); } while (0)
; #define PG8_MMA(ai, bj, At, Bt) do { __builtin_amdgcn_s_setprio(1); _Pragma("unroll") for (int m = 0; m < 4; ++m) _Pragma("unroll") for (int n = 0; n < 2; ++n) _Pragma("unroll") for (int k = 0; k < 2; ++k) \
;         acc[ai][bj][m][n] = __builtin_amdgcn_mfma_f32_16x16x32_bf16(Bt[n][k], At[m][k], acc[ai][bj][m][n], 0, 0, 0); __builtin_amdgcn_s_setprio(0); } while (0)
; #define PG8_WAIT_V(n) asm volatile("s_waitcnt vmcnt(" #n ")" ::: "memory")
; #define PG8_WAIT_L(n) asm volatile("s_waitcnt lgkmcnt(" #n ")" ::: "memory")
; #define PG8_BAR __builtin_amdgcn_s_barrier()
; #define PG8_SCHED __builtin_amdgcn_sched_barrier(0)
; template <class Epi, class Sched, bool ALIGN_EPI = false, bool SP2 = false>
; __device__ __forceinline__ void gemm_phase(PG8_LAS unsigned char* lds, const Gemm g, const Sched& S, const Epi& E, const int wave_id) {
;     ...
;             PG8_WAIT_V(8); PG8_WAIT_L(0); PG8_BAR; PG8_MMA(0, 0, At, B0); PG8_MMA(0, 1, At, B1); PG8_BAR; PG8_SCHED;
;             PG8_LDA(At, 1, 1); PG8_STAGE(PG8_SB(1, 0), b3, voffB); PG8_STAGE(PG8_SB(1, 1), b3 + hstep, voffB); PG8_STAGE(PG8_SA(1, 0), a3, voffA);
;             PG8_WAIT_V(8); PG8_WAIT_L(0); PG8_BAR; PG8_MMA(1, 0, At, B0); PG8_MMA(1, 1, At, B1); PG8_BAR; PG8_SCHED;
	s_setprio 0
	s_add_i32 s18, s20, s24
	v_lshl_add_u64 v[194:195], v[228:229], 0, s[64:65]
	s_mov_b32 m0, s18
	ds_read_b128 v[162:165], v232 offset:49152
	ds_read_b128 v[166:169], v232 offset:50176
	ds_read_b128 v[170:173], v232 offset:51200
	ds_read_b128 v[174:177], v232 offset:52224
	ds_read_b128 v[178:181], v232 offset:53248
	ds_read_b128 v[182:185], v232 offset:54272
	ds_read_b128 v[186:189], v232 offset:55296
	ds_read_b128 v[190:193], v232 offset:56320
	global_load_lds_dwordx4 v[194:195], off
	s_add_i32 m0, s18, 0x2000
	s_add_u32 s16, s16, 0x40080
	v_lshl_add_u64 v[194:195], v[226:227], 0, s[64:65]
	s_addc_u32 s17, s17, 0
	s_add_i32 s18, s21, s24
	global_load_lds_dwordx4 v[194:195], off
	v_lshl_add_u64 v[194:195], s[16:17], 0, v[214:215]
	s_mov_b32 m0, s18
	s_nop 0
	global_load_lds_dwordx4 v[194:195], off
	v_lshl_add_u64 v[194:195], s[16:17], 0, v[210:211]
	s_add_i32 m0, s18, 0x2000
	s_nop 0
	global_load_lds_dwordx4 v[194:195], off
	v_lshl_add_u64 v[194:195], v[222:223], 0, s[64:65]
	s_mov_b32 m0, s37
	s_nop 0
	global_load_lds_dwordx4 v[194:195], off
	v_lshl_add_u64 v[194:195], v[224:225], 0, s[64:65]
	s_mov_b32 m0, s38
	s_nop 0
	global_load_lds_dwordx4 v[194:195], off
	s_waitcnt vmcnt(8)
	s_waitcnt lgkmcnt(0)
	s_setprio 1
	s_barrier
	v_mfma_f32_16x16x32_bf16 v[62:65], v[130:133], v[162:165], v[62:65]
	v_mfma_f32_16x16x32_bf16 v[58:61], v[138:141], v[162:165], v[58:61]
	v_mfma_f32_16x16x32_bf16 v[46:49], v[130:133], v[170:173], v[46:49]
	v_mfma_f32_16x16x32_bf16 v[42:45], v[138:141], v[170:173], v[42:45]
	v_mfma_f32_16x16x32_bf16 v[30:33], v[130:133], v[178:181], v[30:33]
	v_mfma_f32_16x16x32_bf16 v[26:29], v[138:141], v[178:181], v[26:29]
	v_mfma_f32_16x16x32_bf16 v[14:17], v[130:133], v[186:189], v[14:17]
	v_mfma_f32_16x16x32_bf16 v[10:13], v[138:141], v[186:189], v[10:13]
	v_mfma_f32_16x16x32_bf16 v[62:65], v[134:137], v[166:169], v[62:65]
	v_mfma_f32_16x16x32_bf16 v[58:61], v[142:145], v[166:169], v[58:61]
	v_mfma_f32_16x16x32_bf16 v[46:49], v[134:137], v[174:177], v[46:49]
	v_mfma_f32_16x16x32_bf16 v[42:45], v[142:145], v[174:177], v[42:45]
	v_mfma_f32_16x16x32_bf16 v[30:33], v[134:137], v[182:185], v[30:33]
	v_mfma_f32_16x16x32_bf16 v[26:29], v[142:145], v[182:185], v[26:29]
	v_mfma_f32_16x16x32_bf16 v[14:17], v[134:137], v[190:193], v[14:17]
	v_mfma_f32_16x16x32_bf16 v[10:13], v[142:145], v[190:193], v[10:13]
	v_mfma_f32_16x16x32_bf16 v[54:57], v[146:149], v[162:165], v[54:57]
	v_mfma_f32_16x16x32_bf16 v[50:53], v[154:157], v[162:165], v[50:53]
	v_mfma_f32_16x16x32_bf16 v[38:41], v[146:149], v[170:173], v[38:41]
	v_mfma_f32_16x16x32_bf16 v[34:37], v[154:157], v[170:173], v[34:37]
	v_mfma_f32_16x16x32_bf16 v[22:25], v[146:149], v[178:181], v[22:25]
	v_mfma_f32_16x16x32_bf16 v[18:21], v[154:157], v[178:181], v[18:21]
	v_mfma_f32_16x16x32_bf16 v[6:9], v[146:149], v[186:189], v[6:9]
	v_mfma_f32_16x16x32_bf16 v[2:5], v[154:157], v[186:189], v[2:5]
	v_mfma_f32_16x16x32_bf16 v[54:57], v[150:153], v[166:169], v[54:57]
	v_mfma_f32_16x16x32_bf16 v[50:53], v[158:161], v[166:169], v[50:53]
	v_mfma_f32_16x16x32_bf16 v[38:41], v[150:153], v[174:177], v[38:41]
	v_mfma_f32_16x16x32_bf16 v[34:37], v[158:161], v[174:177], v[34:37]
	v_mfma_f32_16x16x32_bf16 v[22:25], v[150:153], v[182:185], v[22:25]
	v_mfma_f32_16x16x32_bf16 v[18:21], v[158:161], v[182:185], v[18:21]
	v_mfma_f32_16x16x32_bf16 v[6:9], v[150:153], v[190:193], v[6:9]
	v_mfma_f32_16x16x32_bf16 v[2:5], v[158:161], v[190:193], v[2:5]
	s_barrier
	s_setprio 0
	s_add_u32 s12, s12, 0x100
	s_addc_u32 s13, s13, 0
	s_cmp_gt_u32 s43, 13
	s_cbranch_scc1 .LBB0_1526

; #define PG8_STAGE(bufoff, gbase, voff) do { _Pragma("unroll") for (int _i = 0; _i < 2; ++_i) \
;         __builtin_amdgcn_global_load_lds((const unsigned*)((const char*)(gbase) + (voff)[_i]), (PG8_LAS unsigned*)(lds + (bufoff) + ldsw + _i * 8192), 16, 0, 0); } while (0)
; #define PG8_LDA(dst, b, h) do { _Pragma("unroll") for (int m = 0; m < 4; ++m) _Pragma("unroll") for (int k = 0; k < 2; ++k) dst[m][k] = *(const PG8_LAS bf16x8*)(lds + PG8_SA(b, h) + aoff + m * 2048 + k * 1024); } while (0)
; #define PG8_LDB(dst, b, h) do { _Pragma("unroll") for (int n = 0; n < 2; ++n) _Pragma("unroll") for (int k = 0; k < 2; ++k) dst[n][k] = *(const PG8_LAS bf16x8*)(lds + PG8_SB(b, h) + boff + n * 2048 + k * 1024); } while (0)
; #define PG8_WAIT_V(n) asm volatile("s_waitcnt vmcnt(" #n ")" ::: "memory")
; #define PG8_WAIT_VN(n) asm volatile("s_waitcnt vmcnt(%0)" :: "n"(n) : "memory")
; #define PG8_WAIT_L(n) asm volatile("s_waitcnt lgkmcnt(" #n ")" ::: "memory")
; template <class Epi, class Sched, bool ALIGN_EPI = false, bool SP2 = false>
; __device__ __forceinline__ void gemm_phase(PG8_LAS unsigned char* lds, const Gemm g, const Sched& S, const Epi& E, const int wave_id) {
;     ...
;         for (int t = 0; t < nt; t += 2) {
;             const bool last = (t == nt - 2);
;             const char* a1 = cA + (size_t)(t + 1) * kstep;
;             const char* a2 = last ? nA : cA + (size_t)(t + 2) * kstep; const char* b2 = last ? nB : cB + (size_t)(t + 2) * kstep;
;             const char* a3 = a2 + kstep; const char* b3 = b2 + kstep;
;             if (last && has_next) S.a_ready(nxt);
;             if constexpr (SP2) {
;             int tz_ = __builtin_amdgcn_readfirstlane(t | (ui > 0 ? 0 : 1)); asm volatile("" : "+s"(tz_));
;             const bool strict = !(Epi::NS > 0 && tz_ == 0);
;             PG8_LDB(B0, 0, 0); PG8_LDB(B1, 0, 1); PG8_SCHED; PG8_LDA(At, 0, 0); PG8_STAGE(PG8_SA(1, 1), a1 + hstep, voffA);
;             PG8_WAIT_VN(8 + Epi::NS); if (strict) PG8_WAIT_V(8); PG8_WAIT_L(0); PG8_BAR; PG8_MMA(0, 0, At, B0); PG8_MMA(0, 1, At, B1); PG8_BAR; PG8_SCHED;
;             PG8_LDA(At, 0, 1); PG8_STAGE(PG8_SB(0, 0), b2, voffB); PG8_STAGE(PG8_SB(0, 1), b2 + hstep, voffB); PG8_STAGE(PG8_SA(0, 0), a2, voffA);
;             PG8_WAIT_VN(8 + Epi::NS); if (strict) PG8_WAIT_V(8); PG8_WAIT_L(0); PG8_BAR; PG8_MMA(1, 0, At, B0); PG8_MMA(1, 1, At, B1); PG8_BAR; PG8_SCHED;
.LBB0_1507:
	s_add_u32 s16, s41, s12
	s_addc_u32 s17, s42, s13
	s_add_u32 s16, s16, 0x8f2c0100
	s_addc_u32 s17, s17, 0
	s_add_u32 s49, s39, s12
	s_addc_u32 s50, s40, s13
	s_cmpk_eq_i32 s12, 0x700
	s_cselect_b32 s19, s11, s17
	s_cselect_b32 s18, s10, s16
	s_cselect_b32 s17, s9, s50
	s_cselect_b32 s16, s8, s49
	s_waitcnt lgkmcnt(0)
	s_setprio 1
	s_barrier
	v_mfma_f32_16x16x32_bf16 v[126:129], v[146:149], v[186:189], v[126:129]
	v_mfma_f32_16x16x32_bf16 v[122:125], v[154:157], v[186:189], v[122:125]
	v_mfma_f32_16x16x32_bf16 v[110:113], v[146:149], v[178:181], v[110:113]
	v_mfma_f32_16x16x32_bf16 v[106:109], v[154:157], v[178:181], v[106:109]
	v_mfma_f32_16x16x32_bf16 v[94:97], v[146:149], v[170:173], v[94:97]
	v_mfma_f32_16x16x32_bf16 v[90:93], v[154:157], v[170:173], v[90:93]
	v_mfma_f32_16x16x32_bf16 v[78:81], v[146:149], v[162:165], v[78:81]
	v_mfma_f32_16x16x32_bf16 v[74:77], v[154:157], v[162:165], v[74:77]
	v_mfma_f32_16x16x32_bf16 v[126:129], v[150:153], v[190:193], v[126:129]
	v_mfma_f32_16x16x32_bf16 v[122:125], v[158:161], v[190:193], v[122:125]
	v_mfma_f32_16x16x32_bf16 v[110:113], v[150:153], v[182:185], v[110:113]
	v_mfma_f32_16x16x32_bf16 v[106:109], v[158:161], v[182:185], v[106:109]
	v_mfma_f32_16x16x32_bf16 v[94:97], v[150:153], v[174:177], v[94:97]
	v_mfma_f32_16x16x32_bf16 v[90:93], v[158:161], v[174:177], v[90:93]
	v_mfma_f32_16x16x32_bf16 v[78:81], v[150:153], v[166:169], v[78:81]
	v_mfma_f32_16x16x32_bf16 v[74:77], v[158:161], v[166:169], v[74:77]
	v_mfma_f32_16x16x32_bf16 v[118:121], v[130:133], v[186:189], v[118:121]
	v_mfma_f32_16x16x32_bf16 v[114:117], v[138:141], v[186:189], v[114:117]
	v_mfma_f32_16x16x32_bf16 v[102:105], v[130:133], v[178:181], v[102:105]
	v_mfma_f32_16x16x32_bf16 v[98:101], v[138:141], v[178:181], v[98:101]
	v_mfma_f32_16x16x32_bf16 v[86:89], v[130:133], v[170:173], v[86:89]
	v_mfma_f32_16x16x32_bf16 v[82:85], v[138:141], v[170:173], v[82:85]
	v_mfma_f32_16x16x32_bf16 v[70:73], v[130:133], v[162:165], v[70:73]
	v_mfma_f32_16x16x32_bf16 v[66:69], v[138:141], v[162:165], v[66:69]
	v_mfma_f32_16x16x32_bf16 v[118:121], v[134:137], v[190:193], v[118:121]
	v_mfma_f32_16x16x32_bf16 v[114:117], v[142:145], v[190:193], v[114:117]
	v_mfma_f32_16x16x32_bf16 v[102:105], v[134:137], v[182:185], v[102:105]
	v_mfma_f32_16x16x32_bf16 v[98:101], v[142:145], v[182:185], v[98:101]
	v_mfma_f32_16x16x32_bf16 v[86:89], v[134:137], v[174:177], v[86:89]
	v_mfma_f32_16x16x32_bf16 v[82:85], v[142:145], v[174:177], v[82:85]
	v_mfma_f32_16x16x32_bf16 v[70:73], v[134:137], v[166:169], v[70:73]
	v_mfma_f32_16x16x32_bf16 v[66:69], v[142:145], v[166:169], v[66:69]
	s_barrier
	s_setprio 0
	s_mov_b32 m0, s26
	v_lshl_add_u64 v[228:229], s[16:17], 0, v[214:215]
	s_add_u32 s50, s16, 0x40000
	ds_read_b128 v[186:189], v232 offset:16384
	ds_read_b128 v[190:193], v232 offset:17408
	ds_read_b128 v[178:181], v232 offset:18432
	ds_read_b128 v[182:185], v232 offset:19456
	ds_read_b128 v[170:173], v232 offset:20480
	ds_read_b128 v[174:177], v232 offset:21504
	ds_read_b128 v[162:165], v232 offset:22528
	ds_read_b128 v[166:169], v232 offset:23552
	global_load_lds_dwordx4 v[228:229], off
	v_lshl_add_u64 v[226:227], s[16:17], 0, v[210:211]
	s_mov_b32 m0, s27
	s_addc_u32 s51, s17, 0
	global_load_lds_dwordx4 v[226:227], off
	v_lshl_add_u64 v[194:195], s[50:51], 0, v[214:215]
	s_mov_b32 m0, s29
	v_lshl_add_u64 v[222:223], s[18:19], 0, v[216:217]
	global_load_lds_dwordx4 v[194:195], off
	v_lshl_add_u64 v[194:195], s[50:51], 0, v[210:211]
	s_mov_b32 m0, s30
	v_lshl_add_u64 v[224:225], s[18:19], 0, v[212:213]
	global_load_lds_dwordx4 v[194:195], off
	s_mov_b32 m0, s25
	s_andn2_b64 vcc, exec, s[20:21]
	global_load_lds_dwordx4 v[222:223], off
	s_mov_b32 m0, s34
	s_nop 0
	global_load_lds_dwordx4 v[224:225], off
	s_waitcnt vmcnt(24)
	s_cbranch_vccnz .LBB0_1504
	s_waitcnt vmcnt(8)
	s_branch .LBB0_1504

; #define PG8_STAGE(bufoff, gbase, voff) do { _Pragma("unroll") for (int _i = 0; _i < 2; ++_i) \
;         __builtin_amdgcn_global_load_lds((const unsigned*)((const char*)(gbase) + (voff)[_i]), (PG8_LAS unsigned*)(lds + (bufoff) + ldsw + _i * 8192), 16, 0, 0); } while (0)
; #define PG8_LDA(dst, b, h) do { _Pragma("unroll") for (int m = 0; m < 4; ++m) _Pragma("unroll") for (int k = 0; k < 2; ++k) dst[m][k] = *(const PG8_LAS bf16x8*)(lds + PG8_SA(b, h) + aoff + m * 2048 + k * 1024); } while (0)
; #define PG8_LDB(dst, b, h) do { _Pragma("unroll") for (int n = 0; n < 2; ++n) _Pragma("unroll") for (int k = 0; k < 2; ++k) dst[n][k] = *(const PG8_LAS bf16x8*)(lds + PG8_SB(b, h) + boff + n * 2048 + k * 1024); } while (0)
; #define PG8_WAIT_V(n) asm volatile("s_waitcnt vmcnt(" #n ")" ::: "memory")
; #define PG8_WAIT_VN(n) asm volatile("s_waitcnt vmcnt(%0)" :: "n"(n) : "memory")
; #define PG8_WAIT_L(n) asm volatile("s_waitcnt lgkmcnt(" #n ")" ::: "memory")
; template <class Epi, class Sched, bool ALIGN_EPI = false, bool SP2 = false>
; __device__ __forceinline__ void gemm_phase(PG8_LAS unsigned char* lds, const Gemm g, const Sched& S, const Epi& E, const int wave_id) {
;     ...
;         for (int t = 0; t < nt; t += 2) {
;             const bool last = (t == nt - 2);
;             const char* a1 = cA + (size_t)(t + 1) * kstep;
;             const char* a2 = last ? nA : cA + (size_t)(t + 2) * kstep; const char* b2 = last ? nB : cB + (size_t)(t + 2) * kstep;
;             const char* a3 = a2 + kstep; const char* b3 = b2 + kstep;
;             if (last && has_next) S.a_ready(nxt);
;             if constexpr (SP2) {
;             int tz_ = __builtin_amdgcn_readfirstlane(t | (ui > 0 ? 0 : 1)); asm volatile("" : "+s"(tz_));
;             const bool strict = !(Epi::NS > 0 && tz_ == 0);
;             PG8_LDB(B0, 0, 0); PG8_LDB(B1, 0, 1); PG8_SCHED; PG8_LDA(At, 0, 0); PG8_STAGE(PG8_SA(1, 1), a1 + hstep, voffA);
;             PG8_WAIT_VN(8 + Epi::NS); if (strict) PG8_WAIT_V(8); PG8_WAIT_L(0); PG8_BAR; PG8_MMA(0, 0, At, B0); PG8_MMA(0, 1, At, B1); PG8_BAR; PG8_SCHED;
;             PG8_LDA(At, 0, 1); PG8_STAGE(PG8_SB(0, 0), b2, voffB); PG8_STAGE(PG8_SB(0, 1), b2 + hstep, voffB); PG8_STAGE(PG8_SA(0, 0), a2, voffA);
;             PG8_WAIT_VN(8 + Epi::NS); if (strict) PG8_WAIT_V(8); PG8_WAIT_L(0); PG8_BAR; PG8_MMA(1, 0, At, B0); PG8_MMA(1, 1, At, B1); PG8_BAR; PG8_SCHED;
.LBB0_1537:
	s_add_u32 s12, s8, s10
	s_addc_u32 s13, s9, s11
	s_add_u32 s12, s12, 0x100
	s_addc_u32 s13, s13, 0
	s_add_u32 s53, s67, s10
	s_addc_u32 s76, s68, s11
	s_add_i32 s69, s69, 2
	s_add_i32 s78, 0, 0x10000
	v_add_u32_e32 v147, s69, v146
	s_cmpk_eq_i32 s10, 0x700
	s_cselect_b32 s26, s57, s12
	v_readfirstlane_b32 s12, v147
	s_cselect_b32 s27, s56, s13
	v_add_u32_e32 v147, s78, v163
	s_cselect_b32 s13, s62, s76
	s_cselect_b32 s12, s63, s53
	s_add_i32 s53, 0, 0x14000
	ds_read_b128 v[148:151], v147
	ds_read_b128 v[152:155], v147 offset:1024
	ds_read_b128 v[156:159], v147 offset:2048
	ds_read_b128 v[166:169], v147 offset:3072
	v_add_u32_e32 v147, s53, v163
	ds_read_b128 v[170:173], v147
	ds_read_b128 v[174:177], v147 offset:1024
	ds_read_b128 v[178:181], v147 offset:2048
	ds_read_b128 v[182:185], v147 offset:3072
	v_lshl_add_u64 v[160:161], v[144:145], 0, s[10:11]
	s_add_i32 m0, s17, 0xc000
	ds_read_b128 v[186:189], v164
	ds_read_b128 v[190:193], v164 offset:1024
	ds_read_b128 v[194:197], v164 offset:2048
	ds_read_b128 v[198:201], v164 offset:3072
	ds_read_b128 v[202:205], v164 offset:4096
	ds_read_b128 v[206:209], v164 offset:5120
	ds_read_b128 v[210:213], v164 offset:6144
	ds_read_b128 v[214:217], v164 offset:7168
	global_load_lds_dwordx4 v[160:161], off
	v_lshl_add_u64 v[160:161], v[142:143], 0, s[10:11]
	s_add_i32 m0, s17, 0xe000
	s_nop 0
	global_load_lds_dwordx4 v[160:161], off
	s_waitcnt vmcnt(8)
	s_waitcnt vmcnt(8)
	s_waitcnt lgkmcnt(0)
	s_setprio 1
	s_barrier
	v_mfma_f32_16x16x32_bf16 v[126:129], v[148:151], v[186:189], v[126:129]
	v_mfma_f32_16x16x32_bf16 v[122:125], v[156:159], v[186:189], v[122:125]
	v_mfma_f32_16x16x32_bf16 v[118:121], v[148:151], v[194:197], v[118:121]
	v_mfma_f32_16x16x32_bf16 v[114:117], v[156:159], v[194:197], v[114:117]
	v_mfma_f32_16x16x32_bf16 v[110:113], v[148:151], v[202:205], v[110:113]
	v_mfma_f32_16x16x32_bf16 v[106:109], v[156:159], v[202:205], v[106:109]
	v_mfma_f32_16x16x32_bf16 v[102:105], v[148:151], v[210:213], v[102:105]
	v_mfma_f32_16x16x32_bf16 v[98:101], v[156:159], v[210:213], v[98:101]
	v_mfma_f32_16x16x32_bf16 v[126:129], v[152:155], v[190:193], v[126:129]
	v_mfma_f32_16x16x32_bf16 v[122:125], v[166:169], v[190:193], v[122:125]
	v_mfma_f32_16x16x32_bf16 v[118:121], v[152:155], v[198:201], v[118:121]
	v_mfma_f32_16x16x32_bf16 v[114:117], v[166:169], v[198:201], v[114:117]
	v_mfma_f32_16x16x32_bf16 v[110:113], v[152:155], v[206:209], v[110:113]
	v_mfma_f32_16x16x32_bf16 v[106:109], v[166:169], v[206:209], v[106:109]
	v_mfma_f32_16x16x32_bf16 v[102:105], v[152:155], v[214:217], v[102:105]
	v_mfma_f32_16x16x32_bf16 v[98:101], v[166:169], v[214:217], v[98:101]
	v_mfma_f32_16x16x32_bf16 v[94:97], v[170:173], v[186:189], v[94:97]
	v_mfma_f32_16x16x32_bf16 v[90:93], v[178:181], v[186:189], v[90:93]
	v_mfma_f32_16x16x32_bf16 v[86:89], v[170:173], v[194:197], v[86:89]
	v_mfma_f32_16x16x32_bf16 v[82:85], v[178:181], v[194:197], v[82:85]
	v_mfma_f32_16x16x32_bf16 v[78:81], v[170:173], v[202:205], v[78:81]
	v_mfma_f32_16x16x32_bf16 v[74:77], v[178:181], v[202:205], v[74:77]
	v_mfma_f32_16x16x32_bf16 v[70:73], v[170:173], v[210:213], v[70:73]
	v_mfma_f32_16x16x32_bf16 v[66:69], v[178:181], v[210:213], v[66:69]
	v_mfma_f32_16x16x32_bf16 v[94:97], v[174:177], v[190:193], v[94:97]
	v_mfma_f32_16x16x32_bf16 v[90:93], v[182:185], v[190:193], v[90:93]
	v_mfma_f32_16x16x32_bf16 v[86:89], v[174:177], v[198:201], v[86:89]
	v_mfma_f32_16x16x32_bf16 v[82:85], v[182:185], v[198:201], v[82:85]
	v_mfma_f32_16x16x32_bf16 v[78:81], v[174:177], v[206:209], v[78:81]
	v_mfma_f32_16x16x32_bf16 v[74:77], v[182:185], v[206:209], v[74:77]
	v_mfma_f32_16x16x32_bf16 v[70:73], v[174:177], v[214:217], v[70:73]
	v_mfma_f32_16x16x32_bf16 v[66:69], v[182:185], v[214:217], v[66:69]
	s_barrier
	s_setprio 0
	s_add_i32 s76, s78, s35
	v_lshl_add_u64 v[160:161], s[12:13], 0, v[132:133]
	s_mov_b32 m0, s76
	ds_read_b128 v[186:189], v164 offset:16384
	ds_read_b128 v[190:193], v164 offset:17408
	ds_read_b128 v[194:197], v164 offset:18432
	ds_read_b128 v[198:201], v164 offset:19456
	ds_read_b128 v[202:205], v164 offset:20480
	ds_read_b128 v[206:209], v164 offset:21504
	ds_read_b128 v[210:213], v164 offset:22528
	ds_read_b128 v[214:217], v164 offset:23552
	global_load_lds_dwordx4 v[160:161], off
	s_add_i32 m0, s76, 0x2000
	s_add_u32 s90, s12, 0x40000
	v_lshl_add_u64 v[218:219], s[12:13], 0, v[136:137]
	s_addc_u32 s91, s13, 0
	s_add_i32 s53, s53, s35
	global_load_lds_dwordx4 v[218:219], off
	v_lshl_add_u64 v[220:221], s[90:91], 0, v[132:133]
	s_mov_b32 m0, s53
	v_lshl_add_u64 v[222:223], s[26:27], 0, v[134:135]
	global_load_lds_dwordx4 v[220:221], off
	v_lshl_add_u64 v[220:221], s[90:91], 0, v[136:137]
	s_add_i32 m0, s53, 0x2000
	s_nop 0
	global_load_lds_dwordx4 v[220:221], off
	v_lshl_add_u64 v[220:221], s[26:27], 0, v[130:131]
	s_mov_b32 m0, s17
	s_nop 0
	global_load_lds_dwordx4 v[220:221], off
	s_mov_b32 m0, s37
	s_nop 0
	global_load_lds_dwordx4 v[222:223], off
	s_waitcnt vmcnt(8)
	s_waitcnt vmcnt(8)
	s_waitcnt lgkmcnt(0)
	s_setprio 1
	s_barrier
; #define PG8_STAGE(bufoff, gbase, voff) do { _Pragma("unroll") for (int _i = 0; _i < 2; ++_i) \
;         __builtin_amdgcn_global_load_lds((const unsigned*)((const char*)(gbase) + (voff)[_i]), (PG8_LAS unsigned*)(lds + (bufoff) + ldsw + _i * 8192), 16, 0, 0); } while (0)
; #define PG8_LDA(dst, b, h) do { _Pragma("unroll") for (int m = 0; m < 4; ++m) _Pragma("unroll") for (int k = 0; k < 2; ++k) dst[m][k] = *(const PG8_LAS bf16x8*)(lds + PG8_SA(b, h) + aoff + m * 2048 + k * 1024); } while (0)
; #define PG8_LDB(dst, b, h) do { _Pragma("unroll") for (int n = 0; n < 2; ++n) _Pragma("unroll") for (int k = 0; k < 2; ++k) dst[n][k] = *(const PG8_LAS bf16x8*)(lds + PG8_SB(b, h) + boff + n * 2048 + k * 1024); } while (0)
; #define PG8_MMA(ai, bj, At, Bt) do { __builtin_amdgcn_s_setprio(1); _Pragma("unroll") for (int m = 0; m < 4; ++m) _Pragma("unroll") for (int n = 0; n < 2; ++n) _Pragma("unroll") for (int k = 0; k < 2; ++k) \
;         acc[ai][bj][m][n] = __builtin_amdgcn_mfma_f32_16x16x32_bf16(Bt[n][k], At[m][k], acc[ai][bj][m][n], 0, 0, 0); __builtin_amdgcn_s_setprio(0); } while (0)
; #define PG8_WAIT_V(n) asm volatile("s_waitcnt vmcnt(" #n ")" ::: "memory")
; #define PG8_WAIT_VN(n) asm volatile("s_waitcnt vmcnt(%0)" :: "n"(n) : "memory")
; #define PG8_WAIT_L(n) asm volatile("s_waitcnt lgkmcnt(" #n ")" ::: "memory")
; #define PG8_BAR __builtin_amdgcn_s_barrier()
; #define PG8_SCHED __builtin_amdgcn_sched_barrier(0)
; template <class Epi, class Sched, bool ALIGN_EPI = false, bool SP2 = false>
; __device__ __forceinline__ void gemm_phase(PG8_LAS unsigned char* lds, const Gemm g, const Sched& S, const Epi& E, const int wave_id) {
;     ...
;             PG8_WAIT_VN(8 + Epi::NS); if (strict) PG8_WAIT_V(8); PG8_WAIT_L(0); PG8_BAR; PG8_MMA(1, 0, At, B0); PG8_MMA(1, 1, At, B1); PG8_BAR; PG8_SCHED;
;             PG8_LDB(B0, 1, 0); PG8_LDB(B1, 1, 1); PG8_SCHED; PG8_LDA(At, 1, 0); PG8_STAGE(PG8_SA(0, 1), a2 + hstep, voffA);
;             PG8_WAIT_V(8); PG8_WAIT_L(0); PG8_BAR; PG8_MMA(0, 0, At, B0); PG8_MMA(0, 1, At, B1); PG8_BAR; PG8_SCHED;
	v_mfma_f32_16x16x32_bf16 v[62:65], v[148:151], v[186:189], v[62:65]
	v_mfma_f32_16x16x32_bf16 v[58:61], v[156:159], v[186:189], v[58:61]
	v_mfma_f32_16x16x32_bf16 v[54:57], v[148:151], v[194:197], v[54:57]
	v_mfma_f32_16x16x32_bf16 v[50:53], v[156:159], v[194:197], v[50:53]
	v_mfma_f32_16x16x32_bf16 v[46:49], v[148:151], v[202:205], v[46:49]
	v_mfma_f32_16x16x32_bf16 v[42:45], v[156:159], v[202:205], v[42:45]
	v_mfma_f32_16x16x32_bf16 v[38:41], v[148:151], v[210:213], v[38:41]
	v_mfma_f32_16x16x32_bf16 v[34:37], v[156:159], v[210:213], v[34:37]
	v_mfma_f32_16x16x32_bf16 v[62:65], v[152:155], v[190:193], v[62:65]
	v_mfma_f32_16x16x32_bf16 v[58:61], v[166:169], v[190:193], v[58:61]
	v_mfma_f32_16x16x32_bf16 v[54:57], v[152:155], v[198:201], v[54:57]
	v_mfma_f32_16x16x32_bf16 v[50:53], v[166:169], v[198:201], v[50:53]
	v_mfma_f32_16x16x32_bf16 v[46:49], v[152:155], v[206:209], v[46:49]
	v_mfma_f32_16x16x32_bf16 v[42:45], v[166:169], v[206:209], v[42:45]
	v_mfma_f32_16x16x32_bf16 v[38:41], v[152:155], v[214:217], v[38:41]
	v_mfma_f32_16x16x32_bf16 v[34:37], v[166:169], v[214:217], v[34:37]
	v_mfma_f32_16x16x32_bf16 v[30:33], v[170:173], v[186:189], v[30:33]
	v_mfma_f32_16x16x32_bf16 v[26:29], v[178:181], v[186:189], v[26:29]
	v_mfma_f32_16x16x32_bf16 v[22:25], v[170:173], v[194:197], v[22:25]
	v_mfma_f32_16x16x32_bf16 v[18:21], v[178:181], v[194:197], v[18:21]
	v_mfma_f32_16x16x32_bf16 v[14:17], v[170:173], v[202:205], v[14:17]
	v_mfma_f32_16x16x32_bf16 v[10:13], v[178:181], v[202:205], v[10:13]
	v_mfma_f32_16x16x32_bf16 v[6:9], v[170:173], v[210:213], v[6:9]
	v_mfma_f32_16x16x32_bf16 v[2:5], v[178:181], v[210:213], v[2:5]
	v_mfma_f32_16x16x32_bf16 v[30:33], v[174:177], v[190:193], v[30:33]
	v_mfma_f32_16x16x32_bf16 v[26:29], v[182:185], v[190:193], v[26:29]
	v_mfma_f32_16x16x32_bf16 v[22:25], v[174:177], v[198:201], v[22:25]
	v_mfma_f32_16x16x32_bf16 v[18:21], v[182:185], v[198:201], v[18:21]
	v_mfma_f32_16x16x32_bf16 v[14:17], v[174:177], v[206:209], v[14:17]
	v_mfma_f32_16x16x32_bf16 v[10:13], v[182:185], v[206:209], v[10:13]
	v_mfma_f32_16x16x32_bf16 v[6:9], v[174:177], v[214:217], v[6:9]
	v_mfma_f32_16x16x32_bf16 v[2:5], v[182:185], v[214:217], v[2:5]
	s_barrier
	s_setprio 0
	s_add_i32 s53, 0, 0x18000
	v_add_u32_e32 v147, s53, v163
	s_add_i32 s76, 0, 0x1c000
	ds_read_b128 v[148:151], v147
	ds_read_b128 v[152:155], v147 offset:1024
	ds_read_b128 v[156:159], v147 offset:2048
	ds_read_b128 v[166:169], v147 offset:3072
	v_add_u32_e32 v147, s76, v163
	ds_read_b128 v[170:173], v147
	ds_read_b128 v[174:177], v147 offset:1024
	ds_read_b128 v[178:181], v147 offset:2048
	ds_read_b128 v[182:185], v147 offset:3072
	s_add_u32 s26, s26, 0x40000
	s_addc_u32 s27, s27, 0
	s_mov_b32 m0, s38
	v_lshl_add_u64 v[224:225], s[26:27], 0, v[130:131]
	ds_read_b128 v[186:189], v164 offset:32768
	ds_read_b128 v[190:193], v164 offset:33792
	ds_read_b128 v[194:197], v164 offset:34816
	ds_read_b128 v[198:201], v164 offset:35840
	ds_read_b128 v[202:205], v164 offset:36864
	ds_read_b128 v[206:209], v164 offset:37888
	ds_read_b128 v[210:213], v164 offset:38912
	ds_read_b128 v[214:217], v164 offset:39936
	global_load_lds_dwordx4 v[224:225], off
	v_lshl_add_u64 v[224:225], s[26:27], 0, v[134:135]
	s_mov_b32 m0, s39
	s_nop 0
	global_load_lds_dwordx4 v[224:225], off
	s_waitcnt vmcnt(8)
	s_waitcnt lgkmcnt(0)
	s_setprio 1
	s_barrier
	v_mfma_f32_16x16x32_bf16 v[126:129], v[148:151], v[186:189], v[126:129]
	v_mfma_f32_16x16x32_bf16 v[122:125], v[156:159], v[186:189], v[122:125]
	v_mfma_f32_16x16x32_bf16 v[118:121], v[148:151], v[194:197], v[118:121]
	v_mfma_f32_16x16x32_bf16 v[114:117], v[156:159], v[194:197], v[114:117]
	v_mfma_f32_16x16x32_bf16 v[110:113], v[148:151], v[202:205], v[110:113]
	v_mfma_f32_16x16x32_bf16 v[106:109], v[156:159], v[202:205], v[106:109]
	v_mfma_f32_16x16x32_bf16 v[102:105], v[148:151], v[210:213], v[102:105]
	v_mfma_f32_16x16x32_bf16 v[98:101], v[156:159], v[210:213], v[98:101]
	v_mfma_f32_16x16x32_bf16 v[126:129], v[152:155], v[190:193], v[126:129]
	v_mfma_f32_16x16x32_bf16 v[122:125], v[166:169], v[190:193], v[122:125]
	v_mfma_f32_16x16x32_bf16 v[118:121], v[152:155], v[198:201], v[118:121]
	v_mfma_f32_16x16x32_bf16 v[114:117], v[166:169], v[198:201], v[114:117]
	v_mfma_f32_16x16x32_bf16 v[110:113], v[152:155], v[206:209], v[110:113]
	v_mfma_f32_16x16x32_bf16 v[106:109], v[166:169], v[206:209], v[106:109]
	v_mfma_f32_16x16x32_bf16 v[102:105], v[152:155], v[214:217], v[102:105]
	v_mfma_f32_16x16x32_bf16 v[98:101], v[166:169], v[214:217], v[98:101]
	v_mfma_f32_16x16x32_bf16 v[94:97], v[170:173], v[186:189], v[94:97]
	v_mfma_f32_16x16x32_bf16 v[90:93], v[178:181], v[186:189], v[90:93]
	v_mfma_f32_16x16x32_bf16 v[86:89], v[170:173], v[194:197], v[86:89]
	v_mfma_f32_16x16x32_bf16 v[82:85], v[178:181], v[194:197], v[82:85]
	v_mfma_f32_16x16x32_bf16 v[78:81], v[170:173], v[202:205], v[78:81]
	v_mfma_f32_16x16x32_bf16 v[74:77], v[178:181], v[202:205], v[74:77]
	v_mfma_f32_16x16x32_bf16 v[70:73], v[170:173], v[210:213], v[70:73]
	v_mfma_f32_16x16x32_bf16 v[66:69], v[178:181], v[210:213], v[66:69]
	v_mfma_f32_16x16x32_bf16 v[94:97], v[174:177], v[190:193], v[94:97]
	v_mfma_f32_16x16x32_bf16 v[90:93], v[182:185], v[190:193], v[90:93]
	v_mfma_f32_16x16x32_bf16 v[86:89], v[174:177], v[198:201], v[86:89]
	v_mfma_f32_16x16x32_bf16 v[82:85], v[182:185], v[198:201], v[82:85]
	v_mfma_f32_16x16x32_bf16 v[78:81], v[174:177], v[206:209], v[78:81]
	v_mfma_f32_16x16x32_bf16 v[74:77], v[182:185], v[206:209], v[74:77]
	v_mfma_f32_16x16x32_bf16 v[70:73], v[174:177], v[214:217], v[70:73]
	v_mfma_f32_16x16x32_bf16 v[66:69], v[182:185], v[214:217], v[66:69]
	s_barrier
; #define PG8_STAGE(bufoff, gbase, voff) do { _Pragma("unroll") for (int _i = 0; _i < 2; ++_i) \
;         __builtin_amdgcn_global_load_lds((const unsigned*)((const char*)(gbase) + (voff)[_i]), (PG8_LAS unsigned*)(lds + (bufoff) + ldsw + _i * 8192), 16, 0, 0); } while (0)
; #define PG8_LDA(dst, b, h) do { _Pragma("unroll") for (int m = 0; m < 4; ++m) _Pragma("unroll") for (int k = 0; k < 2; ++k) dst[m][k] = *(const PG8_LAS bf16x8*)(lds + PG8_SA(b, h) + aoff + m * 2048 + k * 1024); } while (0)
; #define PG8_MMA(ai, bj, At, Bt) do { __builtin_amdgcn_s_setprio(1); _Pragma("unroll") for (int m = 0; m < 4; ++m) _Pragma("unroll") for (int n = 0; n < 2; ++n) _Pragma("unroll") for (int k = 0; k < 2; ++k) \
;         acc[ai][bj][m][n] = __builtin_amdgcn_mfma_f32_16x16x32_bf16(Bt[n][k], At[m][k], acc[ai][bj][m][n], 0, 0, 0); __builtin_amdgcn_s_setprio(0); } while (0)
; #define PG8_WAIT_V(n) asm volatile("s_waitcnt vmcnt(" #n ")" ::: "memory")
; #define PG8_WAIT_L(n) asm volatile("s_waitcnt lgkmcnt(" #n ")" ::: "memory")
; #define PG8_BAR __builtin_amdgcn_s_barrier()
; #define PG8_SCHED __builtin_amdgcn_sched_barrier(0)
; template <class Epi, class Sched, bool ALIGN_EPI = false, bool SP2 = false>
; __device__ __forceinline__ void gemm_phase(PG8_LAS unsigned char* lds, const Gemm g, const Sched& S, const Epi& E, const int wave_id) {
;     ...
;             PG8_WAIT_V(8); PG8_WAIT_L(0); PG8_BAR; PG8_MMA(0, 0, At, B0); PG8_MMA(0, 1, At, B1); PG8_BAR; PG8_SCHED;
;             PG8_LDA(At, 1, 1); PG8_STAGE(PG8_SB(1, 0), b3, voffB); PG8_STAGE(PG8_SB(1, 1), b3 + hstep, voffB); PG8_STAGE(PG8_SA(1, 0), a3, voffA);
;             PG8_WAIT_V(8); PG8_WAIT_L(0); PG8_BAR; PG8_MMA(1, 0, At, B0); PG8_MMA(1, 1, At, B1); PG8_BAR; PG8_SCHED;
	s_setprio 0
	s_add_i32 s26, s53, s35
	v_lshl_add_u64 v[160:161], v[160:161], 0, s[64:65]
	s_mov_b32 m0, s26
	ds_read_b128 v[186:189], v164 offset:49152
	ds_read_b128 v[190:193], v164 offset:50176
	ds_read_b128 v[194:197], v164 offset:51200
	ds_read_b128 v[198:201], v164 offset:52224
	ds_read_b128 v[202:205], v164 offset:53248
	ds_read_b128 v[206:209], v164 offset:54272
	ds_read_b128 v[210:213], v164 offset:55296
	ds_read_b128 v[214:217], v164 offset:56320
	global_load_lds_dwordx4 v[160:161], off
	s_add_i32 m0, s26, 0x2000
	s_add_u32 s12, s12, 0x40080
	v_lshl_add_u64 v[160:161], v[218:219], 0, s[64:65]
	s_addc_u32 s13, s13, 0
	s_add_i32 s26, s76, s35
	global_load_lds_dwordx4 v[160:161], off
	v_lshl_add_u64 v[160:161], s[12:13], 0, v[132:133]
	s_mov_b32 m0, s26
	s_nop 0
	global_load_lds_dwordx4 v[160:161], off
	v_lshl_add_u64 v[160:161], s[12:13], 0, v[136:137]
	s_add_i32 m0, s26, 0x2000
	s_nop 0
	global_load_lds_dwordx4 v[160:161], off
	v_lshl_add_u64 v[160:161], v[220:221], 0, s[64:65]
	s_mov_b32 m0, s41
	s_nop 0
	global_load_lds_dwordx4 v[160:161], off
	v_lshl_add_u64 v[160:161], v[222:223], 0, s[64:65]
	s_mov_b32 m0, s42
	s_nop 0
	global_load_lds_dwordx4 v[160:161], off
	s_waitcnt vmcnt(8)
	s_waitcnt lgkmcnt(0)
	s_setprio 1
	s_barrier
	v_mfma_f32_16x16x32_bf16 v[62:65], v[148:151], v[186:189], v[62:65]
	v_mfma_f32_16x16x32_bf16 v[58:61], v[156:159], v[186:189], v[58:61]
	v_mfma_f32_16x16x32_bf16 v[54:57], v[148:151], v[194:197], v[54:57]
	v_mfma_f32_16x16x32_bf16 v[50:53], v[156:159], v[194:197], v[50:53]
	v_mfma_f32_16x16x32_bf16 v[46:49], v[148:151], v[202:205], v[46:49]
	v_mfma_f32_16x16x32_bf16 v[42:45], v[156:159], v[202:205], v[42:45]
	v_mfma_f32_16x16x32_bf16 v[38:41], v[148:151], v[210:213], v[38:41]
	v_mfma_f32_16x16x32_bf16 v[34:37], v[156:159], v[210:213], v[34:37]
	v_mfma_f32_16x16x32_bf16 v[62:65], v[152:155], v[190:193], v[62:65]
	v_mfma_f32_16x16x32_bf16 v[58:61], v[166:169], v[190:193], v[58:61]
	v_mfma_f32_16x16x32_bf16 v[54:57], v[152:155], v[198:201], v[54:57]
	v_mfma_f32_16x16x32_bf16 v[50:53], v[166:169], v[198:201], v[50:53]
	v_mfma_f32_16x16x32_bf16 v[46:49], v[152:155], v[206:209], v[46:49]
	v_mfma_f32_16x16x32_bf16 v[42:45], v[166:169], v[206:209], v[42:45]
	v_mfma_f32_16x16x32_bf16 v[38:41], v[152:155], v[214:217], v[38:41]
	v_mfma_f32_16x16x32_bf16 v[34:37], v[166:169], v[214:217], v[34:37]
	v_mfma_f32_16x16x32_bf16 v[30:33], v[170:173], v[186:189], v[30:33]
	v_mfma_f32_16x16x32_bf16 v[26:29], v[178:181], v[186:189], v[26:29]
	v_mfma_f32_16x16x32_bf16 v[22:25], v[170:173], v[194:197], v[22:25]
	v_mfma_f32_16x16x32_bf16 v[18:21], v[178:181], v[194:197], v[18:21]
	v_mfma_f32_16x16x32_bf16 v[14:17], v[170:173], v[202:205], v[14:17]
	v_mfma_f32_16x16x32_bf16 v[10:13], v[178:181], v[202:205], v[10:13]
	v_mfma_f32_16x16x32_bf16 v[6:9], v[170:173], v[210:213], v[6:9]
	v_mfma_f32_16x16x32_bf16 v[2:5], v[178:181], v[210:213], v[2:5]
	v_mfma_f32_16x16x32_bf16 v[30:33], v[174:177], v[190:193], v[30:33]
	v_mfma_f32_16x16x32_bf16 v[26:29], v[182:185], v[190:193], v[26:29]
	v_mfma_f32_16x16x32_bf16 v[22:25], v[174:177], v[198:201], v[22:25]
	v_mfma_f32_16x16x32_bf16 v[18:21], v[182:185], v[198:201], v[18:21]
	v_mfma_f32_16x16x32_bf16 v[14:17], v[174:177], v[206:209], v[14:17]
	v_mfma_f32_16x16x32_bf16 v[10:13], v[182:185], v[206:209], v[10:13]
	v_mfma_f32_16x16x32_bf16 v[6:9], v[174:177], v[214:217], v[6:9]
	v_mfma_f32_16x16x32_bf16 v[2:5], v[182:185], v[214:217], v[2:5]
	s_barrier
	s_setprio 0
	s_add_u32 s10, s10, 0x100
	s_addc_u32 s11, s11, 0
	s_cmp_gt_u32 s69, 13
	s_cbranch_scc0 .LBB0_1537
	s_and_b64 vcc, exec, s[24:25]
	s_cbranch_vccz .LBB0_1540
	s_barrier

; #define PG8_STAGE(bufoff, gbase, voff) do { _Pragma("unroll") for (int _i = 0; _i < 2; ++_i) \
;         __builtin_amdgcn_global_load_lds((const unsigned*)((const char*)(gbase) + (voff)[_i]), (PG8_LAS unsigned*)(lds + (bufoff) + ldsw + _i * 8192), 16, 0, 0); } while (0)
; #define PG8_LDA(dst, b, h) do { _Pragma("unroll") for (int m = 0; m < 4; ++m) _Pragma("unroll") for (int k = 0; k < 2; ++k) dst[m][k] = *(const PG8_LAS bf16x8*)(lds + PG8_SA(b, h) + aoff + m * 2048 + k * 1024); } while (0)
; #define PG8_LDB(dst, b, h) do { _Pragma("unroll") for (int n = 0; n < 2; ++n) _Pragma("unroll") for (int k = 0; k < 2; ++k) dst[n][k] = *(const PG8_LAS bf16x8*)(lds + PG8_SB(b, h) + boff + n * 2048 + k * 1024); } while (0)
; #define PG8_WAIT_V(n) asm volatile("s_waitcnt vmcnt(" #n ")" ::: "memory")
; #define PG8_WAIT_VN(n) asm volatile("s_waitcnt vmcnt(%0)" :: "n"(n) : "memory")
; #define PG8_WAIT_L(n) asm volatile("s_waitcnt lgkmcnt(" #n ")" ::: "memory")
; template <class Epi, class Sched, bool ALIGN_EPI = false, bool SP2 = false>
; __device__ __forceinline__ void gemm_phase(PG8_LAS unsigned char* lds, const Gemm g, const Sched& S, const Epi& E, const int wave_id) {
;     ...
;         for (int t = 0; t < nt; t += 2) {
;             const bool last = (t == nt - 2);
;             const char* a1 = cA + (size_t)(t + 1) * kstep;
;             const char* a2 = last ? nA : cA + (size_t)(t + 2) * kstep; const char* b2 = last ? nB : cB + (size_t)(t + 2) * kstep;
;             const char* a3 = a2 + kstep; const char* b3 = b2 + kstep;
;             if (last && has_next) S.a_ready(nxt);
;             if constexpr (SP2) {
;             int tz_ = __builtin_amdgcn_readfirstlane(t | (ui > 0 ? 0 : 1)); asm volatile("" : "+s"(tz_));
;             const bool strict = !(Epi::NS > 0 && tz_ == 0);
;             PG8_LDB(B0, 0, 0); PG8_LDB(B1, 0, 1); PG8_SCHED; PG8_LDA(At, 0, 0); PG8_STAGE(PG8_SA(1, 1), a1 + hstep, voffA);
;             PG8_WAIT_VN(8 + Epi::NS); if (strict) PG8_WAIT_V(8); PG8_WAIT_L(0); PG8_BAR; PG8_MMA(0, 0, At, B0); PG8_MMA(0, 1, At, B1); PG8_BAR; PG8_SCHED;
;             PG8_LDA(At, 0, 1); PG8_STAGE(PG8_SB(0, 0), b2, voffB); PG8_STAGE(PG8_SB(0, 1), b2 + hstep, voffB); PG8_STAGE(PG8_SA(0, 0), a2, voffA);
;             PG8_WAIT_VN(8 + Epi::NS); if (strict) PG8_WAIT_V(8); PG8_WAIT_L(0); PG8_BAR; PG8_MMA(1, 0, At, B0); PG8_MMA(1, 1, At, B1); PG8_BAR; PG8_SCHED;
.LBB0_1685:
	s_add_u32 s24, s20, s22
	s_addc_u32 s25, s21, s23
	s_add_u32 s24, s24, 0x100
	s_addc_u32 s25, s25, 0
	s_add_u32 s53, s52, s22
	s_addc_u32 s57, s54, s23
	s_add_i32 s56, s56, 2
	s_add_i32 s62, 0, 0x10000
	v_add_u32_e32 v147, s56, v146
	s_cmpk_eq_i32 s22, 0x700
	s_cselect_b32 s26, s11, s24
	v_readfirstlane_b32 s24, v147
	s_cselect_b32 s27, s9, s25
	v_add_u32_e32 v147, s62, v163
	s_cselect_b32 s25, s13, s57
	s_cselect_b32 s24, s15, s53
	s_add_i32 s53, 0, 0x14000
	ds_read_b128 v[148:151], v147
	ds_read_b128 v[152:155], v147 offset:1024
	ds_read_b128 v[156:159], v147 offset:2048
	ds_read_b128 v[166:169], v147 offset:3072
	v_add_u32_e32 v147, s53, v163
	ds_read_b128 v[170:173], v147
	ds_read_b128 v[174:177], v147 offset:1024
	ds_read_b128 v[178:181], v147 offset:2048
	ds_read_b128 v[182:185], v147 offset:3072
	v_lshl_add_u64 v[160:161], v[144:145], 0, s[22:23]
	s_add_i32 m0, s38, 0xc000
	ds_read_b128 v[186:189], v164
	ds_read_b128 v[190:193], v164 offset:1024
	ds_read_b128 v[194:197], v164 offset:2048
	ds_read_b128 v[198:201], v164 offset:3072
	ds_read_b128 v[202:205], v164 offset:4096
	ds_read_b128 v[206:209], v164 offset:5120
	ds_read_b128 v[210:213], v164 offset:6144
	ds_read_b128 v[214:217], v164 offset:7168
	global_load_lds_dwordx4 v[160:161], off
	v_lshl_add_u64 v[160:161], v[142:143], 0, s[22:23]
	s_add_i32 m0, s38, 0xe000
	s_nop 0
	global_load_lds_dwordx4 v[160:161], off
	s_waitcnt vmcnt(8)
	s_waitcnt vmcnt(8)
	s_waitcnt lgkmcnt(0)
	s_setprio 1
	s_barrier
	v_mfma_f32_16x16x32_bf16 v[126:129], v[148:151], v[186:189], v[126:129]
	v_mfma_f32_16x16x32_bf16 v[122:125], v[156:159], v[186:189], v[122:125]
	v_mfma_f32_16x16x32_bf16 v[118:121], v[148:151], v[194:197], v[118:121]
	v_mfma_f32_16x16x32_bf16 v[114:117], v[156:159], v[194:197], v[114:117]
	v_mfma_f32_16x16x32_bf16 v[110:113], v[148:151], v[202:205], v[110:113]
	v_mfma_f32_16x16x32_bf16 v[106:109], v[156:159], v[202:205], v[106:109]
	v_mfma_f32_16x16x32_bf16 v[102:105], v[148:151], v[210:213], v[102:105]
	v_mfma_f32_16x16x32_bf16 v[98:101], v[156:159], v[210:213], v[98:101]
	v_mfma_f32_16x16x32_bf16 v[126:129], v[152:155], v[190:193], v[126:129]
	v_mfma_f32_16x16x32_bf16 v[122:125], v[166:169], v[190:193], v[122:125]
	v_mfma_f32_16x16x32_bf16 v[118:121], v[152:155], v[198:201], v[118:121]
	v_mfma_f32_16x16x32_bf16 v[114:117], v[166:169], v[198:201], v[114:117]
	v_mfma_f32_16x16x32_bf16 v[110:113], v[152:155], v[206:209], v[110:113]
	v_mfma_f32_16x16x32_bf16 v[106:109], v[166:169], v[206:209], v[106:109]
	v_mfma_f32_16x16x32_bf16 v[102:105], v[152:155], v[214:217], v[102:105]
	v_mfma_f32_16x16x32_bf16 v[98:101], v[166:169], v[214:217], v[98:101]
	v_mfma_f32_16x16x32_bf16 v[94:97], v[170:173], v[186:189], v[94:97]
	v_mfma_f32_16x16x32_bf16 v[90:93], v[178:181], v[186:189], v[90:93]
	v_mfma_f32_16x16x32_bf16 v[86:89], v[170:173], v[194:197], v[86:89]
	v_mfma_f32_16x16x32_bf16 v[82:85], v[178:181], v[194:197], v[82:85]
	v_mfma_f32_16x16x32_bf16 v[78:81], v[170:173], v[202:205], v[78:81]
	v_mfma_f32_16x16x32_bf16 v[74:77], v[178:181], v[202:205], v[74:77]
	v_mfma_f32_16x16x32_bf16 v[70:73], v[170:173], v[210:213], v[70:73]
	v_mfma_f32_16x16x32_bf16 v[66:69], v[178:181], v[210:213], v[66:69]
	v_mfma_f32_16x16x32_bf16 v[94:97], v[174:177], v[190:193], v[94:97]
	v_mfma_f32_16x16x32_bf16 v[90:93], v[182:185], v[190:193], v[90:93]
	v_mfma_f32_16x16x32_bf16 v[86:89], v[174:177], v[198:201], v[86:89]
	v_mfma_f32_16x16x32_bf16 v[82:85], v[182:185], v[198:201], v[82:85]
	v_mfma_f32_16x16x32_bf16 v[78:81], v[174:177], v[206:209], v[78:81]
	v_mfma_f32_16x16x32_bf16 v[74:77], v[182:185], v[206:209], v[74:77]
	v_mfma_f32_16x16x32_bf16 v[70:73], v[174:177], v[214:217], v[70:73]
	v_mfma_f32_16x16x32_bf16 v[66:69], v[182:185], v[214:217], v[66:69]
	s_barrier
	s_setprio 0
	s_add_i32 s57, s62, s37
	v_lshl_add_u64 v[160:161], s[24:25], 0, v[132:133]
	s_mov_b32 m0, s57
	ds_read_b128 v[186:189], v164 offset:16384
	ds_read_b128 v[190:193], v164 offset:17408
	ds_read_b128 v[194:197], v164 offset:18432
	ds_read_b128 v[198:201], v164 offset:19456
	ds_read_b128 v[202:205], v164 offset:20480
	ds_read_b128 v[206:209], v164 offset:21504
	ds_read_b128 v[210:213], v164 offset:22528
	ds_read_b128 v[214:217], v164 offset:23552
	global_load_lds_dwordx4 v[160:161], off
	s_add_i32 m0, s57, 0x2000
	s_add_u32 s62, s24, 0x40000
	v_lshl_add_u64 v[218:219], s[24:25], 0, v[136:137]
	s_addc_u32 s63, s25, 0
	s_add_i32 s53, s53, s37
	global_load_lds_dwordx4 v[218:219], off
	v_lshl_add_u64 v[220:221], s[62:63], 0, v[132:133]
	s_mov_b32 m0, s53
	v_lshl_add_u64 v[222:223], s[26:27], 0, v[134:135]
	global_load_lds_dwordx4 v[220:221], off
	v_lshl_add_u64 v[220:221], s[62:63], 0, v[136:137]
	s_add_i32 m0, s53, 0x2000
	s_nop 0
	global_load_lds_dwordx4 v[220:221], off
	v_lshl_add_u64 v[220:221], s[26:27], 0, v[130:131]
	s_mov_b32 m0, s38
	s_nop 0
	global_load_lds_dwordx4 v[220:221], off
	s_mov_b32 m0, s39
	s_nop 0
	global_load_lds_dwordx4 v[222:223], off
	s_waitcnt vmcnt(8)
	s_waitcnt vmcnt(8)
	s_waitcnt lgkmcnt(0)
	s_setprio 1
	s_barrier
; #define PG8_STAGE(bufoff, gbase, voff) do { _Pragma("unroll") for (int _i = 0; _i < 2; ++_i) \
;         __builtin_amdgcn_global_load_lds((const unsigned*)((const char*)(gbase) + (voff)[_i]), (PG8_LAS unsigned*)(lds + (bufoff) + ldsw + _i * 8192), 16, 0, 0); } while (0)
; #define PG8_LDA(dst, b, h) do { _Pragma("unroll") for (int m = 0; m < 4; ++m) _Pragma("unroll") for (int k = 0; k < 2; ++k) dst[m][k] = *(const PG8_LAS bf16x8*)(lds + PG8_SA(b, h) + aoff + m * 2048 + k * 1024); } while (0)
; #define PG8_LDB(dst, b, h) do { _Pragma("unroll") for (int n = 0; n < 2; ++n) _Pragma("unroll") for (int k = 0; k < 2; ++k) dst[n][k] = *(const PG8_LAS bf16x8*)(lds + PG8_SB(b, h) + boff + n * 2048 + k * 1024); } while (0)
; #define PG8_MMA(ai, bj, At, Bt) do { __builtin_amdgcn_s_setprio(1); _Pragma("unroll") for (int m = 0; m < 4; ++m) _Pragma("unroll") for (int n = 0; n < 2; ++n) _Pragma("unroll") for (int k = 0; k < 2; ++k) \
;         acc[ai][bj][m][n] = __builtin_amdgcn_mfma_f32_16x16x32_bf16(Bt[n][k], At[m][k], acc[ai][bj][m][n], 0, 0, 0); __builtin_amdgcn_s_setprio(0); } while (0)
; #define PG8_WAIT_V(n) asm volatile("s_waitcnt vmcnt(" #n ")" ::: "memory")
; #define PG8_WAIT_VN(n) asm volatile("s_waitcnt vmcnt(%0)" :: "n"(n) : "memory")
; #define PG8_WAIT_L(n) asm volatile("s_waitcnt lgkmcnt(" #n ")" ::: "memory")
; #define PG8_BAR __builtin_amdgcn_s_barrier()
; #define PG8_SCHED __builtin_amdgcn_sched_barrier(0)
; template <class Epi, class Sched, bool ALIGN_EPI = false, bool SP2 = false>
; __device__ __forceinline__ void gemm_phase(PG8_LAS unsigned char* lds, const Gemm g, const Sched& S, const Epi& E, const int wave_id) {
;     ...
;             PG8_WAIT_VN(8 + Epi::NS); if (strict) PG8_WAIT_V(8); PG8_WAIT_L(0); PG8_BAR; PG8_MMA(1, 0, At, B0); PG8_MMA(1, 1, At, B1); PG8_BAR; PG8_SCHED;
;             PG8_LDB(B0, 1, 0); PG8_LDB(B1, 1, 1); PG8_SCHED; PG8_LDA(At, 1, 0); PG8_STAGE(PG8_SA(0, 1), a2 + hstep, voffA);
;             PG8_WAIT_V(8); PG8_WAIT_L(0); PG8_BAR; PG8_MMA(0, 0, At, B0); PG8_MMA(0, 1, At, B1); PG8_BAR; PG8_SCHED;
	v_mfma_f32_16x16x32_bf16 v[62:65], v[148:151], v[186:189], v[62:65]
	v_mfma_f32_16x16x32_bf16 v[58:61], v[156:159], v[186:189], v[58:61]
	v_mfma_f32_16x16x32_bf16 v[54:57], v[148:151], v[194:197], v[54:57]
	v_mfma_f32_16x16x32_bf16 v[50:53], v[156:159], v[194:197], v[50:53]
	v_mfma_f32_16x16x32_bf16 v[46:49], v[148:151], v[202:205], v[46:49]
	v_mfma_f32_16x16x32_bf16 v[42:45], v[156:159], v[202:205], v[42:45]
	v_mfma_f32_16x16x32_bf16 v[38:41], v[148:151], v[210:213], v[38:41]
	v_mfma_f32_16x16x32_bf16 v[34:37], v[156:159], v[210:213], v[34:37]
	v_mfma_f32_16x16x32_bf16 v[62:65], v[152:155], v[190:193], v[62:65]
	v_mfma_f32_16x16x32_bf16 v[58:61], v[166:169], v[190:193], v[58:61]
	v_mfma_f32_16x16x32_bf16 v[54:57], v[152:155], v[198:201], v[54:57]
	v_mfma_f32_16x16x32_bf16 v[50:53], v[166:169], v[198:201], v[50:53]
	v_mfma_f32_16x16x32_bf16 v[46:49], v[152:155], v[206:209], v[46:49]
	v_mfma_f32_16x16x32_bf16 v[42:45], v[166:169], v[206:209], v[42:45]
	v_mfma_f32_16x16x32_bf16 v[38:41], v[152:155], v[214:217], v[38:41]
	v_mfma_f32_16x16x32_bf16 v[34:37], v[166:169], v[214:217], v[34:37]
	v_mfma_f32_16x16x32_bf16 v[30:33], v[170:173], v[186:189], v[30:33]
	v_mfma_f32_16x16x32_bf16 v[26:29], v[178:181], v[186:189], v[26:29]
	v_mfma_f32_16x16x32_bf16 v[22:25], v[170:173], v[194:197], v[22:25]
	v_mfma_f32_16x16x32_bf16 v[18:21], v[178:181], v[194:197], v[18:21]
	v_mfma_f32_16x16x32_bf16 v[14:17], v[170:173], v[202:205], v[14:17]
	v_mfma_f32_16x16x32_bf16 v[10:13], v[178:181], v[202:205], v[10:13]
	v_mfma_f32_16x16x32_bf16 v[6:9], v[170:173], v[210:213], v[6:9]
	v_mfma_f32_16x16x32_bf16 v[2:5], v[178:181], v[210:213], v[2:5]
	v_mfma_f32_16x16x32_bf16 v[30:33], v[174:177], v[190:193], v[30:33]
	v_mfma_f32_16x16x32_bf16 v[26:29], v[182:185], v[190:193], v[26:29]
	v_mfma_f32_16x16x32_bf16 v[22:25], v[174:177], v[198:201], v[22:25]
	v_mfma_f32_16x16x32_bf16 v[18:21], v[182:185], v[198:201], v[18:21]
	v_mfma_f32_16x16x32_bf16 v[14:17], v[174:177], v[206:209], v[14:17]
	v_mfma_f32_16x16x32_bf16 v[10:13], v[182:185], v[206:209], v[10:13]
	v_mfma_f32_16x16x32_bf16 v[6:9], v[174:177], v[214:217], v[6:9]
	v_mfma_f32_16x16x32_bf16 v[2:5], v[182:185], v[214:217], v[2:5]
	s_barrier
	s_setprio 0
	s_add_i32 s53, 0, 0x18000
	v_add_u32_e32 v147, s53, v163
	s_add_i32 s57, 0, 0x1c000
	ds_read_b128 v[148:151], v147
	ds_read_b128 v[152:155], v147 offset:1024
	ds_read_b128 v[156:159], v147 offset:2048
	ds_read_b128 v[166:169], v147 offset:3072
	v_add_u32_e32 v147, s57, v163
	ds_read_b128 v[170:173], v147
	ds_read_b128 v[174:177], v147 offset:1024
	ds_read_b128 v[178:181], v147 offset:2048
	ds_read_b128 v[182:185], v147 offset:3072
	s_add_u32 s26, s26, 0x40000
	s_addc_u32 s27, s27, 0
	s_mov_b32 m0, s40
	v_lshl_add_u64 v[224:225], s[26:27], 0, v[130:131]
	ds_read_b128 v[186:189], v164 offset:32768
	ds_read_b128 v[190:193], v164 offset:33792
	ds_read_b128 v[194:197], v164 offset:34816
	ds_read_b128 v[198:201], v164 offset:35840
	ds_read_b128 v[202:205], v164 offset:36864
	ds_read_b128 v[206:209], v164 offset:37888
	ds_read_b128 v[210:213], v164 offset:38912
	ds_read_b128 v[214:217], v164 offset:39936
	global_load_lds_dwordx4 v[224:225], off
	v_lshl_add_u64 v[224:225], s[26:27], 0, v[134:135]
	s_mov_b32 m0, s41
	s_nop 0
	global_load_lds_dwordx4 v[224:225], off
	s_waitcnt vmcnt(8)
	s_waitcnt lgkmcnt(0)
	s_setprio 1
	s_barrier
	v_mfma_f32_16x16x32_bf16 v[126:129], v[148:151], v[186:189], v[126:129]
	v_mfma_f32_16x16x32_bf16 v[122:125], v[156:159], v[186:189], v[122:125]
	v_mfma_f32_16x16x32_bf16 v[118:121], v[148:151], v[194:197], v[118:121]
	v_mfma_f32_16x16x32_bf16 v[114:117], v[156:159], v[194:197], v[114:117]
	v_mfma_f32_16x16x32_bf16 v[110:113], v[148:151], v[202:205], v[110:113]
	v_mfma_f32_16x16x32_bf16 v[106:109], v[156:159], v[202:205], v[106:109]
	v_mfma_f32_16x16x32_bf16 v[102:105], v[148:151], v[210:213], v[102:105]
	v_mfma_f32_16x16x32_bf16 v[98:101], v[156:159], v[210:213], v[98:101]
	v_mfma_f32_16x16x32_bf16 v[126:129], v[152:155], v[190:193], v[126:129]
	v_mfma_f32_16x16x32_bf16 v[122:125], v[166:169], v[190:193], v[122:125]
	v_mfma_f32_16x16x32_bf16 v[118:121], v[152:155], v[198:201], v[118:121]
	v_mfma_f32_16x16x32_bf16 v[114:117], v[166:169], v[198:201], v[114:117]
	v_mfma_f32_16x16x32_bf16 v[110:113], v[152:155], v[206:209], v[110:113]
	v_mfma_f32_16x16x32_bf16 v[106:109], v[166:169], v[206:209], v[106:109]
	v_mfma_f32_16x16x32_bf16 v[102:105], v[152:155], v[214:217], v[102:105]
	v_mfma_f32_16x16x32_bf16 v[98:101], v[166:169], v[214:217], v[98:101]
	v_mfma_f32_16x16x32_bf16 v[94:97], v[170:173], v[186:189], v[94:97]
	v_mfma_f32_16x16x32_bf16 v[90:93], v[178:181], v[186:189], v[90:93]
	v_mfma_f32_16x16x32_bf16 v[86:89], v[170:173], v[194:197], v[86:89]
	v_mfma_f32_16x16x32_bf16 v[82:85], v[178:181], v[194:197], v[82:85]
	v_mfma_f32_16x16x32_bf16 v[78:81], v[170:173], v[202:205], v[78:81]
	v_mfma_f32_16x16x32_bf16 v[74:77], v[178:181], v[202:205], v[74:77]
	v_mfma_f32_16x16x32_bf16 v[70:73], v[170:173], v[210:213], v[70:73]
	v_mfma_f32_16x16x32_bf16 v[66:69], v[178:181], v[210:213], v[66:69]
	v_mfma_f32_16x16x32_bf16 v[94:97], v[174:177], v[190:193], v[94:97]
	v_mfma_f32_16x16x32_bf16 v[90:93], v[182:185], v[190:193], v[90:93]
	v_mfma_f32_16x16x32_bf16 v[86:89], v[174:177], v[198:201], v[86:89]
	v_mfma_f32_16x16x32_bf16 v[82:85], v[182:185], v[198:201], v[82:85]
	v_mfma_f32_16x16x32_bf16 v[78:81], v[174:177], v[206:209], v[78:81]
	v_mfma_f32_16x16x32_bf16 v[74:77], v[182:185], v[206:209], v[74:77]
	v_mfma_f32_16x16x32_bf16 v[70:73], v[174:177], v[214:217], v[70:73]
	v_mfma_f32_16x16x32_bf16 v[66:69], v[182:185], v[214:217], v[66:69]
	s_barrier
; #define PG8_STAGE(bufoff, gbase, voff) do { _Pragma("unroll") for (int _i = 0; _i < 2; ++_i) \
;         __builtin_amdgcn_global_load_lds((const unsigned*)((const char*)(gbase) + (voff)[_i]), (PG8_LAS unsigned*)(lds + (bufoff) + ldsw + _i * 8192), 16, 0, 0); } while (0)
; #define PG8_LDA(dst, b, h) do { _Pragma("unroll") for (int m = 0; m < 4; ++m) _Pragma("unroll") for (int k = 0; k < 2; ++k) dst[m][k] = *(const PG8_LAS bf16x8*)(lds + PG8_SA(b, h) + aoff + m * 2048 + k * 1024); } while (0)
; #define PG8_MMA(ai, bj, At, Bt) do { __builtin_amdgcn_s_setprio(1); _Pragma("unroll") for (int m = 0; m < 4; ++m) _Pragma("unroll") for (int n = 0; n < 2; ++n) _Pragma("unroll") for (int k = 0; k < 2; ++k) \
;         acc[ai][bj][m][n] = __builtin_amdgcn_mfma_f32_16x16x32_bf16(Bt[n][k], At[m][k], acc[ai][bj][m][n], 0, 0, 0); __builtin_amdgcn_s_setprio(0); } while (0)
; #define PG8_WAIT_V(n) asm volatile("s_waitcnt vmcnt(" #n ")" ::: "memory")
; #define PG8_WAIT_L(n) asm volatile("s_waitcnt lgkmcnt(" #n ")" ::: "memory")
; #define PG8_BAR __builtin_amdgcn_s_barrier()
; #define PG8_SCHED __builtin_amdgcn_sched_barrier(0)
; template <class Epi, class Sched, bool ALIGN_EPI = false, bool SP2 = false>
; __device__ __forceinline__ void gemm_phase(PG8_LAS unsigned char* lds, const Gemm g, const Sched& S, const Epi& E, const int wave_id) {
;     ...
;             PG8_LDA(At, 1, 1); PG8_STAGE(PG8_SB(1, 0), b3, voffB); PG8_STAGE(PG8_SB(1, 1), b3 + hstep, voffB); PG8_STAGE(PG8_SA(1, 0), a3, voffA);
;             PG8_WAIT_V(8); PG8_WAIT_L(0); PG8_BAR; PG8_MMA(1, 0, At, B0); PG8_MMA(1, 1, At, B1); PG8_BAR; PG8_SCHED;
;     ...
;         if constexpr (ALIGN_EPI) { if (wr == 0) PG8_BAR; }
	s_setprio 0
	s_add_i32 s26, s53, s37
	v_lshl_add_u64 v[160:161], v[160:161], 0, s[64:65]
	s_mov_b32 m0, s26
	ds_read_b128 v[186:189], v164 offset:49152
	ds_read_b128 v[190:193], v164 offset:50176
	ds_read_b128 v[194:197], v164 offset:51200
	ds_read_b128 v[198:201], v164 offset:52224
	ds_read_b128 v[202:205], v164 offset:53248
	ds_read_b128 v[206:209], v164 offset:54272
	ds_read_b128 v[210:213], v164 offset:55296
	ds_read_b128 v[214:217], v164 offset:56320
	global_load_lds_dwordx4 v[160:161], off
	s_add_i32 m0, s26, 0x2000
	s_add_u32 s24, s24, 0x40080
	v_lshl_add_u64 v[160:161], v[218:219], 0, s[64:65]
	s_addc_u32 s25, s25, 0
	s_add_i32 s26, s57, s37
	global_load_lds_dwordx4 v[160:161], off
	v_lshl_add_u64 v[160:161], s[24:25], 0, v[132:133]
	s_mov_b32 m0, s26
	s_nop 0
	global_load_lds_dwordx4 v[160:161], off
	v_lshl_add_u64 v[160:161], s[24:25], 0, v[136:137]
	s_add_i32 m0, s26, 0x2000
	s_nop 0
	global_load_lds_dwordx4 v[160:161], off
	v_lshl_add_u64 v[160:161], v[220:221], 0, s[64:65]
	s_mov_b32 m0, s43
	s_nop 0
	global_load_lds_dwordx4 v[160:161], off
	v_lshl_add_u64 v[160:161], v[222:223], 0, s[64:65]
	s_mov_b32 m0, s49
	s_nop 0
	global_load_lds_dwordx4 v[160:161], off
	s_waitcnt vmcnt(8)
	s_waitcnt lgkmcnt(0)
	s_setprio 1
	s_barrier
	v_mfma_f32_16x16x32_bf16 v[62:65], v[148:151], v[186:189], v[62:65]
	v_mfma_f32_16x16x32_bf16 v[58:61], v[156:159], v[186:189], v[58:61]
	v_mfma_f32_16x16x32_bf16 v[54:57], v[148:151], v[194:197], v[54:57]
	v_mfma_f32_16x16x32_bf16 v[50:53], v[156:159], v[194:197], v[50:53]
	v_mfma_f32_16x16x32_bf16 v[46:49], v[148:151], v[202:205], v[46:49]
	v_mfma_f32_16x16x32_bf16 v[42:45], v[156:159], v[202:205], v[42:45]
	v_mfma_f32_16x16x32_bf16 v[38:41], v[148:151], v[210:213], v[38:41]
	v_mfma_f32_16x16x32_bf16 v[34:37], v[156:159], v[210:213], v[34:37]
	v_mfma_f32_16x16x32_bf16 v[62:65], v[152:155], v[190:193], v[62:65]
	v_mfma_f32_16x16x32_bf16 v[58:61], v[166:169], v[190:193], v[58:61]
	v_mfma_f32_16x16x32_bf16 v[54:57], v[152:155], v[198:201], v[54:57]
	v_mfma_f32_16x16x32_bf16 v[50:53], v[166:169], v[198:201], v[50:53]
	v_mfma_f32_16x16x32_bf16 v[46:49], v[152:155], v[206:209], v[46:49]
	v_mfma_f32_16x16x32_bf16 v[42:45], v[166:169], v[206:209], v[42:45]
	v_mfma_f32_16x16x32_bf16 v[38:41], v[152:155], v[214:217], v[38:41]
	v_mfma_f32_16x16x32_bf16 v[34:37], v[166:169], v[214:217], v[34:37]
	v_mfma_f32_16x16x32_bf16 v[30:33], v[170:173], v[186:189], v[30:33]
	v_mfma_f32_16x16x32_bf16 v[26:29], v[178:181], v[186:189], v[26:29]
	v_mfma_f32_16x16x32_bf16 v[22:25], v[170:173], v[194:197], v[22:25]
	v_mfma_f32_16x16x32_bf16 v[18:21], v[178:181], v[194:197], v[18:21]
	v_mfma_f32_16x16x32_bf16 v[14:17], v[170:173], v[202:205], v[14:17]
	v_mfma_f32_16x16x32_bf16 v[10:13], v[178:181], v[202:205], v[10:13]
	v_mfma_f32_16x16x32_bf16 v[6:9], v[170:173], v[210:213], v[6:9]
	v_mfma_f32_16x16x32_bf16 v[2:5], v[178:181], v[210:213], v[2:5]
	v_mfma_f32_16x16x32_bf16 v[30:33], v[174:177], v[190:193], v[30:33]
	v_mfma_f32_16x16x32_bf16 v[26:29], v[182:185], v[190:193], v[26:29]
	v_mfma_f32_16x16x32_bf16 v[22:25], v[174:177], v[198:201], v[22:25]
	v_mfma_f32_16x16x32_bf16 v[18:21], v[182:185], v[198:201], v[18:21]
	v_mfma_f32_16x16x32_bf16 v[14:17], v[174:177], v[206:209], v[14:17]
	v_mfma_f32_16x16x32_bf16 v[10:13], v[182:185], v[206:209], v[10:13]
	v_mfma_f32_16x16x32_bf16 v[6:9], v[174:177], v[214:217], v[6:9]
	v_mfma_f32_16x16x32_bf16 v[2:5], v[182:185], v[214:217], v[2:5]
	s_barrier
	s_setprio 0
	s_add_u32 s22, s22, 0x100
	s_addc_u32 s23, s23, 0
	s_cmp_gt_u32 s56, 13
	s_cbranch_scc0 .LBB0_1685
	s_and_b64 vcc, exec, s[4:5]
	s_cbranch_vccz .LBB0_1688
	s_barrier

; #define PG8_STAGE(bufoff, gbase, voff) do { _Pragma("unroll") for (int _i = 0; _i < 2; ++_i) \
;         __builtin_amdgcn_global_load_lds((const unsigned*)((const char*)(gbase) + (voff)[_i]), (PG8_LAS unsigned*)(lds + (bufoff) + ldsw + _i * 8192), 16, 0, 0); } while (0)
; #define PG8_LDA(dst, b, h) do { _Pragma("unroll") for (int m = 0; m < 4; ++m) _Pragma("unroll") for (int k = 0; k < 2; ++k) dst[m][k] = *(const PG8_LAS bf16x8*)(lds + PG8_SA(b, h) + aoff + m * 2048 + k * 1024); } while (0)
; #define PG8_LDB(dst, b, h) do { _Pragma("unroll") for (int n = 0; n < 2; ++n) _Pragma("unroll") for (int k = 0; k < 2; ++k) dst[n][k] = *(const PG8_LAS bf16x8*)(lds + PG8_SB(b, h) + boff + n * 2048 + k * 1024); } while (0)
; #define PG8_MMA(ai, bj, At, Bt) do { __builtin_amdgcn_s_setprio(1); _Pragma("unroll") for (int m = 0; m < 4; ++m) _Pragma("unroll") for (int n = 0; n < 2; ++n) _Pragma("unroll") for (int k = 0; k < 2; ++k) \
;         acc[ai][bj][m][n] = __builtin_amdgcn_mfma_f32_16x16x32_bf16(Bt[n][k], At[m][k], acc[ai][bj][m][n], 0, 0, 0); __builtin_amdgcn_s_setprio(0); } while (0)
; #define PG8_WAIT_V(n) asm volatile("s_waitcnt vmcnt(" #n ")" ::: "memory")
; #define PG8_WAIT_VN(n) asm volatile("s_waitcnt vmcnt(%0)" :: "n"(n) : "memory")
; #define PG8_WAIT_L(n) asm volatile("s_waitcnt lgkmcnt(" #n ")" ::: "memory")
; #define PG8_BAR __builtin_amdgcn_s_barrier()
; #define PG8_SCHED __builtin_amdgcn_sched_barrier(0)
; template <class Epi, class Sched, bool ALIGN_EPI = false, bool SP2 = false>
; __device__ __forceinline__ void gemm_phase(PG8_LAS unsigned char* lds, const Gemm g, const Sched& S, const Epi& E, const int wave_id) {
;     ...
;             PG8_WAIT_VN(8 + Epi::NS); if (strict) PG8_WAIT_V(8); PG8_WAIT_L(0); PG8_BAR; PG8_MMA(1, 0, At, B0); PG8_MMA(1, 1, At, B1); PG8_BAR; PG8_SCHED;
;             PG8_LDB(B0, 1, 0); PG8_LDB(B1, 1, 1); PG8_SCHED; PG8_LDA(At, 1, 0); PG8_STAGE(PG8_SA(0, 1), a2 + hstep, voffA);
;             PG8_WAIT_V(8); PG8_WAIT_L(0); PG8_BAR; PG8_MMA(0, 0, At, B0); PG8_MMA(0, 1, At, B1); PG8_BAR; PG8_SCHED;
.LBB0_1821:
	s_waitcnt lgkmcnt(0)
	s_setprio 1
	s_barrier
	v_mfma_f32_16x16x32_bf16 v[62:65], v[146:149], v[186:189], v[62:65]
	v_mfma_f32_16x16x32_bf16 v[58:61], v[154:157], v[186:189], v[58:61]
	v_mfma_f32_16x16x32_bf16 v[46:49], v[146:149], v[178:181], v[46:49]
	v_mfma_f32_16x16x32_bf16 v[42:45], v[154:157], v[178:181], v[42:45]
	v_mfma_f32_16x16x32_bf16 v[30:33], v[146:149], v[170:173], v[30:33]
	v_mfma_f32_16x16x32_bf16 v[26:29], v[154:157], v[170:173], v[26:29]
	v_mfma_f32_16x16x32_bf16 v[14:17], v[146:149], v[162:165], v[14:17]
	v_mfma_f32_16x16x32_bf16 v[10:13], v[154:157], v[162:165], v[10:13]
	v_mfma_f32_16x16x32_bf16 v[62:65], v[150:153], v[190:193], v[62:65]
	v_mfma_f32_16x16x32_bf16 v[58:61], v[158:161], v[190:193], v[58:61]
	v_mfma_f32_16x16x32_bf16 v[46:49], v[150:153], v[182:185], v[46:49]
	v_mfma_f32_16x16x32_bf16 v[42:45], v[158:161], v[182:185], v[42:45]
	v_mfma_f32_16x16x32_bf16 v[30:33], v[150:153], v[174:177], v[30:33]
	v_mfma_f32_16x16x32_bf16 v[26:29], v[158:161], v[174:177], v[26:29]
	v_mfma_f32_16x16x32_bf16 v[14:17], v[150:153], v[166:169], v[14:17]
	v_mfma_f32_16x16x32_bf16 v[10:13], v[158:161], v[166:169], v[10:13]
	v_mfma_f32_16x16x32_bf16 v[54:57], v[130:133], v[186:189], v[54:57]
	v_mfma_f32_16x16x32_bf16 v[50:53], v[138:141], v[186:189], v[50:53]
	v_mfma_f32_16x16x32_bf16 v[38:41], v[130:133], v[178:181], v[38:41]
	v_mfma_f32_16x16x32_bf16 v[34:37], v[138:141], v[178:181], v[34:37]
	v_mfma_f32_16x16x32_bf16 v[22:25], v[130:133], v[170:173], v[22:25]
	v_mfma_f32_16x16x32_bf16 v[18:21], v[138:141], v[170:173], v[18:21]
	v_mfma_f32_16x16x32_bf16 v[6:9], v[130:133], v[162:165], v[6:9]
	v_mfma_f32_16x16x32_bf16 v[2:5], v[138:141], v[162:165], v[2:5]
	v_mfma_f32_16x16x32_bf16 v[54:57], v[134:137], v[190:193], v[54:57]
	v_mfma_f32_16x16x32_bf16 v[50:53], v[142:145], v[190:193], v[50:53]
	v_mfma_f32_16x16x32_bf16 v[38:41], v[134:137], v[182:185], v[38:41]
	v_mfma_f32_16x16x32_bf16 v[34:37], v[142:145], v[182:185], v[34:37]
	v_mfma_f32_16x16x32_bf16 v[22:25], v[134:137], v[174:177], v[22:25]
	v_mfma_f32_16x16x32_bf16 v[18:21], v[142:145], v[174:177], v[18:21]
	v_mfma_f32_16x16x32_bf16 v[6:9], v[134:137], v[166:169], v[6:9]
	v_mfma_f32_16x16x32_bf16 v[2:5], v[142:145], v[166:169], v[2:5]
	s_barrier
	s_setprio 0
	s_add_i32 s26, 0, 0x18000
	s_add_i32 s27, 0, 0x1c000
	v_add_u32_e32 v142, s26, v246
	v_add_u32_e32 v158, s27, v246
	ds_read_b128 v[130:133], v142
	ds_read_b128 v[134:137], v142 offset:1024
	ds_read_b128 v[138:141], v142 offset:2048
	ds_read_b128 v[142:145], v142 offset:3072
	ds_read_b128 v[146:149], v158
	ds_read_b128 v[150:153], v158 offset:1024
	ds_read_b128 v[154:157], v158 offset:2048
	ds_read_b128 v[158:161], v158 offset:3072
	s_add_u32 s24, s24, 0x40000
	s_addc_u32 s25, s25, 0
	s_mov_b32 m0, s50
	v_lshl_add_u64 v[194:195], s[24:25], 0, v[210:211]
	ds_read_b128 v[162:165], v247 offset:32768
	ds_read_b128 v[166:169], v247 offset:33792
	ds_read_b128 v[170:173], v247 offset:34816
	ds_read_b128 v[174:177], v247 offset:35840
	ds_read_b128 v[178:181], v247 offset:36864
	ds_read_b128 v[182:185], v247 offset:37888
	ds_read_b128 v[186:189], v247 offset:38912
	ds_read_b128 v[190:193], v247 offset:39936
	global_load_lds_dwordx4 v[194:195], off
	v_lshl_add_u64 v[194:195], s[24:25], 0, v[214:215]
	s_mov_b32 m0, s51
	s_nop 0
	global_load_lds_dwordx4 v[194:195], off
	s_waitcnt vmcnt(26)
	s_cmp_eq_u32 s100, 0
	s_cbranch_scc1 .Lthird_wait_relaxed_3
	s_waitcnt vmcnt(8)
; #define PG8_STAGE(bufoff, gbase, voff) do { _Pragma("unroll") for (int _i = 0; _i < 2; ++_i) \
;         __builtin_amdgcn_global_load_lds((const unsigned*)((const char*)(gbase) + (voff)[_i]), (PG8_LAS unsigned*)(lds + (bufoff) + ldsw + _i * 8192), 16, 0, 0); } while (0)
; #define PG8_LDA(dst, b, h) do { _Pragma("unroll") for (int m = 0; m < 4; ++m) _Pragma("unroll") for (int k = 0; k < 2; ++k) dst[m][k] = *(const PG8_LAS bf16x8*)(lds + PG8_SA(b, h) + aoff + m * 2048 + k * 1024); } while (0)
; #define PG8_MMA(ai, bj, At, Bt) do { __builtin_amdgcn_s_setprio(1); _Pragma("unroll") for (int m = 0; m < 4; ++m) _Pragma("unroll") for (int n = 0; n < 2; ++n) _Pragma("unroll") for (int k = 0; k < 2; ++k) \
;         acc[ai][bj][m][n] = __builtin_amdgcn_mfma_f32_16x16x32_bf16(Bt[n][k], At[m][k], acc[ai][bj][m][n], 0, 0, 0); __builtin_amdgcn_s_setprio(0); } while (0)
; #define PG8_WAIT_V(n) asm volatile("s_waitcnt vmcnt(" #n ")" ::: "memory")
; #define PG8_WAIT_L(n) asm volatile("s_waitcnt lgkmcnt(" #n ")" ::: "memory")
; #define PG8_BAR __builtin_amdgcn_s_barrier()
; #define PG8_SCHED __builtin_amdgcn_sched_barrier(0)
; template <class Epi, class Sched, bool ALIGN_EPI = false, bool SP2 = false>
; __device__ __forceinline__ void gemm_phase(PG8_LAS unsigned char* lds, const Gemm g, const Sched& S, const Epi& E, const int wave_id) {
;     ...
;             PG8_WAIT_V(8); PG8_WAIT_L(0); PG8_BAR; PG8_MMA(0, 0, At, B0); PG8_MMA(0, 1, At, B1); PG8_BAR; PG8_SCHED;
;             PG8_LDA(At, 1, 1); PG8_STAGE(PG8_SB(1, 0), b3, voffB); PG8_STAGE(PG8_SB(1, 1), b3 + hstep, voffB); PG8_STAGE(PG8_SA(1, 0), a3, voffA);
;             PG8_WAIT_V(8); PG8_WAIT_L(0); PG8_BAR; PG8_MMA(1, 0, At, B0); PG8_MMA(1, 1, At, B1); PG8_BAR; PG8_SCHED;
.Lthird_wait_relaxed_3:
	s_waitcnt lgkmcnt(0)
	s_setprio 1
	s_barrier
	v_mfma_f32_16x16x32_bf16 v[126:129], v[130:133], v[162:165], v[126:129]
	v_mfma_f32_16x16x32_bf16 v[122:125], v[138:141], v[162:165], v[122:125]
	v_mfma_f32_16x16x32_bf16 v[110:113], v[130:133], v[170:173], v[110:113]
	v_mfma_f32_16x16x32_bf16 v[106:109], v[138:141], v[170:173], v[106:109]
	v_mfma_f32_16x16x32_bf16 v[94:97], v[130:133], v[178:181], v[94:97]
	v_mfma_f32_16x16x32_bf16 v[90:93], v[138:141], v[178:181], v[90:93]
	v_mfma_f32_16x16x32_bf16 v[78:81], v[130:133], v[186:189], v[78:81]
	v_mfma_f32_16x16x32_bf16 v[74:77], v[138:141], v[186:189], v[74:77]
	v_mfma_f32_16x16x32_bf16 v[126:129], v[134:137], v[166:169], v[126:129]
	v_mfma_f32_16x16x32_bf16 v[122:125], v[142:145], v[166:169], v[122:125]
	v_mfma_f32_16x16x32_bf16 v[110:113], v[134:137], v[174:177], v[110:113]
	v_mfma_f32_16x16x32_bf16 v[106:109], v[142:145], v[174:177], v[106:109]
	v_mfma_f32_16x16x32_bf16 v[94:97], v[134:137], v[182:185], v[94:97]
	v_mfma_f32_16x16x32_bf16 v[90:93], v[142:145], v[182:185], v[90:93]
	v_mfma_f32_16x16x32_bf16 v[78:81], v[134:137], v[190:193], v[78:81]
	v_mfma_f32_16x16x32_bf16 v[74:77], v[142:145], v[190:193], v[74:77]
	v_mfma_f32_16x16x32_bf16 v[118:121], v[146:149], v[162:165], v[118:121]
	v_mfma_f32_16x16x32_bf16 v[114:117], v[154:157], v[162:165], v[114:117]
	v_mfma_f32_16x16x32_bf16 v[102:105], v[146:149], v[170:173], v[102:105]
	v_mfma_f32_16x16x32_bf16 v[98:101], v[154:157], v[170:173], v[98:101]
	v_mfma_f32_16x16x32_bf16 v[86:89], v[146:149], v[178:181], v[86:89]
	v_mfma_f32_16x16x32_bf16 v[82:85], v[154:157], v[178:181], v[82:85]
	v_mfma_f32_16x16x32_bf16 v[70:73], v[146:149], v[186:189], v[70:73]
	v_mfma_f32_16x16x32_bf16 v[66:69], v[154:157], v[186:189], v[66:69]
	v_mfma_f32_16x16x32_bf16 v[118:121], v[150:153], v[166:169], v[118:121]
	v_mfma_f32_16x16x32_bf16 v[114:117], v[158:161], v[166:169], v[114:117]
	v_mfma_f32_16x16x32_bf16 v[102:105], v[150:153], v[174:177], v[102:105]
	v_mfma_f32_16x16x32_bf16 v[98:101], v[158:161], v[174:177], v[98:101]
	v_mfma_f32_16x16x32_bf16 v[86:89], v[150:153], v[182:185], v[86:89]
	v_mfma_f32_16x16x32_bf16 v[82:85], v[158:161], v[182:185], v[82:85]
	v_mfma_f32_16x16x32_bf16 v[70:73], v[150:153], v[190:193], v[70:73]
	v_mfma_f32_16x16x32_bf16 v[66:69], v[158:161], v[190:193], v[66:69]
	s_barrier
	s_setprio 0
	s_add_i32 s24, s26, s38
	v_lshl_add_u64 v[194:195], v[232:233], 0, s[64:65]
	s_mov_b32 m0, s24
	ds_read_b128 v[162:165], v247 offset:49152
	ds_read_b128 v[166:169], v247 offset:50176
	ds_read_b128 v[170:173], v247 offset:51200
	ds_read_b128 v[174:177], v247 offset:52224
	ds_read_b128 v[178:181], v247 offset:53248
	ds_read_b128 v[182:185], v247 offset:54272
	ds_read_b128 v[186:189], v247 offset:55296
	ds_read_b128 v[190:193], v247 offset:56320
	global_load_lds_dwordx4 v[194:195], off
	s_add_i32 m0, s24, 0x2000
	s_add_u32 s22, s22, 0x40080
	v_lshl_add_u64 v[194:195], v[230:231], 0, s[64:65]
	s_addc_u32 s23, s23, 0
	s_add_i32 s24, s27, s38
	global_load_lds_dwordx4 v[194:195], off
	v_lshl_add_u64 v[194:195], s[22:23], 0, v[212:213]
	s_mov_b32 m0, s24
	s_nop 0
	global_load_lds_dwordx4 v[194:195], off
	v_lshl_add_u64 v[194:195], s[22:23], 0, v[216:217]
	s_add_i32 m0, s24, 0x2000
	s_nop 0
	global_load_lds_dwordx4 v[194:195], off
	v_lshl_add_u64 v[194:195], v[226:227], 0, s[64:65]
	s_mov_b32 m0, s54
	s_nop 0
	global_load_lds_dwordx4 v[194:195], off
	v_lshl_add_u64 v[194:195], v[228:229], 0, s[64:65]
	s_mov_b32 m0, s56
	s_nop 0
	global_load_lds_dwordx4 v[194:195], off
	s_waitcnt vmcnt(8)
	s_waitcnt lgkmcnt(0)
	s_setprio 1
	s_barrier
	v_mfma_f32_16x16x32_bf16 v[62:65], v[130:133], v[162:165], v[62:65]
	v_mfma_f32_16x16x32_bf16 v[58:61], v[138:141], v[162:165], v[58:61]
	v_mfma_f32_16x16x32_bf16 v[46:49], v[130:133], v[170:173], v[46:49]
	v_mfma_f32_16x16x32_bf16 v[42:45], v[138:141], v[170:173], v[42:45]
	v_mfma_f32_16x16x32_bf16 v[30:33], v[130:133], v[178:181], v[30:33]
	v_mfma_f32_16x16x32_bf16 v[26:29], v[138:141], v[178:181], v[26:29]
	v_mfma_f32_16x16x32_bf16 v[14:17], v[130:133], v[186:189], v[14:17]
	v_mfma_f32_16x16x32_bf16 v[10:13], v[138:141], v[186:189], v[10:13]
	v_mfma_f32_16x16x32_bf16 v[62:65], v[134:137], v[166:169], v[62:65]
	v_mfma_f32_16x16x32_bf16 v[58:61], v[142:145], v[166:169], v[58:61]
	v_mfma_f32_16x16x32_bf16 v[46:49], v[134:137], v[174:177], v[46:49]
	v_mfma_f32_16x16x32_bf16 v[42:45], v[142:145], v[174:177], v[42:45]
	v_mfma_f32_16x16x32_bf16 v[30:33], v[134:137], v[182:185], v[30:33]
	v_mfma_f32_16x16x32_bf16 v[26:29], v[142:145], v[182:185], v[26:29]
	v_mfma_f32_16x16x32_bf16 v[14:17], v[134:137], v[190:193], v[14:17]
	v_mfma_f32_16x16x32_bf16 v[10:13], v[142:145], v[190:193], v[10:13]
	v_mfma_f32_16x16x32_bf16 v[54:57], v[146:149], v[162:165], v[54:57]
	v_mfma_f32_16x16x32_bf16 v[50:53], v[154:157], v[162:165], v[50:53]
	v_mfma_f32_16x16x32_bf16 v[38:41], v[146:149], v[170:173], v[38:41]
	v_mfma_f32_16x16x32_bf16 v[34:37], v[154:157], v[170:173], v[34:37]
	v_mfma_f32_16x16x32_bf16 v[22:25], v[146:149], v[178:181], v[22:25]
	v_mfma_f32_16x16x32_bf16 v[18:21], v[154:157], v[178:181], v[18:21]
	v_mfma_f32_16x16x32_bf16 v[6:9], v[146:149], v[186:189], v[6:9]
	v_mfma_f32_16x16x32_bf16 v[2:5], v[154:157], v[186:189], v[2:5]
	v_mfma_f32_16x16x32_bf16 v[54:57], v[150:153], v[166:169], v[54:57]
	v_mfma_f32_16x16x32_bf16 v[50:53], v[158:161], v[166:169], v[50:53]
	v_mfma_f32_16x16x32_bf16 v[38:41], v[150:153], v[174:177], v[38:41]
	v_mfma_f32_16x16x32_bf16 v[34:37], v[158:161], v[174:177], v[34:37]
	v_mfma_f32_16x16x32_bf16 v[22:25], v[150:153], v[182:185], v[22:25]
	v_mfma_f32_16x16x32_bf16 v[18:21], v[158:161], v[182:185], v[18:21]
	v_mfma_f32_16x16x32_bf16 v[6:9], v[150:153], v[190:193], v[6:9]
	v_mfma_f32_16x16x32_bf16 v[2:5], v[158:161], v[190:193], v[2:5]
	s_barrier
	s_setprio 0
	s_add_i32 s74, s74, 2
	s_add_u32 s20, s20, 0x100
	s_addc_u32 s21, s21, 0
	s_cmp_gt_u32 s74, 13
	s_cbranch_scc1 .LBB0_1826

; #define PG8_STAGE(bufoff, gbase, voff) do { _Pragma("unroll") for (int _i = 0; _i < 2; ++_i) \
;         __builtin_amdgcn_global_load_lds((const unsigned*)((const char*)(gbase) + (voff)[_i]), (PG8_LAS unsigned*)(lds + (bufoff) + ldsw + _i * 8192), 16, 0, 0); } while (0)
; #define PG8_LDA(dst, b, h) do { _Pragma("unroll") for (int m = 0; m < 4; ++m) _Pragma("unroll") for (int k = 0; k < 2; ++k) dst[m][k] = *(const PG8_LAS bf16x8*)(lds + PG8_SA(b, h) + aoff + m * 2048 + k * 1024); } while (0)
; #define PG8_LDB(dst, b, h) do { _Pragma("unroll") for (int n = 0; n < 2; ++n) _Pragma("unroll") for (int k = 0; k < 2; ++k) dst[n][k] = *(const PG8_LAS bf16x8*)(lds + PG8_SB(b, h) + boff + n * 2048 + k * 1024); } while (0)
; #define PG8_WAIT_V(n) asm volatile("s_waitcnt vmcnt(" #n ")" ::: "memory")
; #define PG8_WAIT_VN(n) asm volatile("s_waitcnt vmcnt(%0)" :: "n"(n) : "memory")
; #define PG8_WAIT_L(n) asm volatile("s_waitcnt lgkmcnt(" #n ")" ::: "memory")
; #define PG8_BAR __builtin_amdgcn_s_barrier()
; #define PG8_SCHED __builtin_amdgcn_sched_barrier(0)
; template <class Epi, class Sched, bool ALIGN_EPI = false, bool SP2 = false>
; __device__ __forceinline__ void gemm_phase(PG8_LAS unsigned char* lds, const Gemm g, const Sched& S, const Epi& E, const int wave_id) {
;     ...
;             const char* a1 = cA + (size_t)(t + 1) * kstep;
;             const char* a2 = last ? nA : cA + (size_t)(t + 2) * kstep; const char* b2 = last ? nB : cB + (size_t)(t + 2) * kstep;
;             const char* a3 = a2 + kstep; const char* b3 = b2 + kstep;
;             if (last && has_next) S.a_ready(nxt);
;             if constexpr (SP2) {
;             int tz_ = __builtin_amdgcn_readfirstlane(t | (ui > 0 ? 0 : 1)); asm volatile("" : "+s"(tz_));
;             const bool strict = !(Epi::NS > 0 && tz_ == 0);
;             PG8_LDB(B0, 0, 0); PG8_LDB(B1, 0, 1); PG8_SCHED; PG8_LDA(At, 0, 0); PG8_STAGE(PG8_SA(1, 1), a1 + hstep, voffA);
;             PG8_WAIT_VN(8 + Epi::NS); if (strict) PG8_WAIT_V(8); PG8_WAIT_L(0); PG8_BAR; PG8_MMA(0, 0, At, B0); PG8_MMA(0, 1, At, B1); PG8_BAR; PG8_SCHED;
;             PG8_LDA(At, 0, 1); PG8_STAGE(PG8_SB(0, 0), b2, voffB); PG8_STAGE(PG8_SB(0, 1), b2 + hstep, voffB); PG8_STAGE(PG8_SA(0, 0), a2, voffA);
;             PG8_WAIT_VN(8 + Epi::NS); if (strict) PG8_WAIT_V(8); PG8_WAIT_L(0); PG8_BAR; PG8_MMA(1, 0, At, B0); PG8_MMA(1, 1, At, B1); PG8_BAR; PG8_SCHED;
.LBB0_1824:
	s_add_u32 s22, s18, s20
	s_addc_u32 s23, s19, s21
	s_add_u32 s22, s22, 0x100
	s_addc_u32 s23, s23, 0
	s_add_u32 s53, s68, s20
	s_addc_u32 s75, s69, s21
	s_cmpk_eq_i32 s20, 0x700
	s_cselect_b32 s25, s11, s23
	s_cselect_b32 s24, s63, s22
	s_cselect_b32 s23, s9, s75
	s_cselect_b32 s22, s67, s53
	s_waitcnt lgkmcnt(0)
	s_setprio 1
	s_barrier
	v_mfma_f32_16x16x32_bf16 v[126:129], v[146:149], v[186:189], v[126:129]
	v_mfma_f32_16x16x32_bf16 v[122:125], v[154:157], v[186:189], v[122:125]
	v_mfma_f32_16x16x32_bf16 v[110:113], v[146:149], v[178:181], v[110:113]
	v_mfma_f32_16x16x32_bf16 v[106:109], v[154:157], v[178:181], v[106:109]
	v_mfma_f32_16x16x32_bf16 v[94:97], v[146:149], v[170:173], v[94:97]
	v_mfma_f32_16x16x32_bf16 v[90:93], v[154:157], v[170:173], v[90:93]
	v_mfma_f32_16x16x32_bf16 v[78:81], v[146:149], v[162:165], v[78:81]
	v_mfma_f32_16x16x32_bf16 v[74:77], v[154:157], v[162:165], v[74:77]
	v_mfma_f32_16x16x32_bf16 v[126:129], v[150:153], v[190:193], v[126:129]
	v_mfma_f32_16x16x32_bf16 v[122:125], v[158:161], v[190:193], v[122:125]
	v_mfma_f32_16x16x32_bf16 v[110:113], v[150:153], v[182:185], v[110:113]
	v_mfma_f32_16x16x32_bf16 v[106:109], v[158:161], v[182:185], v[106:109]
	v_mfma_f32_16x16x32_bf16 v[94:97], v[150:153], v[174:177], v[94:97]
	v_mfma_f32_16x16x32_bf16 v[90:93], v[158:161], v[174:177], v[90:93]
	v_mfma_f32_16x16x32_bf16 v[78:81], v[150:153], v[166:169], v[78:81]
	v_mfma_f32_16x16x32_bf16 v[74:77], v[158:161], v[166:169], v[74:77]
	v_mfma_f32_16x16x32_bf16 v[118:121], v[130:133], v[186:189], v[118:121]
	v_mfma_f32_16x16x32_bf16 v[114:117], v[138:141], v[186:189], v[114:117]
	v_mfma_f32_16x16x32_bf16 v[102:105], v[130:133], v[178:181], v[102:105]
	v_mfma_f32_16x16x32_bf16 v[98:101], v[138:141], v[178:181], v[98:101]
	v_mfma_f32_16x16x32_bf16 v[86:89], v[130:133], v[170:173], v[86:89]
	v_mfma_f32_16x16x32_bf16 v[82:85], v[138:141], v[170:173], v[82:85]
	v_mfma_f32_16x16x32_bf16 v[70:73], v[130:133], v[162:165], v[70:73]
	v_mfma_f32_16x16x32_bf16 v[66:69], v[138:141], v[162:165], v[66:69]
	v_mfma_f32_16x16x32_bf16 v[118:121], v[134:137], v[190:193], v[118:121]
	v_mfma_f32_16x16x32_bf16 v[114:117], v[142:145], v[190:193], v[114:117]
	v_mfma_f32_16x16x32_bf16 v[102:105], v[134:137], v[182:185], v[102:105]
	v_mfma_f32_16x16x32_bf16 v[98:101], v[142:145], v[182:185], v[98:101]
	v_mfma_f32_16x16x32_bf16 v[86:89], v[134:137], v[174:177], v[86:89]
	v_mfma_f32_16x16x32_bf16 v[82:85], v[142:145], v[174:177], v[82:85]
	v_mfma_f32_16x16x32_bf16 v[70:73], v[134:137], v[166:169], v[70:73]
	v_mfma_f32_16x16x32_bf16 v[66:69], v[142:145], v[166:169], v[66:69]
	s_barrier
	s_setprio 0
	s_mov_b32 m0, s40
	v_lshl_add_u64 v[232:233], s[22:23], 0, v[212:213]
	s_add_u32 s90, s22, 0x40000
	ds_read_b128 v[186:189], v247 offset:16384
	ds_read_b128 v[190:193], v247 offset:17408
	ds_read_b128 v[178:181], v247 offset:18432
	ds_read_b128 v[182:185], v247 offset:19456
	ds_read_b128 v[170:173], v247 offset:20480
	ds_read_b128 v[174:177], v247 offset:21504
	ds_read_b128 v[162:165], v247 offset:22528
	ds_read_b128 v[166:169], v247 offset:23552
	global_load_lds_dwordx4 v[232:233], off
	v_lshl_add_u64 v[230:231], s[22:23], 0, v[216:217]
	s_mov_b32 m0, s41
	s_addc_u32 s91, s23, 0
	global_load_lds_dwordx4 v[230:231], off
	v_lshl_add_u64 v[194:195], s[90:91], 0, v[212:213]
	s_mov_b32 m0, s42
	v_lshl_add_u64 v[226:227], s[24:25], 0, v[210:211]
	global_load_lds_dwordx4 v[194:195], off
	v_lshl_add_u64 v[194:195], s[90:91], 0, v[216:217]
	s_mov_b32 m0, s43
	v_lshl_add_u64 v[228:229], s[24:25], 0, v[214:215]
	global_load_lds_dwordx4 v[194:195], off
	s_mov_b32 m0, s39
	s_andn2_b64 vcc, exec, s[26:27]
	global_load_lds_dwordx4 v[226:227], off
	s_mov_b32 m0, s49
	s_nop 0
	global_load_lds_dwordx4 v[228:229], off
	s_waitcnt vmcnt(24)
	s_cbranch_vccnz .LBB0_1821
	s_waitcnt vmcnt(8)
	s_branch .LBB0_1821

; #define PG8_STAGE(bufoff, gbase, voff) do { _Pragma("unroll") for (int _i = 0; _i < 2; ++_i) \
;         __builtin_amdgcn_global_load_lds((const unsigned*)((const char*)(gbase) + (voff)[_i]), (PG8_LAS unsigned*)(lds + (bufoff) + ldsw + _i * 8192), 16, 0, 0); } while (0)
; #define PG8_LDA(dst, b, h) do { _Pragma("unroll") for (int m = 0; m < 4; ++m) _Pragma("unroll") for (int k = 0; k < 2; ++k) dst[m][k] = *(const PG8_LAS bf16x8*)(lds + PG8_SA(b, h) + aoff + m * 2048 + k * 1024); } while (0)
; #define PG8_LDB(dst, b, h) do { _Pragma("unroll") for (int n = 0; n < 2; ++n) _Pragma("unroll") for (int k = 0; k < 2; ++k) dst[n][k] = *(const PG8_LAS bf16x8*)(lds + PG8_SB(b, h) + boff + n * 2048 + k * 1024); } while (0)
; #define PG8_MMA(ai, bj, At, Bt) do { __builtin_amdgcn_s_setprio(1); _Pragma("unroll") for (int m = 0; m < 4; ++m) _Pragma("unroll") for (int n = 0; n < 2; ++n) _Pragma("unroll") for (int k = 0; k < 2; ++k) \
;         acc[ai][bj][m][n] = __builtin_amdgcn_mfma_f32_16x16x32_bf16(Bt[n][k], At[m][k], acc[ai][bj][m][n], 0, 0, 0); __builtin_amdgcn_s_setprio(0); } while (0)
; #define PG8_WAIT_V(n) asm volatile("s_waitcnt vmcnt(" #n ")" ::: "memory")
; #define PG8_WAIT_VN(n) asm volatile("s_waitcnt vmcnt(%0)" :: "n"(n) : "memory")
; #define PG8_WAIT_L(n) asm volatile("s_waitcnt lgkmcnt(" #n ")" ::: "memory")
; #define PG8_BAR __builtin_amdgcn_s_barrier()
; #define PG8_SCHED __builtin_amdgcn_sched_barrier(0)
; template <class Epi, class Sched, bool ALIGN_EPI = false, bool SP2 = false>
; __device__ __forceinline__ void gemm_phase(PG8_LAS unsigned char* lds, const Gemm g, const Sched& S, const Epi& E, const int wave_id) {
;     ...
;             PG8_WAIT_VN(8 + Epi::NS); if (strict) PG8_WAIT_V(8); PG8_WAIT_L(0); PG8_BAR; PG8_MMA(1, 0, At, B0); PG8_MMA(1, 1, At, B1); PG8_BAR; PG8_SCHED;
;             PG8_LDB(B0, 1, 0); PG8_LDB(B1, 1, 1); PG8_SCHED; PG8_LDA(At, 1, 0); PG8_STAGE(PG8_SA(0, 1), a2 + hstep, voffA);
;             PG8_WAIT_V(8); PG8_WAIT_L(0); PG8_BAR; PG8_MMA(0, 0, At, B0); PG8_MMA(0, 1, At, B1); PG8_BAR; PG8_SCHED;
.LBB0_1889:
	s_waitcnt lgkmcnt(0)
	s_setprio 1
	s_barrier
	v_mfma_f32_16x16x32_bf16 v[62:65], v[146:149], v[186:189], v[62:65]
	v_mfma_f32_16x16x32_bf16 v[58:61], v[154:157], v[186:189], v[58:61]
	v_mfma_f32_16x16x32_bf16 v[54:57], v[146:149], v[178:181], v[54:57]
	v_mfma_f32_16x16x32_bf16 v[50:53], v[154:157], v[178:181], v[50:53]
	v_mfma_f32_16x16x32_bf16 v[30:33], v[146:149], v[170:173], v[30:33]
	v_mfma_f32_16x16x32_bf16 v[26:29], v[154:157], v[170:173], v[26:29]
	v_mfma_f32_16x16x32_bf16 v[22:25], v[146:149], v[162:165], v[22:25]
	v_mfma_f32_16x16x32_bf16 v[18:21], v[154:157], v[162:165], v[18:21]
	v_mfma_f32_16x16x32_bf16 v[62:65], v[150:153], v[190:193], v[62:65]
	v_mfma_f32_16x16x32_bf16 v[58:61], v[158:161], v[190:193], v[58:61]
	v_mfma_f32_16x16x32_bf16 v[54:57], v[150:153], v[182:185], v[54:57]
	v_mfma_f32_16x16x32_bf16 v[50:53], v[158:161], v[182:185], v[50:53]
	v_mfma_f32_16x16x32_bf16 v[30:33], v[150:153], v[174:177], v[30:33]
	v_mfma_f32_16x16x32_bf16 v[26:29], v[158:161], v[174:177], v[26:29]
	v_mfma_f32_16x16x32_bf16 v[22:25], v[150:153], v[166:169], v[22:25]
	v_mfma_f32_16x16x32_bf16 v[18:21], v[158:161], v[166:169], v[18:21]
	v_mfma_f32_16x16x32_bf16 v[46:49], v[130:133], v[186:189], v[46:49]
	v_mfma_f32_16x16x32_bf16 v[42:45], v[138:141], v[186:189], v[42:45]
	v_mfma_f32_16x16x32_bf16 v[38:41], v[130:133], v[178:181], v[38:41]
	v_mfma_f32_16x16x32_bf16 v[34:37], v[138:141], v[178:181], v[34:37]
	v_mfma_f32_16x16x32_bf16 v[14:17], v[130:133], v[170:173], v[14:17]
	v_mfma_f32_16x16x32_bf16 v[10:13], v[138:141], v[170:173], v[10:13]
	v_mfma_f32_16x16x32_bf16 v[6:9], v[130:133], v[162:165], v[6:9]
	v_mfma_f32_16x16x32_bf16 v[2:5], v[138:141], v[162:165], v[2:5]
	v_mfma_f32_16x16x32_bf16 v[46:49], v[134:137], v[190:193], v[46:49]
	v_mfma_f32_16x16x32_bf16 v[42:45], v[142:145], v[190:193], v[42:45]
	v_mfma_f32_16x16x32_bf16 v[38:41], v[134:137], v[182:185], v[38:41]
	v_mfma_f32_16x16x32_bf16 v[34:37], v[142:145], v[182:185], v[34:37]
	v_mfma_f32_16x16x32_bf16 v[14:17], v[134:137], v[174:177], v[14:17]
	v_mfma_f32_16x16x32_bf16 v[10:13], v[142:145], v[174:177], v[10:13]
	v_mfma_f32_16x16x32_bf16 v[6:9], v[134:137], v[166:169], v[6:9]
	v_mfma_f32_16x16x32_bf16 v[2:5], v[142:145], v[166:169], v[2:5]
	s_barrier
	s_setprio 0
	s_add_i32 s16, 0, 0x18000
	s_add_i32 s17, 0, 0x1c000
	v_add_u32_e32 v142, s16, v231
	v_add_u32_e32 v158, s17, v231
	ds_read_b128 v[130:133], v142
	ds_read_b128 v[134:137], v142 offset:1024
	ds_read_b128 v[138:141], v142 offset:2048
	ds_read_b128 v[142:145], v142 offset:3072
	ds_read_b128 v[146:149], v158
	ds_read_b128 v[150:153], v158 offset:1024
	ds_read_b128 v[154:157], v158 offset:2048
	ds_read_b128 v[158:161], v158 offset:3072
	s_add_u32 s14, s14, 0x40000
	s_addc_u32 s15, s15, 0
	s_mov_b32 m0, s28
	v_lshl_add_u64 v[194:195], s[14:15], 0, v[210:211]
	ds_read_b128 v[162:165], v232 offset:32768
	ds_read_b128 v[166:169], v232 offset:33792
	ds_read_b128 v[170:173], v232 offset:34816
	ds_read_b128 v[174:177], v232 offset:35840
	ds_read_b128 v[178:181], v232 offset:36864
	ds_read_b128 v[182:185], v232 offset:37888
	ds_read_b128 v[186:189], v232 offset:38912
	ds_read_b128 v[190:193], v232 offset:39936
	global_load_lds_dwordx4 v[194:195], off
	v_lshl_add_u64 v[194:195], s[14:15], 0, v[214:215]
	s_mov_b32 m0, s29
	s_nop 0
	global_load_lds_dwordx4 v[194:195], off
	s_waitcnt vmcnt(8)
	s_waitcnt lgkmcnt(0)
	s_setprio 1
	s_barrier
	v_mfma_f32_16x16x32_bf16 v[126:129], v[130:133], v[162:165], v[126:129]
	v_mfma_f32_16x16x32_bf16 v[122:125], v[138:141], v[162:165], v[122:125]
	v_mfma_f32_16x16x32_bf16 v[118:121], v[130:133], v[170:173], v[118:121]
	v_mfma_f32_16x16x32_bf16 v[114:117], v[138:141], v[170:173], v[114:117]
	v_mfma_f32_16x16x32_bf16 v[94:97], v[130:133], v[178:181], v[94:97]
	v_mfma_f32_16x16x32_bf16 v[90:93], v[138:141], v[178:181], v[90:93]
	v_mfma_f32_16x16x32_bf16 v[86:89], v[130:133], v[186:189], v[86:89]
	v_mfma_f32_16x16x32_bf16 v[82:85], v[138:141], v[186:189], v[82:85]
	v_mfma_f32_16x16x32_bf16 v[126:129], v[134:137], v[166:169], v[126:129]
	v_mfma_f32_16x16x32_bf16 v[122:125], v[142:145], v[166:169], v[122:125]
	v_mfma_f32_16x16x32_bf16 v[118:121], v[134:137], v[174:177], v[118:121]
	v_mfma_f32_16x16x32_bf16 v[114:117], v[142:145], v[174:177], v[114:117]
	v_mfma_f32_16x16x32_bf16 v[94:97], v[134:137], v[182:185], v[94:97]
	v_mfma_f32_16x16x32_bf16 v[90:93], v[142:145], v[182:185], v[90:93]
	v_mfma_f32_16x16x32_bf16 v[86:89], v[134:137], v[190:193], v[86:89]
	v_mfma_f32_16x16x32_bf16 v[82:85], v[142:145], v[190:193], v[82:85]
	v_mfma_f32_16x16x32_bf16 v[110:113], v[146:149], v[162:165], v[110:113]
	v_mfma_f32_16x16x32_bf16 v[106:109], v[154:157], v[162:165], v[106:109]
	v_mfma_f32_16x16x32_bf16 v[102:105], v[146:149], v[170:173], v[102:105]
	v_mfma_f32_16x16x32_bf16 v[98:101], v[154:157], v[170:173], v[98:101]
	v_mfma_f32_16x16x32_bf16 v[78:81], v[146:149], v[178:181], v[78:81]
	v_mfma_f32_16x16x32_bf16 v[74:77], v[154:157], v[178:181], v[74:77]
	v_mfma_f32_16x16x32_bf16 v[70:73], v[146:149], v[186:189], v[70:73]
	v_mfma_f32_16x16x32_bf16 v[66:69], v[154:157], v[186:189], v[66:69]
	v_mfma_f32_16x16x32_bf16 v[110:113], v[150:153], v[166:169], v[110:113]
	v_mfma_f32_16x16x32_bf16 v[106:109], v[158:161], v[166:169], v[106:109]
	v_mfma_f32_16x16x32_bf16 v[102:105], v[150:153], v[174:177], v[102:105]
	v_mfma_f32_16x16x32_bf16 v[98:101], v[158:161], v[174:177], v[98:101]
	v_mfma_f32_16x16x32_bf16 v[78:81], v[150:153], v[182:185], v[78:81]
	v_mfma_f32_16x16x32_bf16 v[74:77], v[158:161], v[182:185], v[74:77]
	v_mfma_f32_16x16x32_bf16 v[70:73], v[150:153], v[190:193], v[70:73]
	v_mfma_f32_16x16x32_bf16 v[66:69], v[158:161], v[190:193], v[66:69]
	s_barrier
; #define PG8_STAGE(bufoff, gbase, voff) do { _Pragma("unroll") for (int _i = 0; _i < 2; ++_i) \
;         __builtin_amdgcn_global_load_lds((const unsigned*)((const char*)(gbase) + (voff)[_i]), (PG8_LAS unsigned*)(lds + (bufoff) + ldsw + _i * 8192), 16, 0, 0); } while (0)
; #define PG8_LDA(dst, b, h) do { _Pragma("unroll") for (int m = 0; m < 4; ++m) _Pragma("unroll") for (int k = 0; k < 2; ++k) dst[m][k] = *(const PG8_LAS bf16x8*)(lds + PG8_SA(b, h) + aoff + m * 2048 + k * 1024); } while (0)
; #define PG8_MMA(ai, bj, At, Bt) do { __builtin_amdgcn_s_setprio(1); _Pragma("unroll") for (int m = 0; m < 4; ++m) _Pragma("unroll") for (int n = 0; n < 2; ++n) _Pragma("unroll") for (int k = 0; k < 2; ++k) \
;         acc[ai][bj][m][n] = __builtin_amdgcn_mfma_f32_16x16x32_bf16(Bt[n][k], At[m][k], acc[ai][bj][m][n], 0, 0, 0); __builtin_amdgcn_s_setprio(0); } while (0)
; #define PG8_WAIT_V(n) asm volatile("s_waitcnt vmcnt(" #n ")" ::: "memory")
; #define PG8_WAIT_L(n) asm volatile("s_waitcnt lgkmcnt(" #n ")" ::: "memory")
; #define PG8_BAR __builtin_amdgcn_s_barrier()
; #define PG8_SCHED __builtin_amdgcn_sched_barrier(0)
; template <class Epi, class Sched, bool ALIGN_EPI = false, bool SP2 = false>
; __device__ __forceinline__ void gemm_phase(PG8_LAS unsigned char* lds, const Gemm g, const Sched& S, const Epi& E, const int wave_id) {
;     ...
;             PG8_LDA(At, 1, 1); PG8_STAGE(PG8_SB(1, 0), b3, voffB); PG8_STAGE(PG8_SB(1, 1), b3 + hstep, voffB); PG8_STAGE(PG8_SA(1, 0), a3, voffA);
;             PG8_WAIT_V(8); PG8_WAIT_L(0); PG8_BAR; PG8_MMA(1, 0, At, B0); PG8_MMA(1, 1, At, B1); PG8_BAR; PG8_SCHED;
	s_setprio 0
	s_add_i32 s14, s16, s21
	v_lshl_add_u64 v[194:195], v[228:229], 0, s[64:65]
	s_mov_b32 m0, s14
	ds_read_b128 v[162:165], v232 offset:49152
	ds_read_b128 v[166:169], v232 offset:50176
	ds_read_b128 v[170:173], v232 offset:51200
	ds_read_b128 v[174:177], v232 offset:52224
	ds_read_b128 v[178:181], v232 offset:53248
	ds_read_b128 v[182:185], v232 offset:54272
	ds_read_b128 v[186:189], v232 offset:55296
	ds_read_b128 v[190:193], v232 offset:56320
	global_load_lds_dwordx4 v[194:195], off
	s_add_i32 m0, s14, 0x2000
	s_add_u32 s12, s12, 0x40080
	v_lshl_add_u64 v[194:195], v[226:227], 0, s[64:65]
	s_addc_u32 s13, s13, 0
	s_add_i32 s14, s17, s21
	global_load_lds_dwordx4 v[194:195], off
	v_lshl_add_u64 v[194:195], s[12:13], 0, v[212:213]
	s_mov_b32 m0, s14
	s_nop 0
	global_load_lds_dwordx4 v[194:195], off
	v_lshl_add_u64 v[194:195], s[12:13], 0, v[216:217]
	s_add_i32 m0, s14, 0x2000
	s_nop 0
	global_load_lds_dwordx4 v[194:195], off
	v_lshl_add_u64 v[194:195], v[222:223], 0, s[64:65]
	s_mov_b32 m0, s30
	s_nop 0
	global_load_lds_dwordx4 v[194:195], off
	v_lshl_add_u64 v[194:195], v[224:225], 0, s[64:65]
	s_mov_b32 m0, s31
	s_nop 0
	global_load_lds_dwordx4 v[194:195], off
	s_waitcnt vmcnt(8)
	s_waitcnt lgkmcnt(0)
	s_setprio 1
	s_barrier
	v_mfma_f32_16x16x32_bf16 v[62:65], v[130:133], v[162:165], v[62:65]
	v_mfma_f32_16x16x32_bf16 v[58:61], v[138:141], v[162:165], v[58:61]
	v_mfma_f32_16x16x32_bf16 v[54:57], v[130:133], v[170:173], v[54:57]
	v_mfma_f32_16x16x32_bf16 v[50:53], v[138:141], v[170:173], v[50:53]
	v_mfma_f32_16x16x32_bf16 v[30:33], v[130:133], v[178:181], v[30:33]
	v_mfma_f32_16x16x32_bf16 v[26:29], v[138:141], v[178:181], v[26:29]
	v_mfma_f32_16x16x32_bf16 v[22:25], v[130:133], v[186:189], v[22:25]
	v_mfma_f32_16x16x32_bf16 v[18:21], v[138:141], v[186:189], v[18:21]
	v_mfma_f32_16x16x32_bf16 v[62:65], v[134:137], v[166:169], v[62:65]
	v_mfma_f32_16x16x32_bf16 v[58:61], v[142:145], v[166:169], v[58:61]
	v_mfma_f32_16x16x32_bf16 v[54:57], v[134:137], v[174:177], v[54:57]
	v_mfma_f32_16x16x32_bf16 v[50:53], v[142:145], v[174:177], v[50:53]
	v_mfma_f32_16x16x32_bf16 v[30:33], v[134:137], v[182:185], v[30:33]
	v_mfma_f32_16x16x32_bf16 v[26:29], v[142:145], v[182:185], v[26:29]
	v_mfma_f32_16x16x32_bf16 v[22:25], v[134:137], v[190:193], v[22:25]
	v_mfma_f32_16x16x32_bf16 v[18:21], v[142:145], v[190:193], v[18:21]
	v_mfma_f32_16x16x32_bf16 v[46:49], v[146:149], v[162:165], v[46:49]
	v_mfma_f32_16x16x32_bf16 v[42:45], v[154:157], v[162:165], v[42:45]
	v_mfma_f32_16x16x32_bf16 v[38:41], v[146:149], v[170:173], v[38:41]
	v_mfma_f32_16x16x32_bf16 v[34:37], v[154:157], v[170:173], v[34:37]
	v_mfma_f32_16x16x32_bf16 v[14:17], v[146:149], v[178:181], v[14:17]
	v_mfma_f32_16x16x32_bf16 v[10:13], v[154:157], v[178:181], v[10:13]
	v_mfma_f32_16x16x32_bf16 v[6:9], v[146:149], v[186:189], v[6:9]
	v_mfma_f32_16x16x32_bf16 v[2:5], v[154:157], v[186:189], v[2:5]
	v_mfma_f32_16x16x32_bf16 v[46:49], v[150:153], v[166:169], v[46:49]
	v_mfma_f32_16x16x32_bf16 v[42:45], v[158:161], v[166:169], v[42:45]
	v_mfma_f32_16x16x32_bf16 v[38:41], v[150:153], v[174:177], v[38:41]
	v_mfma_f32_16x16x32_bf16 v[34:37], v[158:161], v[174:177], v[34:37]
	v_mfma_f32_16x16x32_bf16 v[14:17], v[150:153], v[182:185], v[14:17]
	v_mfma_f32_16x16x32_bf16 v[10:13], v[158:161], v[182:185], v[10:13]
	v_mfma_f32_16x16x32_bf16 v[6:9], v[150:153], v[190:193], v[6:9]
	v_mfma_f32_16x16x32_bf16 v[2:5], v[158:161], v[190:193], v[2:5]
	s_barrier
	s_setprio 0
	s_add_u32 s10, s10, 0x100
	s_addc_u32 s11, s11, 0
	s_cmp_gt_u32 s38, 13
	v_readlane_b32 s40, v254, 55
	s_cbranch_scc1 .LBB0_1894

; #define PG8_STAGE(bufoff, gbase, voff) do { _Pragma("unroll") for (int _i = 0; _i < 2; ++_i) \
;         __builtin_amdgcn_global_load_lds((const unsigned*)((const char*)(gbase) + (voff)[_i]), (PG8_LAS unsigned*)(lds + (bufoff) + ldsw + _i * 8192), 16, 0, 0); } while (0)
; #define PG8_LDA(dst, b, h) do { _Pragma("unroll") for (int m = 0; m < 4; ++m) _Pragma("unroll") for (int k = 0; k < 2; ++k) dst[m][k] = *(const PG8_LAS bf16x8*)(lds + PG8_SA(b, h) + aoff + m * 2048 + k * 1024); } while (0)
; #define PG8_LDB(dst, b, h) do { _Pragma("unroll") for (int n = 0; n < 2; ++n) _Pragma("unroll") for (int k = 0; k < 2; ++k) dst[n][k] = *(const PG8_LAS bf16x8*)(lds + PG8_SB(b, h) + boff + n * 2048 + k * 1024); } while (0)
; #define PG8_WAIT_V(n) asm volatile("s_waitcnt vmcnt(" #n ")" ::: "memory")
; #define PG8_WAIT_VN(n) asm volatile("s_waitcnt vmcnt(%0)" :: "n"(n) : "memory")
; #define PG8_WAIT_L(n) asm volatile("s_waitcnt lgkmcnt(" #n ")" ::: "memory")
; #define PG8_BAR __builtin_amdgcn_s_barrier()
; #define PG8_SCHED __builtin_amdgcn_sched_barrier(0)
; template <class Epi, class Sched, bool ALIGN_EPI = false, bool SP2 = false>
; __device__ __forceinline__ void gemm_phase(PG8_LAS unsigned char* lds, const Gemm g, const Sched& S, const Epi& E, const int wave_id) {
;     ...
;             const char* a1 = cA + (size_t)(t + 1) * kstep;
;             const char* a2 = last ? nA : cA + (size_t)(t + 2) * kstep; const char* b2 = last ? nB : cB + (size_t)(t + 2) * kstep;
;             const char* a3 = a2 + kstep; const char* b3 = b2 + kstep;
;             if (last && has_next) S.a_ready(nxt);
;             if constexpr (SP2) {
;             int tz_ = __builtin_amdgcn_readfirstlane(t | (ui > 0 ? 0 : 1)); asm volatile("" : "+s"(tz_));
;             const bool strict = !(Epi::NS > 0 && tz_ == 0);
;             PG8_LDB(B0, 0, 0); PG8_LDB(B1, 0, 1); PG8_SCHED; PG8_LDA(At, 0, 0); PG8_STAGE(PG8_SA(1, 1), a1 + hstep, voffA);
;             PG8_WAIT_VN(8 + Epi::NS); if (strict) PG8_WAIT_V(8); PG8_WAIT_L(0); PG8_BAR; PG8_MMA(0, 0, At, B0); PG8_MMA(0, 1, At, B1); PG8_BAR; PG8_SCHED;
;             PG8_LDA(At, 0, 1); PG8_STAGE(PG8_SB(0, 0), b2, voffB); PG8_STAGE(PG8_SB(0, 1), b2 + hstep, voffB); PG8_STAGE(PG8_SA(0, 0), a2, voffA);
;             PG8_WAIT_VN(8 + Epi::NS); if (strict) PG8_WAIT_V(8); PG8_WAIT_L(0); PG8_BAR; PG8_MMA(1, 0, At, B0); PG8_MMA(1, 1, At, B1); PG8_BAR; PG8_SCHED;
.LBB0_1892:
	s_add_u32 s12, s36, s10
	s_addc_u32 s13, s37, s11
	s_add_u32 s12, s12, 0x8200100
	s_addc_u32 s13, s13, 0
	s_add_u32 s39, s34, s10
	s_addc_u32 s40, s35, s11
	s_cmpk_eq_i32 s10, 0x700
	s_cselect_b32 s15, s9, s13
	s_cselect_b32 s14, s8, s12
	s_cselect_b32 s13, s7, s40
	s_cselect_b32 s12, s6, s39
	s_waitcnt lgkmcnt(0)
	s_setprio 1
	s_barrier
	v_mfma_f32_16x16x32_bf16 v[126:129], v[146:149], v[186:189], v[126:129]
	v_mfma_f32_16x16x32_bf16 v[122:125], v[154:157], v[186:189], v[122:125]
	v_mfma_f32_16x16x32_bf16 v[118:121], v[146:149], v[178:181], v[118:121]
	v_mfma_f32_16x16x32_bf16 v[114:117], v[154:157], v[178:181], v[114:117]
	v_mfma_f32_16x16x32_bf16 v[94:97], v[146:149], v[170:173], v[94:97]
	v_mfma_f32_16x16x32_bf16 v[90:93], v[154:157], v[170:173], v[90:93]
	v_mfma_f32_16x16x32_bf16 v[86:89], v[146:149], v[162:165], v[86:89]
	v_mfma_f32_16x16x32_bf16 v[82:85], v[154:157], v[162:165], v[82:85]
	v_mfma_f32_16x16x32_bf16 v[126:129], v[150:153], v[190:193], v[126:129]
	v_mfma_f32_16x16x32_bf16 v[122:125], v[158:161], v[190:193], v[122:125]
	v_mfma_f32_16x16x32_bf16 v[118:121], v[150:153], v[182:185], v[118:121]
	v_mfma_f32_16x16x32_bf16 v[114:117], v[158:161], v[182:185], v[114:117]
	v_mfma_f32_16x16x32_bf16 v[94:97], v[150:153], v[174:177], v[94:97]
	v_mfma_f32_16x16x32_bf16 v[90:93], v[158:161], v[174:177], v[90:93]
	v_mfma_f32_16x16x32_bf16 v[86:89], v[150:153], v[166:169], v[86:89]
	v_mfma_f32_16x16x32_bf16 v[82:85], v[158:161], v[166:169], v[82:85]
	v_mfma_f32_16x16x32_bf16 v[110:113], v[130:133], v[186:189], v[110:113]
	v_mfma_f32_16x16x32_bf16 v[106:109], v[138:141], v[186:189], v[106:109]
	v_mfma_f32_16x16x32_bf16 v[102:105], v[130:133], v[178:181], v[102:105]
	v_mfma_f32_16x16x32_bf16 v[98:101], v[138:141], v[178:181], v[98:101]
	v_mfma_f32_16x16x32_bf16 v[78:81], v[130:133], v[170:173], v[78:81]
	v_mfma_f32_16x16x32_bf16 v[74:77], v[138:141], v[170:173], v[74:77]
	v_mfma_f32_16x16x32_bf16 v[70:73], v[130:133], v[162:165], v[70:73]
	v_mfma_f32_16x16x32_bf16 v[66:69], v[138:141], v[162:165], v[66:69]
	v_mfma_f32_16x16x32_bf16 v[110:113], v[134:137], v[190:193], v[110:113]
	v_mfma_f32_16x16x32_bf16 v[106:109], v[142:145], v[190:193], v[106:109]
	v_mfma_f32_16x16x32_bf16 v[102:105], v[134:137], v[182:185], v[102:105]
	v_mfma_f32_16x16x32_bf16 v[98:101], v[142:145], v[182:185], v[98:101]
	v_mfma_f32_16x16x32_bf16 v[78:81], v[134:137], v[174:177], v[78:81]
	v_mfma_f32_16x16x32_bf16 v[74:77], v[142:145], v[174:177], v[74:77]
	v_mfma_f32_16x16x32_bf16 v[70:73], v[134:137], v[166:169], v[70:73]
	v_mfma_f32_16x16x32_bf16 v[66:69], v[142:145], v[166:169], v[66:69]
	s_barrier
	s_setprio 0
	s_mov_b32 m0, s22
	v_lshl_add_u64 v[228:229], s[12:13], 0, v[212:213]
	s_add_u32 s40, s12, 0x40000
	ds_read_b128 v[186:189], v232 offset:16384
	ds_read_b128 v[190:193], v232 offset:17408
	ds_read_b128 v[178:181], v232 offset:18432
	ds_read_b128 v[182:185], v232 offset:19456
	ds_read_b128 v[170:173], v232 offset:20480
	ds_read_b128 v[174:177], v232 offset:21504
	ds_read_b128 v[162:165], v232 offset:22528
	ds_read_b128 v[166:169], v232 offset:23552
	global_load_lds_dwordx4 v[228:229], off
	v_lshl_add_u64 v[226:227], s[12:13], 0, v[216:217]
	s_mov_b32 m0, s23
	s_addc_u32 s41, s13, 0
	global_load_lds_dwordx4 v[226:227], off
	v_lshl_add_u64 v[194:195], s[40:41], 0, v[212:213]
	s_mov_b32 m0, s24
	v_lshl_add_u64 v[222:223], s[14:15], 0, v[210:211]
	global_load_lds_dwordx4 v[194:195], off
	v_lshl_add_u64 v[194:195], s[40:41], 0, v[216:217]
	s_mov_b32 m0, s25
	v_lshl_add_u64 v[224:225], s[14:15], 0, v[214:215]
	global_load_lds_dwordx4 v[194:195], off
	s_mov_b32 m0, s5
	s_andn2_b64 vcc, exec, s[16:17]
	global_load_lds_dwordx4 v[222:223], off
	s_mov_b32 m0, s26
	s_nop 0
	global_load_lds_dwordx4 v[224:225], off
	s_waitcnt vmcnt(16)
	s_cbranch_vccnz .LBB0_1889
	s_waitcnt vmcnt(8)
	s_branch .LBB0_1889

; #define PG8_STAGE(bufoff, gbase, voff) do { _Pragma("unroll") for (int _i = 0; _i < 2; ++_i) \
;         __builtin_amdgcn_global_load_lds((const unsigned*)((const char*)(gbase) + (voff)[_i]), (PG8_LAS unsigned*)(lds + (bufoff) + ldsw + _i * 8192), 16, 0, 0); } while (0)
; #define PG8_LDA(dst, b, h) do { _Pragma("unroll") for (int m = 0; m < 4; ++m) _Pragma("unroll") for (int k = 0; k < 2; ++k) dst[m][k] = *(const PG8_LAS bf16x8*)(lds + PG8_SA(b, h) + aoff + m * 2048 + k * 1024); } while (0)
; #define PG8_LDB(dst, b, h) do { _Pragma("unroll") for (int n = 0; n < 2; ++n) _Pragma("unroll") for (int k = 0; k < 2; ++k) dst[n][k] = *(const PG8_LAS bf16x8*)(lds + PG8_SB(b, h) + boff + n * 2048 + k * 1024); } while (0)
; #define PG8_MMA(ai, bj, At, Bt) do { __builtin_amdgcn_s_setprio(1); _Pragma("unroll") for (int m = 0; m < 4; ++m) _Pragma("unroll") for (int n = 0; n < 2; ++n) _Pragma("unroll") for (int k = 0; k < 2; ++k) \
;         acc[ai][bj][m][n] = __builtin_amdgcn_mfma_f32_16x16x32_bf16(Bt[n][k], At[m][k], acc[ai][bj][m][n], 0, 0, 0); __builtin_amdgcn_s_setprio(0); } while (0)
; #define PG8_WAIT_V(n) asm volatile("s_waitcnt vmcnt(" #n ")" ::: "memory")
; #define PG8_WAIT_VN(n) asm volatile("s_waitcnt vmcnt(%0)" :: "n"(n) : "memory")
; #define PG8_WAIT_L(n) asm volatile("s_waitcnt lgkmcnt(" #n ")" ::: "memory")
; #define PG8_BAR __builtin_amdgcn_s_barrier()
; #define PG8_SCHED __builtin_amdgcn_sched_barrier(0)
; template <class Epi, class Sched, bool ALIGN_EPI = false, bool SP2 = false>
; __device__ __forceinline__ void gemm_phase(PG8_LAS unsigned char* lds, const Gemm g, const Sched& S, const Epi& E, const int wave_id) {
;     ...
;             PG8_WAIT_VN(8 + Epi::NS); if (strict) PG8_WAIT_V(8); PG8_WAIT_L(0); PG8_BAR; PG8_MMA(1, 0, At, B0); PG8_MMA(1, 1, At, B1); PG8_BAR; PG8_SCHED;
;             PG8_LDB(B0, 1, 0); PG8_LDB(B1, 1, 1); PG8_SCHED; PG8_LDA(At, 1, 0); PG8_STAGE(PG8_SA(0, 1), a2 + hstep, voffA);
;             PG8_WAIT_V(8); PG8_WAIT_L(0); PG8_BAR; PG8_MMA(0, 0, At, B0); PG8_MMA(0, 1, At, B1); PG8_BAR; PG8_SCHED;
.LBB0_1952:
	s_waitcnt lgkmcnt(0)
	s_setprio 1
	s_barrier
	v_mfma_f32_16x16x32_bf16 v[62:65], v[146:149], v[186:189], v[62:65]
	v_mfma_f32_16x16x32_bf16 v[58:61], v[154:157], v[186:189], v[58:61]
	v_mfma_f32_16x16x32_bf16 v[54:57], v[146:149], v[178:181], v[54:57]
	v_mfma_f32_16x16x32_bf16 v[50:53], v[154:157], v[178:181], v[50:53]
	v_mfma_f32_16x16x32_bf16 v[30:33], v[146:149], v[170:173], v[30:33]
	v_mfma_f32_16x16x32_bf16 v[26:29], v[154:157], v[170:173], v[26:29]
	v_mfma_f32_16x16x32_bf16 v[22:25], v[146:149], v[162:165], v[22:25]
	v_mfma_f32_16x16x32_bf16 v[18:21], v[154:157], v[162:165], v[18:21]
	v_mfma_f32_16x16x32_bf16 v[62:65], v[150:153], v[190:193], v[62:65]
	v_mfma_f32_16x16x32_bf16 v[58:61], v[158:161], v[190:193], v[58:61]
	v_mfma_f32_16x16x32_bf16 v[54:57], v[150:153], v[182:185], v[54:57]
	v_mfma_f32_16x16x32_bf16 v[50:53], v[158:161], v[182:185], v[50:53]
	v_mfma_f32_16x16x32_bf16 v[30:33], v[150:153], v[174:177], v[30:33]
	v_mfma_f32_16x16x32_bf16 v[26:29], v[158:161], v[174:177], v[26:29]
	v_mfma_f32_16x16x32_bf16 v[22:25], v[150:153], v[166:169], v[22:25]
	v_mfma_f32_16x16x32_bf16 v[18:21], v[158:161], v[166:169], v[18:21]
	v_mfma_f32_16x16x32_bf16 v[46:49], v[130:133], v[186:189], v[46:49]
	v_mfma_f32_16x16x32_bf16 v[42:45], v[138:141], v[186:189], v[42:45]
	v_mfma_f32_16x16x32_bf16 v[38:41], v[130:133], v[178:181], v[38:41]
	v_mfma_f32_16x16x32_bf16 v[34:37], v[138:141], v[178:181], v[34:37]
	v_mfma_f32_16x16x32_bf16 v[14:17], v[130:133], v[170:173], v[14:17]
	v_mfma_f32_16x16x32_bf16 v[10:13], v[138:141], v[170:173], v[10:13]
	v_mfma_f32_16x16x32_bf16 v[6:9], v[130:133], v[162:165], v[6:9]
	v_mfma_f32_16x16x32_bf16 v[2:5], v[138:141], v[162:165], v[2:5]
	v_mfma_f32_16x16x32_bf16 v[46:49], v[134:137], v[190:193], v[46:49]
	v_mfma_f32_16x16x32_bf16 v[42:45], v[142:145], v[190:193], v[42:45]
	v_mfma_f32_16x16x32_bf16 v[38:41], v[134:137], v[182:185], v[38:41]
	v_mfma_f32_16x16x32_bf16 v[34:37], v[142:145], v[182:185], v[34:37]
	v_mfma_f32_16x16x32_bf16 v[14:17], v[134:137], v[174:177], v[14:17]
	v_mfma_f32_16x16x32_bf16 v[10:13], v[142:145], v[174:177], v[10:13]
	v_mfma_f32_16x16x32_bf16 v[6:9], v[134:137], v[166:169], v[6:9]
	v_mfma_f32_16x16x32_bf16 v[2:5], v[142:145], v[166:169], v[2:5]
	s_barrier
	s_setprio 0
	s_add_i32 s28, 0, 0x18000
	s_add_i32 s29, 0, 0x1c000
	v_add_u32_e32 v142, s28, v246
	v_add_u32_e32 v158, s29, v246
	ds_read_b128 v[130:133], v142
	ds_read_b128 v[134:137], v142 offset:1024
	ds_read_b128 v[138:141], v142 offset:2048
	ds_read_b128 v[142:145], v142 offset:3072
	ds_read_b128 v[146:149], v158
	ds_read_b128 v[150:153], v158 offset:1024
	ds_read_b128 v[154:157], v158 offset:2048
	ds_read_b128 v[158:161], v158 offset:3072
	s_add_u32 s26, s26, 0x40000
	s_addc_u32 s27, s27, 0
	s_mov_b32 m0, s52
	v_lshl_add_u64 v[194:195], s[26:27], 0, v[216:217]
	ds_read_b128 v[162:165], v247 offset:32768
	ds_read_b128 v[166:169], v247 offset:33792
	ds_read_b128 v[170:173], v247 offset:34816
	ds_read_b128 v[174:177], v247 offset:35840
	ds_read_b128 v[178:181], v247 offset:36864
	ds_read_b128 v[182:185], v247 offset:37888
	ds_read_b128 v[186:189], v247 offset:38912
	ds_read_b128 v[190:193], v247 offset:39936
	global_load_lds_dwordx4 v[194:195], off
	v_lshl_add_u64 v[194:195], s[26:27], 0, v[212:213]
	s_mov_b32 m0, s54
	s_nop 0
	global_load_lds_dwordx4 v[194:195], off
	s_waitcnt vmcnt(18)
	s_cmp_eq_u32 s100, 0
	s_cbranch_scc1 .Lthird_wait_relaxed_2
	s_waitcnt vmcnt(8)
; #define PG8_STAGE(bufoff, gbase, voff) do { _Pragma("unroll") for (int _i = 0; _i < 2; ++_i) \
;         __builtin_amdgcn_global_load_lds((const unsigned*)((const char*)(gbase) + (voff)[_i]), (PG8_LAS unsigned*)(lds + (bufoff) + ldsw + _i * 8192), 16, 0, 0); } while (0)
; #define PG8_LDA(dst, b, h) do { _Pragma("unroll") for (int m = 0; m < 4; ++m) _Pragma("unroll") for (int k = 0; k < 2; ++k) dst[m][k] = *(const PG8_LAS bf16x8*)(lds + PG8_SA(b, h) + aoff + m * 2048 + k * 1024); } while (0)
; #define PG8_MMA(ai, bj, At, Bt) do { __builtin_amdgcn_s_setprio(1); _Pragma("unroll") for (int m = 0; m < 4; ++m) _Pragma("unroll") for (int n = 0; n < 2; ++n) _Pragma("unroll") for (int k = 0; k < 2; ++k) \
;         acc[ai][bj][m][n] = __builtin_amdgcn_mfma_f32_16x16x32_bf16(Bt[n][k], At[m][k], acc[ai][bj][m][n], 0, 0, 0); __builtin_amdgcn_s_setprio(0); } while (0)
; #define PG8_WAIT_V(n) asm volatile("s_waitcnt vmcnt(" #n ")" ::: "memory")
; #define PG8_WAIT_L(n) asm volatile("s_waitcnt lgkmcnt(" #n ")" ::: "memory")
; #define PG8_BAR __builtin_amdgcn_s_barrier()
; #define PG8_SCHED __builtin_amdgcn_sched_barrier(0)
; template <class Epi, class Sched, bool ALIGN_EPI = false, bool SP2 = false>
; __device__ __forceinline__ void gemm_phase(PG8_LAS unsigned char* lds, const Gemm g, const Sched& S, const Epi& E, const int wave_id) {
;     ...
;             PG8_WAIT_V(8); PG8_WAIT_L(0); PG8_BAR; PG8_MMA(0, 0, At, B0); PG8_MMA(0, 1, At, B1); PG8_BAR; PG8_SCHED;
;             PG8_LDA(At, 1, 1); PG8_STAGE(PG8_SB(1, 0), b3, voffB); PG8_STAGE(PG8_SB(1, 1), b3 + hstep, voffB); PG8_STAGE(PG8_SA(1, 0), a3, voffA);
;             PG8_WAIT_V(8); PG8_WAIT_L(0); PG8_BAR; PG8_MMA(1, 0, At, B0); PG8_MMA(1, 1, At, B1); PG8_BAR; PG8_SCHED;
.Lthird_wait_relaxed_2:
	s_waitcnt lgkmcnt(0)
	s_setprio 1
	s_barrier
	v_mfma_f32_16x16x32_bf16 v[126:129], v[130:133], v[162:165], v[126:129]
	v_mfma_f32_16x16x32_bf16 v[122:125], v[138:141], v[162:165], v[122:125]
	v_mfma_f32_16x16x32_bf16 v[118:121], v[130:133], v[170:173], v[118:121]
	v_mfma_f32_16x16x32_bf16 v[114:117], v[138:141], v[170:173], v[114:117]
	v_mfma_f32_16x16x32_bf16 v[94:97], v[130:133], v[178:181], v[94:97]
	v_mfma_f32_16x16x32_bf16 v[90:93], v[138:141], v[178:181], v[90:93]
	v_mfma_f32_16x16x32_bf16 v[86:89], v[130:133], v[186:189], v[86:89]
	v_mfma_f32_16x16x32_bf16 v[82:85], v[138:141], v[186:189], v[82:85]
	v_mfma_f32_16x16x32_bf16 v[126:129], v[134:137], v[166:169], v[126:129]
	v_mfma_f32_16x16x32_bf16 v[122:125], v[142:145], v[166:169], v[122:125]
	v_mfma_f32_16x16x32_bf16 v[118:121], v[134:137], v[174:177], v[118:121]
	v_mfma_f32_16x16x32_bf16 v[114:117], v[142:145], v[174:177], v[114:117]
	v_mfma_f32_16x16x32_bf16 v[94:97], v[134:137], v[182:185], v[94:97]
	v_mfma_f32_16x16x32_bf16 v[90:93], v[142:145], v[182:185], v[90:93]
	v_mfma_f32_16x16x32_bf16 v[86:89], v[134:137], v[190:193], v[86:89]
	v_mfma_f32_16x16x32_bf16 v[82:85], v[142:145], v[190:193], v[82:85]
	v_mfma_f32_16x16x32_bf16 v[110:113], v[146:149], v[162:165], v[110:113]
	v_mfma_f32_16x16x32_bf16 v[106:109], v[154:157], v[162:165], v[106:109]
	v_mfma_f32_16x16x32_bf16 v[102:105], v[146:149], v[170:173], v[102:105]
	v_mfma_f32_16x16x32_bf16 v[98:101], v[154:157], v[170:173], v[98:101]
	v_mfma_f32_16x16x32_bf16 v[78:81], v[146:149], v[178:181], v[78:81]
	v_mfma_f32_16x16x32_bf16 v[74:77], v[154:157], v[178:181], v[74:77]
	v_mfma_f32_16x16x32_bf16 v[70:73], v[146:149], v[186:189], v[70:73]
	v_mfma_f32_16x16x32_bf16 v[66:69], v[154:157], v[186:189], v[66:69]
	v_mfma_f32_16x16x32_bf16 v[110:113], v[150:153], v[166:169], v[110:113]
	v_mfma_f32_16x16x32_bf16 v[106:109], v[158:161], v[166:169], v[106:109]
	v_mfma_f32_16x16x32_bf16 v[102:105], v[150:153], v[174:177], v[102:105]
	v_mfma_f32_16x16x32_bf16 v[98:101], v[158:161], v[174:177], v[98:101]
	v_mfma_f32_16x16x32_bf16 v[78:81], v[150:153], v[182:185], v[78:81]
	v_mfma_f32_16x16x32_bf16 v[74:77], v[158:161], v[182:185], v[74:77]
	v_mfma_f32_16x16x32_bf16 v[70:73], v[150:153], v[190:193], v[70:73]
	v_mfma_f32_16x16x32_bf16 v[66:69], v[158:161], v[190:193], v[66:69]
	s_barrier
	s_setprio 0
	s_add_i32 s26, s28, s39
	v_lshl_add_u64 v[194:195], v[232:233], 0, s[64:65]
	s_mov_b32 m0, s26
	ds_read_b128 v[162:165], v247 offset:49152
	ds_read_b128 v[166:169], v247 offset:50176
	ds_read_b128 v[170:173], v247 offset:51200
	ds_read_b128 v[174:177], v247 offset:52224
	ds_read_b128 v[178:181], v247 offset:53248
	ds_read_b128 v[182:185], v247 offset:54272
	ds_read_b128 v[186:189], v247 offset:55296
	ds_read_b128 v[190:193], v247 offset:56320
	global_load_lds_dwordx4 v[194:195], off
	s_add_i32 m0, s26, 0x2000
	s_add_u32 s24, s24, 0x40080
	v_lshl_add_u64 v[194:195], v[230:231], 0, s[64:65]
	s_addc_u32 s25, s25, 0
	s_add_i32 s26, s29, s39
	global_load_lds_dwordx4 v[194:195], off
	v_lshl_add_u64 v[194:195], s[24:25], 0, v[214:215]
	s_mov_b32 m0, s26
	s_nop 0
	global_load_lds_dwordx4 v[194:195], off
	v_lshl_add_u64 v[194:195], s[24:25], 0, v[210:211]
	s_add_i32 m0, s26, 0x2000
	s_nop 0
	global_load_lds_dwordx4 v[194:195], off
	v_lshl_add_u64 v[194:195], v[226:227], 0, s[64:65]
	s_mov_b32 m0, s57
	s_nop 0
	global_load_lds_dwordx4 v[194:195], off
	v_lshl_add_u64 v[194:195], v[228:229], 0, s[64:65]
	s_mov_b32 m0, s62
	s_nop 0
	global_load_lds_dwordx4 v[194:195], off
	s_waitcnt vmcnt(8)
	s_waitcnt lgkmcnt(0)
	s_setprio 1
	s_barrier
	v_mfma_f32_16x16x32_bf16 v[62:65], v[130:133], v[162:165], v[62:65]
	v_mfma_f32_16x16x32_bf16 v[58:61], v[138:141], v[162:165], v[58:61]
	v_mfma_f32_16x16x32_bf16 v[54:57], v[130:133], v[170:173], v[54:57]
	v_mfma_f32_16x16x32_bf16 v[50:53], v[138:141], v[170:173], v[50:53]
	v_mfma_f32_16x16x32_bf16 v[30:33], v[130:133], v[178:181], v[30:33]
	v_mfma_f32_16x16x32_bf16 v[26:29], v[138:141], v[178:181], v[26:29]
	v_mfma_f32_16x16x32_bf16 v[22:25], v[130:133], v[186:189], v[22:25]
	v_mfma_f32_16x16x32_bf16 v[18:21], v[138:141], v[186:189], v[18:21]
	v_mfma_f32_16x16x32_bf16 v[62:65], v[134:137], v[166:169], v[62:65]
	v_mfma_f32_16x16x32_bf16 v[58:61], v[142:145], v[166:169], v[58:61]
	v_mfma_f32_16x16x32_bf16 v[54:57], v[134:137], v[174:177], v[54:57]
	v_mfma_f32_16x16x32_bf16 v[50:53], v[142:145], v[174:177], v[50:53]
	v_mfma_f32_16x16x32_bf16 v[30:33], v[134:137], v[182:185], v[30:33]
	v_mfma_f32_16x16x32_bf16 v[26:29], v[142:145], v[182:185], v[26:29]
	v_mfma_f32_16x16x32_bf16 v[22:25], v[134:137], v[190:193], v[22:25]
	v_mfma_f32_16x16x32_bf16 v[18:21], v[142:145], v[190:193], v[18:21]
	v_mfma_f32_16x16x32_bf16 v[46:49], v[146:149], v[162:165], v[46:49]
	v_mfma_f32_16x16x32_bf16 v[42:45], v[154:157], v[162:165], v[42:45]
	v_mfma_f32_16x16x32_bf16 v[38:41], v[146:149], v[170:173], v[38:41]
	v_mfma_f32_16x16x32_bf16 v[34:37], v[154:157], v[170:173], v[34:37]
	v_mfma_f32_16x16x32_bf16 v[14:17], v[146:149], v[178:181], v[14:17]
	v_mfma_f32_16x16x32_bf16 v[10:13], v[154:157], v[178:181], v[10:13]
	v_mfma_f32_16x16x32_bf16 v[6:9], v[146:149], v[186:189], v[6:9]
	v_mfma_f32_16x16x32_bf16 v[2:5], v[154:157], v[186:189], v[2:5]
	v_mfma_f32_16x16x32_bf16 v[46:49], v[150:153], v[166:169], v[46:49]
	v_mfma_f32_16x16x32_bf16 v[42:45], v[158:161], v[166:169], v[42:45]
	v_mfma_f32_16x16x32_bf16 v[38:41], v[150:153], v[174:177], v[38:41]
	v_mfma_f32_16x16x32_bf16 v[34:37], v[158:161], v[174:177], v[34:37]
	v_mfma_f32_16x16x32_bf16 v[14:17], v[150:153], v[182:185], v[14:17]
	v_mfma_f32_16x16x32_bf16 v[10:13], v[158:161], v[182:185], v[10:13]
	v_mfma_f32_16x16x32_bf16 v[6:9], v[150:153], v[190:193], v[6:9]
	v_mfma_f32_16x16x32_bf16 v[2:5], v[158:161], v[190:193], v[2:5]
	s_barrier
	s_setprio 0
	s_add_i32 s76, s76, 2
	s_add_u32 s22, s22, 0x100
	s_addc_u32 s23, s23, 0
	s_cmp_gt_u32 s76, 13
	s_cbranch_scc1 .LBB0_1957

; #define PG8_STAGE(bufoff, gbase, voff) do { _Pragma("unroll") for (int _i = 0; _i < 2; ++_i) \
;         __builtin_amdgcn_global_load_lds((const unsigned*)((const char*)(gbase) + (voff)[_i]), (PG8_LAS unsigned*)(lds + (bufoff) + ldsw + _i * 8192), 16, 0, 0); } while (0)
; #define PG8_LDA(dst, b, h) do { _Pragma("unroll") for (int m = 0; m < 4; ++m) _Pragma("unroll") for (int k = 0; k < 2; ++k) dst[m][k] = *(const PG8_LAS bf16x8*)(lds + PG8_SA(b, h) + aoff + m * 2048 + k * 1024); } while (0)
; #define PG8_LDB(dst, b, h) do { _Pragma("unroll") for (int n = 0; n < 2; ++n) _Pragma("unroll") for (int k = 0; k < 2; ++k) dst[n][k] = *(const PG8_LAS bf16x8*)(lds + PG8_SB(b, h) + boff + n * 2048 + k * 1024); } while (0)
; #define PG8_WAIT_V(n) asm volatile("s_waitcnt vmcnt(" #n ")" ::: "memory")
; #define PG8_WAIT_VN(n) asm volatile("s_waitcnt vmcnt(%0)" :: "n"(n) : "memory")
; #define PG8_WAIT_L(n) asm volatile("s_waitcnt lgkmcnt(" #n ")" ::: "memory")
; #define PG8_BAR __builtin_amdgcn_s_barrier()
; #define PG8_SCHED __builtin_amdgcn_sched_barrier(0)
; template <class Epi, class Sched, bool ALIGN_EPI = false, bool SP2 = false>
; __device__ __forceinline__ void gemm_phase(PG8_LAS unsigned char* lds, const Gemm g, const Sched& S, const Epi& E, const int wave_id) {
;     ...
;             const char* a1 = cA + (size_t)(t + 1) * kstep;
;             const char* a2 = last ? nA : cA + (size_t)(t + 2) * kstep; const char* b2 = last ? nB : cB + (size_t)(t + 2) * kstep;
;             const char* a3 = a2 + kstep; const char* b3 = b2 + kstep;
;             if (last && has_next) S.a_ready(nxt);
;             if constexpr (SP2) {
;             int tz_ = __builtin_amdgcn_readfirstlane(t | (ui > 0 ? 0 : 1)); asm volatile("" : "+s"(tz_));
;             const bool strict = !(Epi::NS > 0 && tz_ == 0);
;             PG8_LDB(B0, 0, 0); PG8_LDB(B1, 0, 1); PG8_SCHED; PG8_LDA(At, 0, 0); PG8_STAGE(PG8_SA(1, 1), a1 + hstep, voffA);
;             PG8_WAIT_VN(8 + Epi::NS); if (strict) PG8_WAIT_V(8); PG8_WAIT_L(0); PG8_BAR; PG8_MMA(0, 0, At, B0); PG8_MMA(0, 1, At, B1); PG8_BAR; PG8_SCHED;
;             PG8_LDA(At, 0, 1); PG8_STAGE(PG8_SB(0, 0), b2, voffB); PG8_STAGE(PG8_SB(0, 1), b2 + hstep, voffB); PG8_STAGE(PG8_SA(0, 0), a2, voffA);
;             PG8_WAIT_VN(8 + Epi::NS); if (strict) PG8_WAIT_V(8); PG8_WAIT_L(0); PG8_BAR; PG8_MMA(1, 0, At, B0); PG8_MMA(1, 1, At, B1); PG8_BAR; PG8_SCHED;
.LBB0_1955:
	s_add_u32 s24, s20, s22
	s_addc_u32 s25, s21, s23
	s_add_u32 s24, s24, 0x100
	s_addc_u32 s25, s25, 0
	s_add_u32 s53, s74, s22
	s_addc_u32 s78, s75, s23
	s_cmpk_eq_i32 s22, 0x700
	s_cselect_b32 s27, s13, s25
	s_cselect_b32 s26, s68, s24
	s_cselect_b32 s25, s11, s78
	s_cselect_b32 s24, s69, s53
	s_waitcnt lgkmcnt(0)
	s_setprio 1
	s_barrier
	v_mfma_f32_16x16x32_bf16 v[126:129], v[146:149], v[186:189], v[126:129]
	v_mfma_f32_16x16x32_bf16 v[122:125], v[154:157], v[186:189], v[122:125]
	v_mfma_f32_16x16x32_bf16 v[118:121], v[146:149], v[178:181], v[118:121]
	v_mfma_f32_16x16x32_bf16 v[114:117], v[154:157], v[178:181], v[114:117]
	v_mfma_f32_16x16x32_bf16 v[94:97], v[146:149], v[170:173], v[94:97]
	v_mfma_f32_16x16x32_bf16 v[90:93], v[154:157], v[170:173], v[90:93]
	v_mfma_f32_16x16x32_bf16 v[86:89], v[146:149], v[162:165], v[86:89]
	v_mfma_f32_16x16x32_bf16 v[82:85], v[154:157], v[162:165], v[82:85]
	v_mfma_f32_16x16x32_bf16 v[126:129], v[150:153], v[190:193], v[126:129]
	v_mfma_f32_16x16x32_bf16 v[122:125], v[158:161], v[190:193], v[122:125]
	v_mfma_f32_16x16x32_bf16 v[118:121], v[150:153], v[182:185], v[118:121]
	v_mfma_f32_16x16x32_bf16 v[114:117], v[158:161], v[182:185], v[114:117]
	v_mfma_f32_16x16x32_bf16 v[94:97], v[150:153], v[174:177], v[94:97]
	v_mfma_f32_16x16x32_bf16 v[90:93], v[158:161], v[174:177], v[90:93]
	v_mfma_f32_16x16x32_bf16 v[86:89], v[150:153], v[166:169], v[86:89]
	v_mfma_f32_16x16x32_bf16 v[82:85], v[158:161], v[166:169], v[82:85]
	v_mfma_f32_16x16x32_bf16 v[110:113], v[130:133], v[186:189], v[110:113]
	v_mfma_f32_16x16x32_bf16 v[106:109], v[138:141], v[186:189], v[106:109]
	v_mfma_f32_16x16x32_bf16 v[102:105], v[130:133], v[178:181], v[102:105]
	v_mfma_f32_16x16x32_bf16 v[98:101], v[138:141], v[178:181], v[98:101]
	v_mfma_f32_16x16x32_bf16 v[78:81], v[130:133], v[170:173], v[78:81]
	v_mfma_f32_16x16x32_bf16 v[74:77], v[138:141], v[170:173], v[74:77]
	v_mfma_f32_16x16x32_bf16 v[70:73], v[130:133], v[162:165], v[70:73]
	v_mfma_f32_16x16x32_bf16 v[66:69], v[138:141], v[162:165], v[66:69]
	v_mfma_f32_16x16x32_bf16 v[110:113], v[134:137], v[190:193], v[110:113]
	v_mfma_f32_16x16x32_bf16 v[106:109], v[142:145], v[190:193], v[106:109]
	v_mfma_f32_16x16x32_bf16 v[102:105], v[134:137], v[182:185], v[102:105]
	v_mfma_f32_16x16x32_bf16 v[98:101], v[142:145], v[182:185], v[98:101]
	v_mfma_f32_16x16x32_bf16 v[78:81], v[134:137], v[174:177], v[78:81]
	v_mfma_f32_16x16x32_bf16 v[74:77], v[142:145], v[174:177], v[74:77]
	v_mfma_f32_16x16x32_bf16 v[70:73], v[134:137], v[166:169], v[70:73]
	v_mfma_f32_16x16x32_bf16 v[66:69], v[142:145], v[166:169], v[66:69]
	s_barrier
	s_setprio 0
	s_mov_b32 m0, s42
	v_lshl_add_u64 v[232:233], s[24:25], 0, v[214:215]
	s_add_u32 s90, s24, 0x40000
	ds_read_b128 v[186:189], v247 offset:16384
	ds_read_b128 v[190:193], v247 offset:17408
	ds_read_b128 v[178:181], v247 offset:18432
	ds_read_b128 v[182:185], v247 offset:19456
	ds_read_b128 v[170:173], v247 offset:20480
	ds_read_b128 v[174:177], v247 offset:21504
	ds_read_b128 v[162:165], v247 offset:22528
	ds_read_b128 v[166:169], v247 offset:23552
	global_load_lds_dwordx4 v[232:233], off
	v_lshl_add_u64 v[230:231], s[24:25], 0, v[210:211]
	s_mov_b32 m0, s43
	s_addc_u32 s91, s25, 0
	global_load_lds_dwordx4 v[230:231], off
	v_lshl_add_u64 v[194:195], s[90:91], 0, v[214:215]
	s_mov_b32 m0, s49
	v_lshl_add_u64 v[226:227], s[26:27], 0, v[216:217]
	global_load_lds_dwordx4 v[194:195], off
	v_lshl_add_u64 v[194:195], s[90:91], 0, v[210:211]
	s_mov_b32 m0, s50
	v_lshl_add_u64 v[228:229], s[26:27], 0, v[212:213]
	global_load_lds_dwordx4 v[194:195], off
	s_mov_b32 m0, s41
	s_andn2_b64 vcc, exec, s[28:29]
	global_load_lds_dwordx4 v[226:227], off
	s_mov_b32 m0, s51
	s_nop 0
	global_load_lds_dwordx4 v[228:229], off
	s_waitcnt vmcnt(16)
	s_cbranch_vccnz .LBB0_1952
	s_waitcnt vmcnt(8)
	s_branch .LBB0_1952

; #define PG8_STAGE(bufoff, gbase, voff) do { _Pragma("unroll") for (int _i = 0; _i < 2; ++_i) \
;         __builtin_amdgcn_global_load_lds((const unsigned*)((const char*)(gbase) + (voff)[_i]), (PG8_LAS unsigned*)(lds + (bufoff) + ldsw + _i * 8192), 16, 0, 0); } while (0)
; #define PG8_LDA(dst, b, h) do { _Pragma("unroll") for (int m = 0; m < 4; ++m) _Pragma("unroll") for (int k = 0; k < 2; ++k) dst[m][k] = *(const PG8_LAS bf16x8*)(lds + PG8_SA(b, h) + aoff + m * 2048 + k * 1024); } while (0)
; #define PG8_LDB(dst, b, h) do { _Pragma("unroll") for (int n = 0; n < 2; ++n) _Pragma("unroll") for (int k = 0; k < 2; ++k) dst[n][k] = *(const PG8_LAS bf16x8*)(lds + PG8_SB(b, h) + boff + n * 2048 + k * 1024); } while (0)
; #define PG8_WAIT_V(n) asm volatile("s_waitcnt vmcnt(" #n ")" ::: "memory")
; #define PG8_WAIT_VN(n) asm volatile("s_waitcnt vmcnt(%0)" :: "n"(n) : "memory")
; #define PG8_WAIT_L(n) asm volatile("s_waitcnt lgkmcnt(" #n ")" ::: "memory")
; #define PG8_BAR __builtin_amdgcn_s_barrier()
; #define PG8_SCHED __builtin_amdgcn_sched_barrier(0)
; template <class Epi, class Sched, bool ALIGN_EPI = false, bool SP2 = false>
; __device__ __forceinline__ void gemm_phase(PG8_LAS unsigned char* lds, const Gemm g, const Sched& S, const Epi& E, const int wave_id) {
;     ...
;             const char* a1 = cA + (size_t)(t + 1) * kstep;
;             const char* a2 = last ? nA : cA + (size_t)(t + 2) * kstep; const char* b2 = last ? nB : cB + (size_t)(t + 2) * kstep;
;             const char* a3 = a2 + kstep; const char* b3 = b2 + kstep;
;             if (last && has_next) S.a_ready(nxt);
;             if constexpr (SP2) {
;             int tz_ = __builtin_amdgcn_readfirstlane(t | (ui > 0 ? 0 : 1)); asm volatile("" : "+s"(tz_));
;             const bool strict = !(Epi::NS > 0 && tz_ == 0);
;             PG8_LDB(B0, 0, 0); PG8_LDB(B1, 0, 1); PG8_SCHED; PG8_LDA(At, 0, 0); PG8_STAGE(PG8_SA(1, 1), a1 + hstep, voffA);
;             PG8_WAIT_VN(8 + Epi::NS); if (strict) PG8_WAIT_V(8); PG8_WAIT_L(0); PG8_BAR; PG8_MMA(0, 0, At, B0); PG8_MMA(0, 1, At, B1); PG8_BAR; PG8_SCHED;
;             PG8_LDA(At, 0, 1); PG8_STAGE(PG8_SB(0, 0), b2, voffB); PG8_STAGE(PG8_SB(0, 1), b2 + hstep, voffB); PG8_STAGE(PG8_SA(0, 0), a2, voffA);
;             PG8_WAIT_VN(8 + Epi::NS); if (strict) PG8_WAIT_V(8); PG8_WAIT_L(0); PG8_BAR; PG8_MMA(1, 0, At, B0); PG8_MMA(1, 1, At, B1); PG8_BAR; PG8_SCHED;
.LBB0_2033:
	s_add_u32 s16, s12, s14
	s_addc_u32 s17, s13, s15
	s_add_u32 s16, s16, 0x100
	s_addc_u32 s17, s17, 0
	s_add_u32 s53, s57, s14
	s_addc_u32 s67, s62, s15
	s_cmpk_eq_i32 s14, 0x1500
	s_cselect_b32 s19, s9, s17
	s_cselect_b32 s18, s8, s16
	s_cselect_b32 s17, s11, s67
	s_cselect_b32 s16, s10, s53
	s_waitcnt lgkmcnt(0)
	s_setprio 1
	s_barrier
	v_mfma_f32_16x16x32_bf16 v[126:129], v[146:149], v[186:189], v[126:129]
	v_mfma_f32_16x16x32_bf16 v[122:125], v[154:157], v[186:189], v[122:125]
	v_mfma_f32_16x16x32_bf16 v[110:113], v[146:149], v[178:181], v[110:113]
	v_mfma_f32_16x16x32_bf16 v[106:109], v[154:157], v[178:181], v[106:109]
	v_mfma_f32_16x16x32_bf16 v[94:97], v[146:149], v[170:173], v[94:97]
	v_mfma_f32_16x16x32_bf16 v[90:93], v[154:157], v[170:173], v[90:93]
	v_mfma_f32_16x16x32_bf16 v[78:81], v[146:149], v[162:165], v[78:81]
	v_mfma_f32_16x16x32_bf16 v[74:77], v[154:157], v[162:165], v[74:77]
	v_mfma_f32_16x16x32_bf16 v[126:129], v[150:153], v[190:193], v[126:129]
	v_mfma_f32_16x16x32_bf16 v[122:125], v[158:161], v[190:193], v[122:125]
	v_mfma_f32_16x16x32_bf16 v[110:113], v[150:153], v[182:185], v[110:113]
	v_mfma_f32_16x16x32_bf16 v[106:109], v[158:161], v[182:185], v[106:109]
	v_mfma_f32_16x16x32_bf16 v[94:97], v[150:153], v[174:177], v[94:97]
	v_mfma_f32_16x16x32_bf16 v[90:93], v[158:161], v[174:177], v[90:93]
	v_mfma_f32_16x16x32_bf16 v[78:81], v[150:153], v[166:169], v[78:81]
	v_mfma_f32_16x16x32_bf16 v[74:77], v[158:161], v[166:169], v[74:77]
	v_mfma_f32_16x16x32_bf16 v[118:121], v[130:133], v[186:189], v[118:121]
	v_mfma_f32_16x16x32_bf16 v[114:117], v[138:141], v[186:189], v[114:117]
	v_mfma_f32_16x16x32_bf16 v[102:105], v[130:133], v[178:181], v[102:105]
	v_mfma_f32_16x16x32_bf16 v[98:101], v[138:141], v[178:181], v[98:101]
	v_mfma_f32_16x16x32_bf16 v[86:89], v[130:133], v[170:173], v[86:89]
	v_mfma_f32_16x16x32_bf16 v[82:85], v[138:141], v[170:173], v[82:85]
	v_mfma_f32_16x16x32_bf16 v[70:73], v[130:133], v[162:165], v[70:73]
	v_mfma_f32_16x16x32_bf16 v[66:69], v[138:141], v[162:165], v[66:69]
	v_mfma_f32_16x16x32_bf16 v[118:121], v[134:137], v[190:193], v[118:121]
	v_mfma_f32_16x16x32_bf16 v[114:117], v[142:145], v[190:193], v[114:117]
	v_mfma_f32_16x16x32_bf16 v[102:105], v[134:137], v[182:185], v[102:105]
	v_mfma_f32_16x16x32_bf16 v[98:101], v[142:145], v[182:185], v[98:101]
	v_mfma_f32_16x16x32_bf16 v[86:89], v[134:137], v[174:177], v[86:89]
	v_mfma_f32_16x16x32_bf16 v[82:85], v[142:145], v[174:177], v[82:85]
	v_mfma_f32_16x16x32_bf16 v[70:73], v[134:137], v[166:169], v[70:73]
	v_mfma_f32_16x16x32_bf16 v[66:69], v[142:145], v[166:169], v[66:69]
	s_barrier
	s_setprio 0
	s_mov_b32 m0, s34
	v_lshl_add_u64 v[232:233], s[16:17], 0, v[212:213]
	s_add_u32 s68, s16, 0xb0000
	ds_read_b128 v[186:189], v247 offset:16384
	ds_read_b128 v[190:193], v247 offset:17408
	ds_read_b128 v[178:181], v247 offset:18432
	ds_read_b128 v[182:185], v247 offset:19456
	ds_read_b128 v[170:173], v247 offset:20480
	ds_read_b128 v[174:177], v247 offset:21504
	ds_read_b128 v[162:165], v247 offset:22528
	ds_read_b128 v[166:169], v247 offset:23552
	global_load_lds_dwordx4 v[232:233], off
	v_lshl_add_u64 v[230:231], s[16:17], 0, v[216:217]
	s_mov_b32 m0, s35
	s_addc_u32 s69, s17, 0
	global_load_lds_dwordx4 v[230:231], off
	v_lshl_add_u64 v[194:195], s[68:69], 0, v[212:213]
	s_mov_b32 m0, s36
	v_lshl_add_u64 v[226:227], s[18:19], 0, v[210:211]
	global_load_lds_dwordx4 v[194:195], off
	v_lshl_add_u64 v[194:195], s[68:69], 0, v[216:217]
	s_mov_b32 m0, s37
	v_lshl_add_u64 v[228:229], s[18:19], 0, v[214:215]
	global_load_lds_dwordx4 v[194:195], off
	s_mov_b32 m0, s31
	s_andn2_b64 vcc, exec, s[20:21]
	global_load_lds_dwordx4 v[226:227], off
	s_mov_b32 m0, s38
	s_nop 0
	global_load_lds_dwordx4 v[228:229], off
	s_waitcnt vmcnt(24)
	s_cbranch_vccnz .LBB0_2030
	s_waitcnt vmcnt(8)
	s_branch .LBB0_2030
